# v87 (all K-loop DMA loads in SGPR-base form, no setprio) + accumulator-stationary MFMA order in the 32-MFMA blocks
# speedup vs baseline: 1.0171x; 1.0171x over previous
; #define PG8_STAGE(bufoff, gbase, voff) do { _Pragma("unroll") for (int _i = 0; _i < 2; ++_i) \
;         __builtin_amdgcn_global_load_lds((const unsigned*)((const char*)(gbase) + (voff)[_i]), (PG8_LAS unsigned*)(lds + (bufoff) + ldsw + _i * 8192), 16, 0, 0); } while (0)
; #define PG8_LDA(dst, b, h) do { _Pragma("unroll") for (int m = 0; m < 4; ++m) _Pragma("unroll") for (int k = 0; k < 2; ++k) dst[m][k] = *(const PG8_LAS bf16x8*)(lds + PG8_SA(b, h) + aoff + m * 2048 + k * 1024); } while (0)
; #define PG8_LDB(dst, b, h) do { _Pragma("unroll") for (int n = 0; n < 2; ++n) _Pragma("unroll") for (int k = 0; k < 2; ++k) dst[n][k] = *(const PG8_LAS bf16x8*)(lds + PG8_SB(b, h) + boff + n * 2048 + k * 1024); } while (0)
; #define PG8_MMA(ai, bj, At, Bt) do { __builtin_amdgcn_s_setprio(1); _Pragma("unroll") for (int m = 0; m < 4; ++m) _Pragma("unroll") for (int n = 0; n < 2; ++n) _Pragma("unroll") for (int k = 0; k < 2; ++k) \
;         acc[ai][bj][m][n] = mma16<Epi::I8>(Bt[n][k], At[m][k], acc[ai][bj][m][n]); __builtin_amdgcn_s_setprio(0); } while (0)
; #define PG8_WAIT_V(n) asm volatile("s_waitcnt vmcnt(" #n ")" ::: "memory")
; #define PG8_WAIT_L(n) asm volatile("s_waitcnt lgkmcnt(" #n ")" ::: "memory")
; #define PG8_BAR __builtin_amdgcn_s_barrier()
; template <class Epi, class Sched, bool ALIGN_EPI = false, bool SP2 = false>
; __device__ __forceinline__ void gemm_phase(PG8_LAS unsigned char* lds, const Gemm g, const Sched& S, const Epi& E) {
;     ...
;             const bool last = (t == nt - 2);
;             const char* a1 = cA + (size_t)(t + 1) * kstep;
;             const char* a2 = last ? nA : cA + (size_t)(t + 2) * kstep; const char* b2 = last ? nB : cB + (size_t)(t + 2) * kstep;
;             const char* a3 = a2 + kstep; const char* b3 = b2 + kstep;
;             if (last && has_next) S.a_ready(nxt);
;             if constexpr (SP2) {
;             PG8_LDB(B0, 0, 0); PG8_LDB(B1, 0, 1); PG8_SCHED; PG8_LDA(At, 0, 0); PG8_STAGE(PG8_SA(1, 1), a1 + hstep, voffA);
;             PG8_WAIT_V(8); PG8_WAIT_L(0); PG8_BAR; PG8_MMA(0, 0, At, B0); PG8_MMA(0, 1, At, B1); PG8_BAR; PG8_SCHED;
;             PG8_LDA(At, 0, 1); PG8_STAGE(PG8_SB(0, 0), b2, voffB); PG8_STAGE(PG8_SB(0, 1), b2 + hstep, voffB); PG8_STAGE(PG8_SA(0, 0), a2, voffA);
;             PG8_WAIT_V(8); PG8_WAIT_L(0); PG8_BAR; PG8_MMA(1, 0, At, B0); PG8_MMA(1, 1, At, B1); PG8_BAR; PG8_SCHED;
.Lpeel80:
	s_add_u32 s8, s0, 0x100
	s_addc_u32 s9, s1, 0
	s_add_i32 vcc_hi, 0, 0x10000
	s_cmp_eq_u32 vcc_lo, 12
	s_cselect_b32 s13, s66, s9
	s_cselect_b32 s12, s67, s8
	s_cselect_b32 s7, s82, s97
	s_cselect_b32 s6, s83, s96
	s_add_i32 s4, 0, 0x14000
	v_add_u32_e32 v38, vcc_hi, v242
	v_add_u32_e32 v158, s4, v242
	ds_read_b128 v[18:21], v38
	ds_read_b128 v[22:25], v38 offset:1024
	ds_read_b128 v[34:37], v38 offset:2048
	ds_read_b128 v[38:41], v38 offset:3072
	ds_read_b128 v[130:133], v158
	ds_read_b128 v[134:137], v158 offset:1024
	ds_read_b128 v[154:157], v158 offset:2048
	ds_read_b128 v[158:161], v158 offset:3072
	s_add_i32 m0, s11, 0xc000
	ds_read_b128 v[162:165], v243
	ds_read_b128 v[166:169], v243 offset:1024
	ds_read_b128 v[170:173], v243 offset:2048
	ds_read_b128 v[174:177], v243 offset:3072
	ds_read_b128 v[178:181], v243 offset:4096
	ds_read_b128 v[182:185], v243 offset:5120
	ds_read_b128 v[186:189], v243 offset:6144
	ds_read_b128 v[190:193], v243 offset:7168
	global_load_lds_dwordx4 v216, s[0:1]
	s_add_i32 m0, s11, 0xe000
	s_nop 0
	global_load_lds_dwordx4 v218, s[0:1]
	s_waitcnt vmcnt(8)
	s_waitcnt lgkmcnt(0)
	s_barrier
	s_waitcnt lgkmcnt(0)
	v_mfma_i32_16x16x64_i8 v[150:153], v[18:21], v[162:165], 0
	v_mfma_i32_16x16x64_i8 v[150:153], v[22:25], v[166:169], v[150:153]
	v_mfma_i32_16x16x64_i8 v[146:149], v[34:37], v[162:165], 0
	v_mfma_i32_16x16x64_i8 v[146:149], v[38:41], v[166:169], v[146:149]
	v_mfma_i32_16x16x64_i8 v[110:113], v[34:37], v[170:173], 0
	v_mfma_i32_16x16x64_i8 v[110:113], v[38:41], v[174:177], v[110:113]
	v_mfma_i32_16x16x64_i8 v[118:121], v[18:21], v[170:173], 0
	v_mfma_i32_16x16x64_i8 v[118:121], v[22:25], v[174:177], v[118:121]
	v_mfma_i32_16x16x64_i8 v[54:57], v[18:21], v[178:181], 0
	v_mfma_i32_16x16x64_i8 v[54:57], v[22:25], v[182:185], v[54:57]
	v_mfma_i32_16x16x64_i8 v[30:33], v[34:37], v[178:181], 0
	v_mfma_i32_16x16x64_i8 v[30:33], v[38:41], v[182:185], v[30:33]
	v_mfma_i32_16x16x64_i8 v[58:61], v[34:37], v[186:189], 0
	v_mfma_i32_16x16x64_i8 v[58:61], v[38:41], v[190:193], v[58:61]
	v_mfma_i32_16x16x64_i8 v[94:97], v[18:21], v[186:189], 0
	v_mfma_i32_16x16x64_i8 v[94:97], v[22:25], v[190:193], v[94:97]
	v_mfma_i32_16x16x64_i8 v[142:145], v[130:133], v[162:165], 0
	v_mfma_i32_16x16x64_i8 v[142:145], v[134:137], v[166:169], v[142:145]
	v_mfma_i32_16x16x64_i8 v[138:141], v[154:157], v[162:165], 0
	v_mfma_i32_16x16x64_i8 v[138:141], v[158:161], v[166:169], v[138:141]
	v_mfma_i32_16x16x64_i8 v[98:101], v[154:157], v[170:173], 0
	v_mfma_i32_16x16x64_i8 v[98:101], v[158:161], v[174:177], v[98:101]
	v_mfma_i32_16x16x64_i8 v[102:105], v[130:133], v[170:173], 0
	v_mfma_i32_16x16x64_i8 v[102:105], v[134:137], v[174:177], v[102:105]
	v_mfma_i32_16x16x64_i8 v[42:45], v[130:133], v[178:181], 0
	v_mfma_i32_16x16x64_i8 v[42:45], v[134:137], v[182:185], v[42:45]
	v_mfma_i32_16x16x64_i8 v[26:29], v[154:157], v[178:181], 0
	v_mfma_i32_16x16x64_i8 v[26:29], v[158:161], v[182:185], v[26:29]
	v_mfma_i32_16x16x64_i8 v[62:65], v[154:157], v[186:189], 0
	v_mfma_i32_16x16x64_i8 v[62:65], v[158:161], v[190:193], v[62:65]
	v_mfma_i32_16x16x64_i8 v[78:81], v[130:133], v[186:189], 0
	v_mfma_i32_16x16x64_i8 v[78:81], v[134:137], v[190:193], v[78:81]
	s_barrier
	s_add_i32 s0, vcc_hi, s69
	s_mov_b32 m0, s0
	ds_read_b128 v[162:165], v243 offset:16384
	ds_read_b128 v[166:169], v243 offset:17408
	ds_read_b128 v[170:173], v243 offset:18432
	ds_read_b128 v[174:177], v243 offset:19456
	ds_read_b128 v[178:181], v243 offset:20480
	ds_read_b128 v[182:185], v243 offset:21504
	ds_read_b128 v[186:189], v243 offset:22528
	ds_read_b128 v[190:193], v243 offset:23552
	global_load_lds_dwordx4 v0, s[6:7]
	s_add_i32 m0, s0, 0x2000
	s_add_u32 s0, s6, 0x40000
	s_addc_u32 s1, s7, 0
	s_add_i32 s4, s4, s69
	global_load_lds_dwordx4 v214, s[6:7]
	s_mov_b32 m0, s4
	s_nop 0
	global_load_lds_dwordx4 v0, s[0:1]
	s_add_i32 m0, s4, 0x2000
	s_nop 0
	global_load_lds_dwordx4 v214, s[0:1]
	s_mov_b32 m0, s11
	s_nop 0
	global_load_lds_dwordx4 v210, s[12:13]
	s_mov_b32 m0, s71
	s_nop 0
	global_load_lds_dwordx4 v212, s[12:13]
	s_waitcnt vmcnt(8)
	s_waitcnt lgkmcnt(0)
	s_barrier
	s_waitcnt lgkmcnt(0)
	v_mfma_i32_16x16x64_i8 v[106:109], v[18:21], v[162:165], 0
	v_mfma_i32_16x16x64_i8 v[106:109], v[22:25], v[166:169], v[106:109]
	v_mfma_i32_16x16x64_i8 v[46:49], v[34:37], v[162:165], 0
	v_mfma_i32_16x16x64_i8 v[46:49], v[38:41], v[166:169], v[46:49]
	v_mfma_i32_16x16x64_i8 v[6:9], v[34:37], v[170:173], 0
	v_mfma_i32_16x16x64_i8 v[6:9], v[38:41], v[174:177], v[6:9]
	v_mfma_i32_16x16x64_i8 v[14:17], v[18:21], v[170:173], 0
	v_mfma_i32_16x16x64_i8 v[14:17], v[22:25], v[174:177], v[14:17]
	v_mfma_i32_16x16x64_i8 v[90:93], v[18:21], v[178:181], 0
	v_mfma_i32_16x16x64_i8 v[90:93], v[22:25], v[182:185], v[90:93]
	v_mfma_i32_16x16x64_i8 v[86:89], v[34:37], v[178:181], 0
	v_mfma_i32_16x16x64_i8 v[86:89], v[38:41], v[182:185], v[86:89]
	v_mfma_i32_16x16x64_i8 v[18:21], v[18:21], v[186:189], 0
	v_mfma_i32_16x16x64_i8 v[18:21], v[22:25], v[190:193], v[18:21]
	v_mfma_i32_16x16x64_i8 v[22:25], v[34:37], v[186:189], 0
	v_mfma_i32_16x16x64_i8 v[22:25], v[38:41], v[190:193], v[22:25]
	v_mfma_i32_16x16x64_i8 v[38:41], v[154:157], v[162:165], 0
	v_mfma_i32_16x16x64_i8 v[38:41], v[158:161], v[166:169], v[38:41]
	v_mfma_i32_16x16x64_i8 v[2:5], v[154:157], v[170:173], 0
	v_mfma_i32_16x16x64_i8 v[2:5], v[158:161], v[174:177], v[2:5]
	v_mfma_i32_16x16x64_i8 v[10:13], v[130:133], v[170:173], 0
	v_mfma_i32_16x16x64_i8 v[10:13], v[134:137], v[174:177], v[10:13]
	v_mfma_i32_16x16x64_i8 v[50:53], v[130:133], v[178:181], 0
	v_mfma_i32_16x16x64_i8 v[82:85], v[134:137], v[182:185], v[50:53]
	v_mfma_i32_16x16x64_i8 v[34:37], v[130:133], v[162:165], 0
	v_mfma_i32_16x16x64_i8 v[34:37], v[134:137], v[166:169], v[34:37]
	v_mfma_i32_16x16x64_i8 v[50:53], v[154:157], v[178:181], 0
	v_mfma_i32_16x16x64_i8 v[74:77], v[158:161], v[182:185], v[50:53]
	v_mfma_i32_16x16x64_i8 v[50:53], v[130:133], v[186:189], 0
	v_mfma_i32_16x16x64_i8 v[122:125], v[134:137], v[190:193], v[50:53]
	v_mfma_i32_16x16x64_i8 v[50:53], v[154:157], v[186:189], 0
	v_mfma_i32_16x16x64_i8 v[70:73], v[158:161], v[190:193], v[50:53]
	s_barrier
; #define PG8_STAGE(bufoff, gbase, voff) do { _Pragma("unroll") for (int _i = 0; _i < 2; ++_i) \
;         __builtin_amdgcn_global_load_lds((const unsigned*)((const char*)(gbase) + (voff)[_i]), (PG8_LAS unsigned*)(lds + (bufoff) + ldsw + _i * 8192), 16, 0, 0); } while (0)
; #define PG8_LDA(dst, b, h) do { _Pragma("unroll") for (int m = 0; m < 4; ++m) _Pragma("unroll") for (int k = 0; k < 2; ++k) dst[m][k] = *(const PG8_LAS bf16x8*)(lds + PG8_SA(b, h) + aoff + m * 2048 + k * 1024); } while (0)
; #define PG8_LDB(dst, b, h) do { _Pragma("unroll") for (int n = 0; n < 2; ++n) _Pragma("unroll") for (int k = 0; k < 2; ++k) dst[n][k] = *(const PG8_LAS bf16x8*)(lds + PG8_SB(b, h) + boff + n * 2048 + k * 1024); } while (0)
; #define PG8_MMA(ai, bj, At, Bt) do { __builtin_amdgcn_s_setprio(1); _Pragma("unroll") for (int m = 0; m < 4; ++m) _Pragma("unroll") for (int n = 0; n < 2; ++n) _Pragma("unroll") for (int k = 0; k < 2; ++k) \
;         acc[ai][bj][m][n] = mma16<Epi::I8>(Bt[n][k], At[m][k], acc[ai][bj][m][n]); __builtin_amdgcn_s_setprio(0); } while (0)
; #define PG8_WAIT_V(n) asm volatile("s_waitcnt vmcnt(" #n ")" ::: "memory")
; #define PG8_WAIT_L(n) asm volatile("s_waitcnt lgkmcnt(" #n ")" ::: "memory")
; #define PG8_BAR __builtin_amdgcn_s_barrier()
; #define PG8_SCHED __builtin_amdgcn_sched_barrier(0)
; template <class Epi, class Sched, bool ALIGN_EPI = false, bool SP2 = false>
; __device__ __forceinline__ void gemm_phase(PG8_LAS unsigned char* lds, const Gemm g, const Sched& S, const Epi& E) {
;     ...
;             PG8_LDB(B0, 1, 0); PG8_LDB(B1, 1, 1); PG8_SCHED; PG8_LDA(At, 1, 0); PG8_STAGE(PG8_SA(0, 1), a2 + hstep, voffA);
;             PG8_WAIT_V(8); PG8_WAIT_L(0); PG8_BAR; PG8_MMA(0, 0, At, B0); PG8_MMA(0, 1, At, B1); PG8_BAR; PG8_SCHED;
;             PG8_LDA(At, 1, 1); PG8_STAGE(PG8_SB(1, 0), b3, voffB); PG8_STAGE(PG8_SB(1, 1), b3 + hstep, voffB); PG8_STAGE(PG8_SA(1, 0), a3, voffA);
;             PG8_WAIT_V(8); PG8_WAIT_L(0); PG8_BAR; PG8_MMA(1, 0, At, B0); PG8_MMA(1, 1, At, B1); PG8_BAR; PG8_SCHED;
	s_add_i32 s4, 0, 0x18000
	v_add_u32_e32 v126, s4, v242
	s_add_i32 s5, 0, 0x1c000
	ds_read_b128 v[50:53], v126
	ds_read_b128 v[66:69], v126 offset:1024
	ds_read_b128 v[114:117], v126 offset:2048
	ds_read_b128 v[130:133], v126 offset:3072
	v_add_u32_e32 v126, s5, v242
	ds_read_b128 v[134:137], v126
	ds_read_b128 v[154:157], v126 offset:1024
	ds_read_b128 v[158:161], v126 offset:2048
	ds_read_b128 v[162:165], v126 offset:3072
	s_add_u32 s0, s12, 0x40000
	s_addc_u32 s1, s13, 0
	s_mov_b32 m0, s80
	ds_read_b128 v[126:129], v243 offset:32768
	ds_read_b128 v[166:169], v243 offset:33792
	ds_read_b128 v[170:173], v243 offset:34816
	ds_read_b128 v[174:177], v243 offset:35840
	ds_read_b128 v[178:181], v243 offset:36864
	ds_read_b128 v[182:185], v243 offset:37888
	ds_read_b128 v[186:189], v243 offset:38912
	ds_read_b128 v[190:193], v243 offset:39936
	global_load_lds_dwordx4 v210, s[0:1]
	s_mov_b32 m0, s81
	s_nop 0
	global_load_lds_dwordx4 v212, s[0:1]
	s_waitcnt vmcnt(8)
	s_waitcnt lgkmcnt(0)
	s_barrier
	s_waitcnt lgkmcnt(0)
	v_mfma_i32_16x16x64_i8 v[150:153], v[50:53], v[126:129], v[150:153]
	v_mfma_i32_16x16x64_i8 v[150:153], v[66:69], v[166:169], v[150:153]
	v_mfma_i32_16x16x64_i8 v[146:149], v[114:117], v[126:129], v[146:149]
	v_mfma_i32_16x16x64_i8 v[146:149], v[130:133], v[166:169], v[146:149]
	v_mfma_i32_16x16x64_i8 v[110:113], v[114:117], v[170:173], v[110:113]
	v_mfma_i32_16x16x64_i8 v[110:113], v[130:133], v[174:177], v[110:113]
	v_mfma_i32_16x16x64_i8 v[118:121], v[50:53], v[170:173], v[118:121]
	v_mfma_i32_16x16x64_i8 v[118:121], v[66:69], v[174:177], v[118:121]
	v_mfma_i32_16x16x64_i8 v[54:57], v[50:53], v[178:181], v[54:57]
	v_mfma_i32_16x16x64_i8 v[54:57], v[66:69], v[182:185], v[54:57]
	v_mfma_i32_16x16x64_i8 v[30:33], v[114:117], v[178:181], v[30:33]
	v_mfma_i32_16x16x64_i8 v[30:33], v[130:133], v[182:185], v[30:33]
	v_mfma_i32_16x16x64_i8 v[58:61], v[114:117], v[186:189], v[58:61]
	v_mfma_i32_16x16x64_i8 v[58:61], v[130:133], v[190:193], v[58:61]
	v_mfma_i32_16x16x64_i8 v[94:97], v[50:53], v[186:189], v[94:97]
	v_mfma_i32_16x16x64_i8 v[94:97], v[66:69], v[190:193], v[94:97]
	v_mfma_i32_16x16x64_i8 v[142:145], v[134:137], v[126:129], v[142:145]
	v_mfma_i32_16x16x64_i8 v[142:145], v[154:157], v[166:169], v[142:145]
	v_mfma_i32_16x16x64_i8 v[126:129], v[158:161], v[126:129], v[138:141]
	v_mfma_i32_16x16x64_i8 v[138:141], v[162:165], v[166:169], v[126:129]
	v_mfma_i32_16x16x64_i8 v[98:101], v[158:161], v[170:173], v[98:101]
	v_mfma_i32_16x16x64_i8 v[98:101], v[162:165], v[174:177], v[98:101]
	v_mfma_i32_16x16x64_i8 v[102:105], v[134:137], v[170:173], v[102:105]
	v_mfma_i32_16x16x64_i8 v[102:105], v[154:157], v[174:177], v[102:105]
	v_mfma_i32_16x16x64_i8 v[42:45], v[134:137], v[178:181], v[42:45]
	v_mfma_i32_16x16x64_i8 v[42:45], v[154:157], v[182:185], v[42:45]
	v_mfma_i32_16x16x64_i8 v[26:29], v[158:161], v[178:181], v[26:29]
	v_mfma_i32_16x16x64_i8 v[26:29], v[162:165], v[182:185], v[26:29]
	v_mfma_i32_16x16x64_i8 v[62:65], v[158:161], v[186:189], v[62:65]
	v_mfma_i32_16x16x64_i8 v[62:65], v[162:165], v[190:193], v[62:65]
	v_mfma_i32_16x16x64_i8 v[78:81], v[134:137], v[186:189], v[78:81]
	v_mfma_i32_16x16x64_i8 v[78:81], v[154:157], v[190:193], v[78:81]
	s_barrier
	s_add_u32 s98, s6, 0x80
	s_addc_u32 s99, s7, 0
	s_add_u32 s100, s12, 0x80
	s_addc_u32 s101, s13, 0
	s_add_i32 s0, s4, s69
	s_mov_b32 m0, s0
	ds_read_b128 v[166:169], v243 offset:49152
	ds_read_b128 v[170:173], v243 offset:50176
	ds_read_b128 v[174:177], v243 offset:51200
	ds_read_b128 v[178:181], v243 offset:52224
	ds_read_b128 v[182:185], v243 offset:53248
	ds_read_b128 v[186:189], v243 offset:54272
	ds_read_b128 v[190:193], v243 offset:55296
	ds_read_b128 v[194:197], v243 offset:56320
	global_load_lds_dwordx4 v0, s[98:99]
	s_add_i32 m0, s0, 0x2000
	s_add_u32 s0, s6, 0x40080
	s_addc_u32 s1, s7, 0
	s_add_i32 s4, s5, s69
	global_load_lds_dwordx4 v214, s[98:99]
	s_mov_b32 m0, s4
	s_nop 0
	global_load_lds_dwordx4 v0, s[0:1]
	s_add_i32 m0, s4, 0x2000
	s_nop 0
	global_load_lds_dwordx4 v214, s[0:1]
	s_mov_b32 m0, s84
	s_nop 0
	global_load_lds_dwordx4 v210, s[100:101]
	s_mov_b32 m0, s85
	s_nop 0
	global_load_lds_dwordx4 v212, s[100:101]
	s_waitcnt vmcnt(8)
	s_waitcnt lgkmcnt(0)
	s_barrier
	s_waitcnt lgkmcnt(0)
	v_mfma_i32_16x16x64_i8 v[18:21], v[50:53], v[190:193], v[18:21]
	v_mfma_i32_16x16x64_i8 v[126:129], v[66:69], v[194:197], v[18:21]
	v_mfma_i32_16x16x64_i8 v[106:109], v[50:53], v[166:169], v[106:109]
	v_mfma_i32_16x16x64_i8 v[106:109], v[66:69], v[170:173], v[106:109]
	v_mfma_i32_16x16x64_i8 v[46:49], v[114:117], v[166:169], v[46:49]
	v_mfma_i32_16x16x64_i8 v[46:49], v[130:133], v[170:173], v[46:49]
	v_mfma_i32_16x16x64_i8 v[6:9], v[114:117], v[174:177], v[6:9]
	v_mfma_i32_16x16x64_i8 v[6:9], v[130:133], v[178:181], v[6:9]
	v_mfma_i32_16x16x64_i8 v[14:17], v[50:53], v[174:177], v[14:17]
	v_mfma_i32_16x16x64_i8 v[14:17], v[66:69], v[178:181], v[14:17]
	v_mfma_i32_16x16x64_i8 v[90:93], v[50:53], v[182:185], v[90:93]
	v_mfma_i32_16x16x64_i8 v[90:93], v[66:69], v[186:189], v[90:93]
	v_mfma_i32_16x16x64_i8 v[86:89], v[114:117], v[182:185], v[86:89]
	v_mfma_i32_16x16x64_i8 v[86:89], v[130:133], v[186:189], v[86:89]
	v_mfma_i32_16x16x64_i8 v[18:21], v[114:117], v[190:193], v[22:25]
	v_mfma_i32_16x16x64_i8 v[66:69], v[130:133], v[194:197], v[18:21]
	v_mfma_i32_16x16x64_i8 v[18:21], v[134:137], v[166:169], v[34:37]
	v_mfma_i32_16x16x64_i8 v[114:117], v[154:157], v[170:173], v[18:21]
	v_mfma_i32_16x16x64_i8 v[10:13], v[134:137], v[174:177], v[10:13]
	v_mfma_i32_16x16x64_i8 v[10:13], v[154:157], v[178:181], v[10:13]
	v_mfma_i32_16x16x64_i8 v[2:5], v[158:161], v[174:177], v[2:5]
	v_mfma_i32_16x16x64_i8 v[2:5], v[162:165], v[178:181], v[2:5]
	v_mfma_i32_16x16x64_i8 v[18:21], v[158:161], v[166:169], v[38:41]
	v_mfma_i32_16x16x64_i8 v[50:53], v[162:165], v[170:173], v[18:21]
	v_mfma_i32_16x16x64_i8 v[18:21], v[134:137], v[182:185], v[82:85]
	v_mfma_i32_16x16x64_i8 v[82:85], v[154:157], v[186:189], v[18:21]
	v_mfma_i32_16x16x64_i8 v[18:21], v[158:161], v[182:185], v[74:77]
	v_mfma_i32_16x16x64_i8 v[74:77], v[162:165], v[186:189], v[18:21]
	v_mfma_i32_16x16x64_i8 v[18:21], v[134:137], v[190:193], v[122:125]
	v_mfma_i32_16x16x64_i8 v[122:125], v[154:157], v[194:197], v[18:21]
	v_mfma_i32_16x16x64_i8 v[18:21], v[158:161], v[190:193], v[70:73]
	v_mfma_i32_16x16x64_i8 v[70:73], v[162:165], v[194:197], v[18:21]
	s_barrier
	s_add_i32 vcc_lo, vcc_lo, 2
	s_add_u32 s96, s96, 0x100
	s_addc_u32 s97, s97, 0
	s_cmp_gt_u32 vcc_lo, 13
	s_mov_b64 s[0:1], s[8:9]
	s_cbranch_scc0 .LBB0_80
	s_branch .Lpeelx80
; #define PG8_STAGE(bufoff, gbase, voff) do { _Pragma("unroll") for (int _i = 0; _i < 2; ++_i) \
;         __builtin_amdgcn_global_load_lds((const unsigned*)((const char*)(gbase) + (voff)[_i]), (PG8_LAS unsigned*)(lds + (bufoff) + ldsw + _i * 8192), 16, 0, 0); } while (0)
; #define PG8_LDA(dst, b, h) do { _Pragma("unroll") for (int m = 0; m < 4; ++m) _Pragma("unroll") for (int k = 0; k < 2; ++k) dst[m][k] = *(const PG8_LAS bf16x8*)(lds + PG8_SA(b, h) + aoff + m * 2048 + k * 1024); } while (0)
; #define PG8_LDB(dst, b, h) do { _Pragma("unroll") for (int n = 0; n < 2; ++n) _Pragma("unroll") for (int k = 0; k < 2; ++k) dst[n][k] = *(const PG8_LAS bf16x8*)(lds + PG8_SB(b, h) + boff + n * 2048 + k * 1024); } while (0)
; #define PG8_MMA(ai, bj, At, Bt) do { __builtin_amdgcn_s_setprio(1); _Pragma("unroll") for (int m = 0; m < 4; ++m) _Pragma("unroll") for (int n = 0; n < 2; ++n) _Pragma("unroll") for (int k = 0; k < 2; ++k) \
;         acc[ai][bj][m][n] = mma16<Epi::I8>(Bt[n][k], At[m][k], acc[ai][bj][m][n]); __builtin_amdgcn_s_setprio(0); } while (0)
; #define PG8_WAIT_V(n) asm volatile("s_waitcnt vmcnt(" #n ")" ::: "memory")
; #define PG8_WAIT_L(n) asm volatile("s_waitcnt lgkmcnt(" #n ")" ::: "memory")
; #define PG8_BAR __builtin_amdgcn_s_barrier()
; template <class Epi, class Sched, bool ALIGN_EPI = false, bool SP2 = false>
; __device__ __forceinline__ void gemm_phase(PG8_LAS unsigned char* lds, const Gemm g, const Sched& S, const Epi& E) {
;     ...
;             const bool last = (t == nt - 2);
;             const char* a1 = cA + (size_t)(t + 1) * kstep;
;             const char* a2 = last ? nA : cA + (size_t)(t + 2) * kstep; const char* b2 = last ? nB : cB + (size_t)(t + 2) * kstep;
;             const char* a3 = a2 + kstep; const char* b3 = b2 + kstep;
;             if (last && has_next) S.a_ready(nxt);
;             if constexpr (SP2) {
;             PG8_LDB(B0, 0, 0); PG8_LDB(B1, 0, 1); PG8_SCHED; PG8_LDA(At, 0, 0); PG8_STAGE(PG8_SA(1, 1), a1 + hstep, voffA);
;             PG8_WAIT_V(8); PG8_WAIT_L(0); PG8_BAR; PG8_MMA(0, 0, At, B0); PG8_MMA(0, 1, At, B1); PG8_BAR; PG8_SCHED;
;             PG8_LDA(At, 0, 1); PG8_STAGE(PG8_SB(0, 0), b2, voffB); PG8_STAGE(PG8_SB(0, 1), b2 + hstep, voffB); PG8_STAGE(PG8_SA(0, 0), a2, voffA);
;             PG8_WAIT_V(8); PG8_WAIT_L(0); PG8_BAR; PG8_MMA(1, 0, At, B0); PG8_MMA(1, 1, At, B1); PG8_BAR; PG8_SCHED;
.LBB0_80:
	s_add_u32 s8, s0, 0x100
	s_addc_u32 s9, s1, 0
	s_add_i32 vcc_hi, 0, 0x10000
	s_cmp_eq_u32 vcc_lo, 12
	s_cselect_b32 s13, s66, s9
	s_cselect_b32 s12, s67, s8
	s_cselect_b32 s7, s82, s97
	s_cselect_b32 s6, s83, s96
	s_add_i32 s4, 0, 0x14000
	v_add_u32_e32 v38, vcc_hi, v242
	v_add_u32_e32 v158, s4, v242
	ds_read_b128 v[18:21], v38
	ds_read_b128 v[22:25], v38 offset:1024
	ds_read_b128 v[34:37], v38 offset:2048
	ds_read_b128 v[38:41], v38 offset:3072
	ds_read_b128 v[130:133], v158
	ds_read_b128 v[134:137], v158 offset:1024
	ds_read_b128 v[154:157], v158 offset:2048
	ds_read_b128 v[158:161], v158 offset:3072
	s_add_i32 m0, s11, 0xc000
	ds_read_b128 v[162:165], v243
	ds_read_b128 v[166:169], v243 offset:1024
	ds_read_b128 v[170:173], v243 offset:2048
	ds_read_b128 v[174:177], v243 offset:3072
	ds_read_b128 v[178:181], v243 offset:4096
	ds_read_b128 v[182:185], v243 offset:5120
	ds_read_b128 v[186:189], v243 offset:6144
	ds_read_b128 v[190:193], v243 offset:7168
	global_load_lds_dwordx4 v216, s[0:1]
	s_add_i32 m0, s11, 0xe000
	s_nop 0
	global_load_lds_dwordx4 v218, s[0:1]
	s_waitcnt vmcnt(8)
	s_waitcnt lgkmcnt(0)
	s_barrier
	s_waitcnt lgkmcnt(0)
	v_mfma_i32_16x16x64_i8 v[150:153], v[18:21], v[162:165], v[150:153]
	v_mfma_i32_16x16x64_i8 v[150:153], v[22:25], v[166:169], v[150:153]
	v_mfma_i32_16x16x64_i8 v[146:149], v[34:37], v[162:165], v[146:149]
	v_mfma_i32_16x16x64_i8 v[146:149], v[38:41], v[166:169], v[146:149]
	v_mfma_i32_16x16x64_i8 v[110:113], v[34:37], v[170:173], v[110:113]
	v_mfma_i32_16x16x64_i8 v[110:113], v[38:41], v[174:177], v[110:113]
	v_mfma_i32_16x16x64_i8 v[118:121], v[18:21], v[170:173], v[118:121]
	v_mfma_i32_16x16x64_i8 v[118:121], v[22:25], v[174:177], v[118:121]
	v_mfma_i32_16x16x64_i8 v[54:57], v[18:21], v[178:181], v[54:57]
	v_mfma_i32_16x16x64_i8 v[54:57], v[22:25], v[182:185], v[54:57]
	v_mfma_i32_16x16x64_i8 v[30:33], v[34:37], v[178:181], v[30:33]
	v_mfma_i32_16x16x64_i8 v[30:33], v[38:41], v[182:185], v[30:33]
	v_mfma_i32_16x16x64_i8 v[58:61], v[34:37], v[186:189], v[58:61]
	v_mfma_i32_16x16x64_i8 v[58:61], v[38:41], v[190:193], v[58:61]
	v_mfma_i32_16x16x64_i8 v[94:97], v[18:21], v[186:189], v[94:97]
	v_mfma_i32_16x16x64_i8 v[94:97], v[22:25], v[190:193], v[94:97]
	v_mfma_i32_16x16x64_i8 v[142:145], v[130:133], v[162:165], v[142:145]
	v_mfma_i32_16x16x64_i8 v[142:145], v[134:137], v[166:169], v[142:145]
	v_mfma_i32_16x16x64_i8 v[138:141], v[154:157], v[162:165], v[138:141]
	v_mfma_i32_16x16x64_i8 v[138:141], v[158:161], v[166:169], v[138:141]
	v_mfma_i32_16x16x64_i8 v[98:101], v[154:157], v[170:173], v[98:101]
	v_mfma_i32_16x16x64_i8 v[98:101], v[158:161], v[174:177], v[98:101]
	v_mfma_i32_16x16x64_i8 v[102:105], v[130:133], v[170:173], v[102:105]
	v_mfma_i32_16x16x64_i8 v[102:105], v[134:137], v[174:177], v[102:105]
	v_mfma_i32_16x16x64_i8 v[42:45], v[130:133], v[178:181], v[42:45]
	v_mfma_i32_16x16x64_i8 v[42:45], v[134:137], v[182:185], v[42:45]
	v_mfma_i32_16x16x64_i8 v[26:29], v[154:157], v[178:181], v[26:29]
	v_mfma_i32_16x16x64_i8 v[26:29], v[158:161], v[182:185], v[26:29]
	v_mfma_i32_16x16x64_i8 v[62:65], v[154:157], v[186:189], v[62:65]
	v_mfma_i32_16x16x64_i8 v[62:65], v[158:161], v[190:193], v[62:65]
	v_mfma_i32_16x16x64_i8 v[78:81], v[130:133], v[186:189], v[78:81]
	v_mfma_i32_16x16x64_i8 v[78:81], v[134:137], v[190:193], v[78:81]
	s_barrier
	s_add_i32 s0, vcc_hi, s69
	s_mov_b32 m0, s0
	ds_read_b128 v[162:165], v243 offset:16384
	ds_read_b128 v[166:169], v243 offset:17408
	ds_read_b128 v[170:173], v243 offset:18432
	ds_read_b128 v[174:177], v243 offset:19456
	ds_read_b128 v[178:181], v243 offset:20480
	ds_read_b128 v[182:185], v243 offset:21504
	ds_read_b128 v[186:189], v243 offset:22528
	ds_read_b128 v[190:193], v243 offset:23552
	global_load_lds_dwordx4 v0, s[6:7]
	s_add_i32 m0, s0, 0x2000
	s_add_u32 s0, s6, 0x40000
	s_addc_u32 s1, s7, 0
	s_add_i32 s4, s4, s69
	global_load_lds_dwordx4 v214, s[6:7]
	s_mov_b32 m0, s4
	s_nop 0
	global_load_lds_dwordx4 v0, s[0:1]
	s_add_i32 m0, s4, 0x2000
	s_nop 0
	global_load_lds_dwordx4 v214, s[0:1]
	s_mov_b32 m0, s11
	s_nop 0
	global_load_lds_dwordx4 v210, s[12:13]
	s_mov_b32 m0, s71
	s_nop 0
	global_load_lds_dwordx4 v212, s[12:13]
	s_waitcnt vmcnt(8)
	s_waitcnt lgkmcnt(0)
	s_barrier
	s_waitcnt lgkmcnt(0)
	v_mfma_i32_16x16x64_i8 v[106:109], v[18:21], v[162:165], v[106:109]
	v_mfma_i32_16x16x64_i8 v[106:109], v[22:25], v[166:169], v[106:109]
	v_mfma_i32_16x16x64_i8 v[46:49], v[34:37], v[162:165], v[46:49]
	v_mfma_i32_16x16x64_i8 v[46:49], v[38:41], v[166:169], v[46:49]
	v_mfma_i32_16x16x64_i8 v[6:9], v[34:37], v[170:173], v[6:9]
	v_mfma_i32_16x16x64_i8 v[6:9], v[38:41], v[174:177], v[6:9]
	v_mfma_i32_16x16x64_i8 v[14:17], v[18:21], v[170:173], v[14:17]
	v_mfma_i32_16x16x64_i8 v[14:17], v[22:25], v[174:177], v[14:17]
	v_mfma_i32_16x16x64_i8 v[90:93], v[18:21], v[178:181], v[90:93]
	v_mfma_i32_16x16x64_i8 v[90:93], v[22:25], v[182:185], v[90:93]
	v_mfma_i32_16x16x64_i8 v[86:89], v[34:37], v[178:181], v[86:89]
	v_mfma_i32_16x16x64_i8 v[86:89], v[38:41], v[182:185], v[86:89]
	v_mfma_i32_16x16x64_i8 v[18:21], v[18:21], v[186:189], v[126:129]
	v_mfma_i32_16x16x64_i8 v[18:21], v[22:25], v[190:193], v[18:21]
	v_mfma_i32_16x16x64_i8 v[22:25], v[34:37], v[186:189], v[66:69]
	v_mfma_i32_16x16x64_i8 v[22:25], v[38:41], v[190:193], v[22:25]
	v_mfma_i32_16x16x64_i8 v[38:41], v[154:157], v[162:165], v[50:53]
	v_mfma_i32_16x16x64_i8 v[38:41], v[158:161], v[166:169], v[38:41]
	v_mfma_i32_16x16x64_i8 v[2:5], v[154:157], v[170:173], v[2:5]
	v_mfma_i32_16x16x64_i8 v[2:5], v[158:161], v[174:177], v[2:5]
	v_mfma_i32_16x16x64_i8 v[10:13], v[130:133], v[170:173], v[10:13]
	v_mfma_i32_16x16x64_i8 v[10:13], v[134:137], v[174:177], v[10:13]
	v_mfma_i32_16x16x64_i8 v[50:53], v[130:133], v[178:181], v[82:85]
	v_mfma_i32_16x16x64_i8 v[82:85], v[134:137], v[182:185], v[50:53]
	v_mfma_i32_16x16x64_i8 v[34:37], v[130:133], v[162:165], v[114:117]
	v_mfma_i32_16x16x64_i8 v[34:37], v[134:137], v[166:169], v[34:37]
	v_mfma_i32_16x16x64_i8 v[50:53], v[154:157], v[178:181], v[74:77]
	v_mfma_i32_16x16x64_i8 v[74:77], v[158:161], v[182:185], v[50:53]
	v_mfma_i32_16x16x64_i8 v[50:53], v[130:133], v[186:189], v[122:125]
	v_mfma_i32_16x16x64_i8 v[122:125], v[134:137], v[190:193], v[50:53]
	v_mfma_i32_16x16x64_i8 v[50:53], v[154:157], v[186:189], v[70:73]
	v_mfma_i32_16x16x64_i8 v[70:73], v[158:161], v[190:193], v[50:53]
	s_barrier
; #define PG8_STAGE(bufoff, gbase, voff) do { _Pragma("unroll") for (int _i = 0; _i < 2; ++_i) \
;         __builtin_amdgcn_global_load_lds((const unsigned*)((const char*)(gbase) + (voff)[_i]), (PG8_LAS unsigned*)(lds + (bufoff) + ldsw + _i * 8192), 16, 0, 0); } while (0)
; #define PG8_LDA(dst, b, h) do { _Pragma("unroll") for (int m = 0; m < 4; ++m) _Pragma("unroll") for (int k = 0; k < 2; ++k) dst[m][k] = *(const PG8_LAS bf16x8*)(lds + PG8_SA(b, h) + aoff + m * 2048 + k * 1024); } while (0)
; #define PG8_LDB(dst, b, h) do { _Pragma("unroll") for (int n = 0; n < 2; ++n) _Pragma("unroll") for (int k = 0; k < 2; ++k) dst[n][k] = *(const PG8_LAS bf16x8*)(lds + PG8_SB(b, h) + boff + n * 2048 + k * 1024); } while (0)
; #define PG8_MMA(ai, bj, At, Bt) do { __builtin_amdgcn_s_setprio(1); _Pragma("unroll") for (int m = 0; m < 4; ++m) _Pragma("unroll") for (int n = 0; n < 2; ++n) _Pragma("unroll") for (int k = 0; k < 2; ++k) \
;         acc[ai][bj][m][n] = mma16<Epi::I8>(Bt[n][k], At[m][k], acc[ai][bj][m][n]); __builtin_amdgcn_s_setprio(0); } while (0)
; #define PG8_WAIT_V(n) asm volatile("s_waitcnt vmcnt(" #n ")" ::: "memory")
; #define PG8_WAIT_L(n) asm volatile("s_waitcnt lgkmcnt(" #n ")" ::: "memory")
; #define PG8_BAR __builtin_amdgcn_s_barrier()
; #define PG8_SCHED __builtin_amdgcn_sched_barrier(0)
; template <class Epi, class Sched, bool ALIGN_EPI = false, bool SP2 = false>
; __device__ __forceinline__ void gemm_phase(PG8_LAS unsigned char* lds, const Gemm g, const Sched& S, const Epi& E) {
;     ...
;             PG8_LDB(B0, 1, 0); PG8_LDB(B1, 1, 1); PG8_SCHED; PG8_LDA(At, 1, 0); PG8_STAGE(PG8_SA(0, 1), a2 + hstep, voffA);
;             PG8_WAIT_V(8); PG8_WAIT_L(0); PG8_BAR; PG8_MMA(0, 0, At, B0); PG8_MMA(0, 1, At, B1); PG8_BAR; PG8_SCHED;
;             PG8_LDA(At, 1, 1); PG8_STAGE(PG8_SB(1, 0), b3, voffB); PG8_STAGE(PG8_SB(1, 1), b3 + hstep, voffB); PG8_STAGE(PG8_SA(1, 0), a3, voffA);
;             PG8_WAIT_V(8); PG8_WAIT_L(0); PG8_BAR; PG8_MMA(1, 0, At, B0); PG8_MMA(1, 1, At, B1); PG8_BAR; PG8_SCHED;
	s_add_i32 s4, 0, 0x18000
	v_add_u32_e32 v126, s4, v242
	s_add_i32 s5, 0, 0x1c000
	ds_read_b128 v[50:53], v126
	ds_read_b128 v[66:69], v126 offset:1024
	ds_read_b128 v[114:117], v126 offset:2048
	ds_read_b128 v[130:133], v126 offset:3072
	v_add_u32_e32 v126, s5, v242
	ds_read_b128 v[134:137], v126
	ds_read_b128 v[154:157], v126 offset:1024
	ds_read_b128 v[158:161], v126 offset:2048
	ds_read_b128 v[162:165], v126 offset:3072
	s_add_u32 s0, s12, 0x40000
	s_addc_u32 s1, s13, 0
	s_mov_b32 m0, s80
	ds_read_b128 v[126:129], v243 offset:32768
	ds_read_b128 v[166:169], v243 offset:33792
	ds_read_b128 v[170:173], v243 offset:34816
	ds_read_b128 v[174:177], v243 offset:35840
	ds_read_b128 v[178:181], v243 offset:36864
	ds_read_b128 v[182:185], v243 offset:37888
	ds_read_b128 v[186:189], v243 offset:38912
	ds_read_b128 v[190:193], v243 offset:39936
	global_load_lds_dwordx4 v210, s[0:1]
	s_mov_b32 m0, s81
	s_nop 0
	global_load_lds_dwordx4 v212, s[0:1]
	s_waitcnt vmcnt(8)
	s_waitcnt lgkmcnt(0)
	s_barrier
	s_waitcnt lgkmcnt(0)
	v_mfma_i32_16x16x64_i8 v[150:153], v[50:53], v[126:129], v[150:153]
	v_mfma_i32_16x16x64_i8 v[150:153], v[66:69], v[166:169], v[150:153]
	v_mfma_i32_16x16x64_i8 v[146:149], v[114:117], v[126:129], v[146:149]
	v_mfma_i32_16x16x64_i8 v[146:149], v[130:133], v[166:169], v[146:149]
	v_mfma_i32_16x16x64_i8 v[110:113], v[114:117], v[170:173], v[110:113]
	v_mfma_i32_16x16x64_i8 v[110:113], v[130:133], v[174:177], v[110:113]
	v_mfma_i32_16x16x64_i8 v[118:121], v[50:53], v[170:173], v[118:121]
	v_mfma_i32_16x16x64_i8 v[118:121], v[66:69], v[174:177], v[118:121]
	v_mfma_i32_16x16x64_i8 v[54:57], v[50:53], v[178:181], v[54:57]
	v_mfma_i32_16x16x64_i8 v[54:57], v[66:69], v[182:185], v[54:57]
	v_mfma_i32_16x16x64_i8 v[30:33], v[114:117], v[178:181], v[30:33]
	v_mfma_i32_16x16x64_i8 v[30:33], v[130:133], v[182:185], v[30:33]
	v_mfma_i32_16x16x64_i8 v[58:61], v[114:117], v[186:189], v[58:61]
	v_mfma_i32_16x16x64_i8 v[58:61], v[130:133], v[190:193], v[58:61]
	v_mfma_i32_16x16x64_i8 v[94:97], v[50:53], v[186:189], v[94:97]
	v_mfma_i32_16x16x64_i8 v[94:97], v[66:69], v[190:193], v[94:97]
	v_mfma_i32_16x16x64_i8 v[142:145], v[134:137], v[126:129], v[142:145]
	v_mfma_i32_16x16x64_i8 v[142:145], v[154:157], v[166:169], v[142:145]
	v_mfma_i32_16x16x64_i8 v[126:129], v[158:161], v[126:129], v[138:141]
	v_mfma_i32_16x16x64_i8 v[138:141], v[162:165], v[166:169], v[126:129]
	v_mfma_i32_16x16x64_i8 v[98:101], v[158:161], v[170:173], v[98:101]
	v_mfma_i32_16x16x64_i8 v[98:101], v[162:165], v[174:177], v[98:101]
	v_mfma_i32_16x16x64_i8 v[102:105], v[134:137], v[170:173], v[102:105]
	v_mfma_i32_16x16x64_i8 v[102:105], v[154:157], v[174:177], v[102:105]
	v_mfma_i32_16x16x64_i8 v[42:45], v[134:137], v[178:181], v[42:45]
	v_mfma_i32_16x16x64_i8 v[42:45], v[154:157], v[182:185], v[42:45]
	v_mfma_i32_16x16x64_i8 v[26:29], v[158:161], v[178:181], v[26:29]
	v_mfma_i32_16x16x64_i8 v[26:29], v[162:165], v[182:185], v[26:29]
	v_mfma_i32_16x16x64_i8 v[62:65], v[158:161], v[186:189], v[62:65]
	v_mfma_i32_16x16x64_i8 v[62:65], v[162:165], v[190:193], v[62:65]
	v_mfma_i32_16x16x64_i8 v[78:81], v[134:137], v[186:189], v[78:81]
	v_mfma_i32_16x16x64_i8 v[78:81], v[154:157], v[190:193], v[78:81]
	s_barrier
	s_add_u32 s98, s6, 0x80
	s_addc_u32 s99, s7, 0
	s_add_u32 s100, s12, 0x80
	s_addc_u32 s101, s13, 0
	s_add_i32 s0, s4, s69
	s_mov_b32 m0, s0
	ds_read_b128 v[166:169], v243 offset:49152
	ds_read_b128 v[170:173], v243 offset:50176
	ds_read_b128 v[174:177], v243 offset:51200
	ds_read_b128 v[178:181], v243 offset:52224
	ds_read_b128 v[182:185], v243 offset:53248
	ds_read_b128 v[186:189], v243 offset:54272
	ds_read_b128 v[190:193], v243 offset:55296
	ds_read_b128 v[194:197], v243 offset:56320
	global_load_lds_dwordx4 v0, s[98:99]
	s_add_i32 m0, s0, 0x2000
	s_add_u32 s0, s6, 0x40080
	s_addc_u32 s1, s7, 0
	s_add_i32 s4, s5, s69
	global_load_lds_dwordx4 v214, s[98:99]
	s_mov_b32 m0, s4
	s_nop 0
	global_load_lds_dwordx4 v0, s[0:1]
	s_add_i32 m0, s4, 0x2000
	s_nop 0
	global_load_lds_dwordx4 v214, s[0:1]
	s_mov_b32 m0, s84
	s_nop 0
	global_load_lds_dwordx4 v210, s[100:101]
	s_mov_b32 m0, s85
	s_nop 0
	global_load_lds_dwordx4 v212, s[100:101]
	s_waitcnt vmcnt(8)
	s_waitcnt lgkmcnt(0)
	s_barrier
	s_waitcnt lgkmcnt(0)
	v_mfma_i32_16x16x64_i8 v[18:21], v[50:53], v[190:193], v[18:21]
	v_mfma_i32_16x16x64_i8 v[126:129], v[66:69], v[194:197], v[18:21]
	v_mfma_i32_16x16x64_i8 v[106:109], v[50:53], v[166:169], v[106:109]
	v_mfma_i32_16x16x64_i8 v[106:109], v[66:69], v[170:173], v[106:109]
	v_mfma_i32_16x16x64_i8 v[46:49], v[114:117], v[166:169], v[46:49]
	v_mfma_i32_16x16x64_i8 v[46:49], v[130:133], v[170:173], v[46:49]
	v_mfma_i32_16x16x64_i8 v[6:9], v[114:117], v[174:177], v[6:9]
	v_mfma_i32_16x16x64_i8 v[6:9], v[130:133], v[178:181], v[6:9]
	v_mfma_i32_16x16x64_i8 v[14:17], v[50:53], v[174:177], v[14:17]
	v_mfma_i32_16x16x64_i8 v[14:17], v[66:69], v[178:181], v[14:17]
	v_mfma_i32_16x16x64_i8 v[90:93], v[50:53], v[182:185], v[90:93]
	v_mfma_i32_16x16x64_i8 v[90:93], v[66:69], v[186:189], v[90:93]
	v_mfma_i32_16x16x64_i8 v[86:89], v[114:117], v[182:185], v[86:89]
	v_mfma_i32_16x16x64_i8 v[86:89], v[130:133], v[186:189], v[86:89]
	v_mfma_i32_16x16x64_i8 v[18:21], v[114:117], v[190:193], v[22:25]
	v_mfma_i32_16x16x64_i8 v[66:69], v[130:133], v[194:197], v[18:21]
	v_mfma_i32_16x16x64_i8 v[18:21], v[134:137], v[166:169], v[34:37]
	v_mfma_i32_16x16x64_i8 v[114:117], v[154:157], v[170:173], v[18:21]
	v_mfma_i32_16x16x64_i8 v[10:13], v[134:137], v[174:177], v[10:13]
	v_mfma_i32_16x16x64_i8 v[10:13], v[154:157], v[178:181], v[10:13]
	v_mfma_i32_16x16x64_i8 v[2:5], v[158:161], v[174:177], v[2:5]
	v_mfma_i32_16x16x64_i8 v[2:5], v[162:165], v[178:181], v[2:5]
	v_mfma_i32_16x16x64_i8 v[18:21], v[158:161], v[166:169], v[38:41]
	v_mfma_i32_16x16x64_i8 v[50:53], v[162:165], v[170:173], v[18:21]
	v_mfma_i32_16x16x64_i8 v[18:21], v[134:137], v[182:185], v[82:85]
	v_mfma_i32_16x16x64_i8 v[82:85], v[154:157], v[186:189], v[18:21]
	v_mfma_i32_16x16x64_i8 v[18:21], v[158:161], v[182:185], v[74:77]
	v_mfma_i32_16x16x64_i8 v[74:77], v[162:165], v[186:189], v[18:21]
	v_mfma_i32_16x16x64_i8 v[18:21], v[134:137], v[190:193], v[122:125]
	v_mfma_i32_16x16x64_i8 v[122:125], v[154:157], v[194:197], v[18:21]
	v_mfma_i32_16x16x64_i8 v[18:21], v[158:161], v[190:193], v[70:73]
	v_mfma_i32_16x16x64_i8 v[70:73], v[162:165], v[194:197], v[18:21]
	s_barrier
	s_add_i32 vcc_lo, vcc_lo, 2
	s_add_u32 s96, s96, 0x100
	s_addc_u32 s97, s97, 0
	s_cmp_gt_u32 vcc_lo, 13
	s_mov_b64 s[0:1], s[8:9]
	s_cbranch_scc0 .LBB0_80

; #define PG8_STAGE(bufoff, gbase, voff) do { _Pragma("unroll") for (int _i = 0; _i < 2; ++_i) \
;         __builtin_amdgcn_global_load_lds((const unsigned*)((const char*)(gbase) + (voff)[_i]), (PG8_LAS unsigned*)(lds + (bufoff) + ldsw + _i * 8192), 16, 0, 0); } while (0)
; #define PG8_LDA(dst, b, h) do { _Pragma("unroll") for (int m = 0; m < 4; ++m) _Pragma("unroll") for (int k = 0; k < 2; ++k) dst[m][k] = *(const PG8_LAS bf16x8*)(lds + PG8_SA(b, h) + aoff + m * 2048 + k * 1024); } while (0)
; #define PG8_LDB(dst, b, h) do { _Pragma("unroll") for (int n = 0; n < 2; ++n) _Pragma("unroll") for (int k = 0; k < 2; ++k) dst[n][k] = *(const PG8_LAS bf16x8*)(lds + PG8_SB(b, h) + boff + n * 2048 + k * 1024); } while (0)
; #define PG8_MMA(ai, bj, At, Bt) do { __builtin_amdgcn_s_setprio(1); _Pragma("unroll") for (int m = 0; m < 4; ++m) _Pragma("unroll") for (int n = 0; n < 2; ++n) _Pragma("unroll") for (int k = 0; k < 2; ++k) \
;         acc[ai][bj][m][n] = mma16<Epi::I8>(Bt[n][k], At[m][k], acc[ai][bj][m][n]); __builtin_amdgcn_s_setprio(0); } while (0)
; #define PG8_WAIT_V(n) asm volatile("s_waitcnt vmcnt(" #n ")" ::: "memory")
; #define PG8_WAIT_L(n) asm volatile("s_waitcnt lgkmcnt(" #n ")" ::: "memory")
; #define PG8_BAR __builtin_amdgcn_s_barrier()
; template <class Epi, class Sched, bool ALIGN_EPI = false, bool SP2 = false>
; __device__ __forceinline__ void gemm_phase(PG8_LAS unsigned char* lds, const Gemm g, const Sched& S, const Epi& E) {
;     ...
;             const bool last = (t == nt - 2);
;             const char* a1 = cA + (size_t)(t + 1) * kstep;
;             const char* a2 = last ? nA : cA + (size_t)(t + 2) * kstep; const char* b2 = last ? nB : cB + (size_t)(t + 2) * kstep;
;             const char* a3 = a2 + kstep; const char* b3 = b2 + kstep;
;             if (last && has_next) S.a_ready(nxt);
;             if constexpr (SP2) {
;             PG8_LDB(B0, 0, 0); PG8_LDB(B1, 0, 1); PG8_SCHED; PG8_LDA(At, 0, 0); PG8_STAGE(PG8_SA(1, 1), a1 + hstep, voffA);
;             PG8_WAIT_V(8); PG8_WAIT_L(0); PG8_BAR; PG8_MMA(0, 0, At, B0); PG8_MMA(0, 1, At, B1); PG8_BAR; PG8_SCHED;
;             PG8_LDA(At, 0, 1); PG8_STAGE(PG8_SB(0, 0), b2, voffB); PG8_STAGE(PG8_SB(0, 1), b2 + hstep, voffB); PG8_STAGE(PG8_SA(0, 0), a2, voffA);
;             PG8_WAIT_V(8); PG8_WAIT_L(0); PG8_BAR; PG8_MMA(1, 0, At, B0); PG8_MMA(1, 1, At, B1); PG8_BAR; PG8_SCHED;
.Lpeel175:
	s_add_i32 vcc_lo, s8, 2
	s_add_u32 s4, s6, s98
	s_addc_u32 s5, s7, 0
	s_add_i32 vcc_hi, 0, 0x10000
	s_cmp_eq_u32 s13, s8
	s_cselect_b32 s9, s1, s5
	s_cselect_b32 s8, s0, s4
	s_cselect_b32 s5, s97, s85
	s_cselect_b32 s4, s96, s67
	s_add_i32 s84, 0, 0x14000
	v_add_u32_e32 v122, vcc_hi, v248
	v_add_u32_e32 v154, s84, v248
	ds_read_b128 v[98:101], v122
	ds_read_b128 v[102:105], v122 offset:1024
	ds_read_b128 v[114:117], v122 offset:2048
	ds_read_b128 v[122:125], v122 offset:3072
	ds_read_b128 v[130:133], v154
	ds_read_b128 v[138:141], v154 offset:1024
	ds_read_b128 v[146:149], v154 offset:2048
	ds_read_b128 v[154:157], v154 offset:3072
	s_add_i32 m0, s81, 0xc000
	ds_read_b128 v[162:165], v249
	ds_read_b128 v[166:169], v249 offset:1024
	ds_read_b128 v[170:173], v249 offset:2048
	ds_read_b128 v[174:177], v249 offset:3072
	ds_read_b128 v[178:181], v249 offset:4096
	ds_read_b128 v[182:185], v249 offset:5120
	ds_read_b128 v[186:189], v249 offset:6144
	ds_read_b128 v[190:193], v249 offset:7168
	global_load_lds_dwordx4 v200, s[6:7]
	s_add_i32 m0, s81, 0xe000
	s_nop 0
	global_load_lds_dwordx4 v210, s[6:7]
	s_waitcnt vmcnt(8)
	s_waitcnt lgkmcnt(0)
	s_barrier
	s_waitcnt lgkmcnt(0)
	v_mfma_f32_16x16x32_bf16 v[158:161], v[98:101], v[162:165], 0
	v_mfma_f32_16x16x32_bf16 v[158:161], v[102:105], v[166:169], v[158:161]
	v_mfma_f32_16x16x32_bf16 v[150:153], v[114:117], v[162:165], 0
	v_mfma_f32_16x16x32_bf16 v[150:153], v[122:125], v[166:169], v[150:153]
	v_mfma_f32_16x16x32_bf16 v[118:121], v[114:117], v[170:173], 0
	v_mfma_f32_16x16x32_bf16 v[118:121], v[122:125], v[174:177], v[118:121]
	v_mfma_f32_16x16x32_bf16 v[126:129], v[98:101], v[170:173], 0
	v_mfma_f32_16x16x32_bf16 v[126:129], v[102:105], v[174:177], v[126:129]
	v_mfma_f32_16x16x32_bf16 v[94:97], v[98:101], v[178:181], 0
	v_mfma_f32_16x16x32_bf16 v[94:97], v[102:105], v[182:185], v[94:97]
	v_mfma_f32_16x16x32_bf16 v[90:93], v[114:117], v[178:181], 0
	v_mfma_f32_16x16x32_bf16 v[90:93], v[122:125], v[182:185], v[90:93]
	v_mfma_f32_16x16x32_bf16 v[74:77], v[114:117], v[186:189], 0
	v_mfma_f32_16x16x32_bf16 v[74:77], v[122:125], v[190:193], v[74:77]
	v_mfma_f32_16x16x32_bf16 v[78:81], v[98:101], v[186:189], 0
	v_mfma_f32_16x16x32_bf16 v[78:81], v[102:105], v[190:193], v[78:81]
	v_mfma_f32_16x16x32_bf16 v[142:145], v[130:133], v[162:165], 0
	v_mfma_f32_16x16x32_bf16 v[142:145], v[138:141], v[166:169], v[142:145]
	v_mfma_f32_16x16x32_bf16 v[134:137], v[146:149], v[162:165], 0
	v_mfma_f32_16x16x32_bf16 v[134:137], v[154:157], v[166:169], v[134:137]
	v_mfma_f32_16x16x32_bf16 v[106:109], v[146:149], v[170:173], 0
	v_mfma_f32_16x16x32_bf16 v[106:109], v[154:157], v[174:177], v[106:109]
	v_mfma_f32_16x16x32_bf16 v[110:113], v[130:133], v[170:173], 0
	v_mfma_f32_16x16x32_bf16 v[110:113], v[138:141], v[174:177], v[110:113]
	v_mfma_f32_16x16x32_bf16 v[86:89], v[130:133], v[178:181], 0
	v_mfma_f32_16x16x32_bf16 v[86:89], v[138:141], v[182:185], v[86:89]
	v_mfma_f32_16x16x32_bf16 v[82:85], v[146:149], v[178:181], 0
	v_mfma_f32_16x16x32_bf16 v[82:85], v[154:157], v[182:185], v[82:85]
	v_mfma_f32_16x16x32_bf16 v[66:69], v[146:149], v[186:189], 0
	v_mfma_f32_16x16x32_bf16 v[66:69], v[154:157], v[190:193], v[66:69]
	v_mfma_f32_16x16x32_bf16 v[70:73], v[130:133], v[186:189], 0
	v_mfma_f32_16x16x32_bf16 v[70:73], v[138:141], v[190:193], v[70:73]
	s_barrier
	s_add_i32 vcc_hi, vcc_hi, s80
	s_mov_b64 s[92:93], s[4:5]
	s_mov_b32 m0, vcc_hi
	ds_read_b128 v[162:165], v249 offset:16384
	ds_read_b128 v[166:169], v249 offset:17408
	ds_read_b128 v[170:173], v249 offset:18432
	ds_read_b128 v[174:177], v249 offset:19456
	ds_read_b128 v[178:181], v249 offset:20480
	ds_read_b128 v[182:185], v249 offset:21504
	ds_read_b128 v[186:189], v249 offset:22528
	ds_read_b128 v[190:193], v249 offset:23552
	global_load_lds_dwordx4 v0, s[4:5]
	s_add_i32 m0, vcc_hi, 0x2000
	s_add_i32 s84, s84, s80
	global_load_lds_dwordx4 v198, s[4:5]
	s_add_u32 s4, s4, s100
	s_addc_u32 s5, s5, 0
	s_mov_b32 m0, s84
	s_nop 0
	global_load_lds_dwordx4 v0, s[4:5]
	s_add_i32 m0, s84, 0x2000
	s_nop 0
	global_load_lds_dwordx4 v198, s[4:5]
	s_mov_b32 m0, s81
	s_nop 0
	global_load_lds_dwordx4 v194, s[8:9]
	s_mov_b32 m0, s70
	s_nop 0
	global_load_lds_dwordx4 v196, s[8:9]
	s_waitcnt vmcnt(8)
	s_waitcnt lgkmcnt(0)
	s_barrier
	s_waitcnt lgkmcnt(0)
	v_mfma_f32_16x16x32_bf16 v[62:65], v[98:101], v[162:165], 0
	v_mfma_f32_16x16x32_bf16 v[62:65], v[102:105], v[166:169], v[62:65]
	v_mfma_f32_16x16x32_bf16 v[58:61], v[114:117], v[162:165], 0
	v_mfma_f32_16x16x32_bf16 v[58:61], v[122:125], v[166:169], v[58:61]
	v_mfma_f32_16x16x32_bf16 v[42:45], v[114:117], v[170:173], 0
	v_mfma_f32_16x16x32_bf16 v[42:45], v[122:125], v[174:177], v[42:45]
	v_mfma_f32_16x16x32_bf16 v[46:49], v[98:101], v[170:173], 0
	v_mfma_f32_16x16x32_bf16 v[46:49], v[102:105], v[174:177], v[46:49]
	v_mfma_f32_16x16x32_bf16 v[30:33], v[98:101], v[178:181], 0
	v_mfma_f32_16x16x32_bf16 v[30:33], v[102:105], v[182:185], v[30:33]
	v_mfma_f32_16x16x32_bf16 v[26:29], v[114:117], v[178:181], 0
	v_mfma_f32_16x16x32_bf16 v[26:29], v[122:125], v[182:185], v[26:29]
	v_mfma_f32_16x16x32_bf16 v[10:13], v[114:117], v[186:189], 0
	v_mfma_f32_16x16x32_bf16 v[10:13], v[122:125], v[190:193], v[10:13]
	v_mfma_f32_16x16x32_bf16 v[14:17], v[98:101], v[186:189], 0
	v_mfma_f32_16x16x32_bf16 v[14:17], v[102:105], v[190:193], v[14:17]
	v_mfma_f32_16x16x32_bf16 v[54:57], v[130:133], v[162:165], 0
	v_mfma_f32_16x16x32_bf16 v[54:57], v[138:141], v[166:169], v[54:57]
	v_mfma_f32_16x16x32_bf16 v[50:53], v[146:149], v[162:165], 0
	v_mfma_f32_16x16x32_bf16 v[50:53], v[154:157], v[166:169], v[50:53]
	v_mfma_f32_16x16x32_bf16 v[34:37], v[146:149], v[170:173], 0
	v_mfma_f32_16x16x32_bf16 v[34:37], v[154:157], v[174:177], v[34:37]
	v_mfma_f32_16x16x32_bf16 v[38:41], v[130:133], v[170:173], 0
	v_mfma_f32_16x16x32_bf16 v[38:41], v[138:141], v[174:177], v[38:41]
	v_mfma_f32_16x16x32_bf16 v[22:25], v[130:133], v[178:181], 0
	v_mfma_f32_16x16x32_bf16 v[22:25], v[138:141], v[182:185], v[22:25]
	v_mfma_f32_16x16x32_bf16 v[18:21], v[146:149], v[178:181], 0
	v_mfma_f32_16x16x32_bf16 v[18:21], v[154:157], v[182:185], v[18:21]
	v_mfma_f32_16x16x32_bf16 v[2:5], v[146:149], v[186:189], 0
	v_mfma_f32_16x16x32_bf16 v[2:5], v[154:157], v[190:193], v[2:5]
	v_mfma_f32_16x16x32_bf16 v[6:9], v[130:133], v[186:189], 0
	v_mfma_f32_16x16x32_bf16 v[6:9], v[138:141], v[190:193], v[6:9]
	s_barrier
; #define PG8_STAGE(bufoff, gbase, voff) do { _Pragma("unroll") for (int _i = 0; _i < 2; ++_i) \
;         __builtin_amdgcn_global_load_lds((const unsigned*)((const char*)(gbase) + (voff)[_i]), (PG8_LAS unsigned*)(lds + (bufoff) + ldsw + _i * 8192), 16, 0, 0); } while (0)
; #define PG8_LDA(dst, b, h) do { _Pragma("unroll") for (int m = 0; m < 4; ++m) _Pragma("unroll") for (int k = 0; k < 2; ++k) dst[m][k] = *(const PG8_LAS bf16x8*)(lds + PG8_SA(b, h) + aoff + m * 2048 + k * 1024); } while (0)
; #define PG8_LDB(dst, b, h) do { _Pragma("unroll") for (int n = 0; n < 2; ++n) _Pragma("unroll") for (int k = 0; k < 2; ++k) dst[n][k] = *(const PG8_LAS bf16x8*)(lds + PG8_SB(b, h) + boff + n * 2048 + k * 1024); } while (0)
; #define PG8_MMA(ai, bj, At, Bt) do { __builtin_amdgcn_s_setprio(1); _Pragma("unroll") for (int m = 0; m < 4; ++m) _Pragma("unroll") for (int n = 0; n < 2; ++n) _Pragma("unroll") for (int k = 0; k < 2; ++k) \
;         acc[ai][bj][m][n] = mma16<Epi::I8>(Bt[n][k], At[m][k], acc[ai][bj][m][n]); __builtin_amdgcn_s_setprio(0); } while (0)
; #define PG8_WAIT_V(n) asm volatile("s_waitcnt vmcnt(" #n ")" ::: "memory")
; #define PG8_WAIT_L(n) asm volatile("s_waitcnt lgkmcnt(" #n ")" ::: "memory")
; #define PG8_BAR __builtin_amdgcn_s_barrier()
; #define PG8_SCHED __builtin_amdgcn_sched_barrier(0)
; template <class Epi, class Sched, bool ALIGN_EPI = false, bool SP2 = false>
; __device__ __forceinline__ void gemm_phase(PG8_LAS unsigned char* lds, const Gemm g, const Sched& S, const Epi& E) {
;     ...
;             PG8_LDB(B0, 1, 0); PG8_LDB(B1, 1, 1); PG8_SCHED; PG8_LDA(At, 1, 0); PG8_STAGE(PG8_SA(0, 1), a2 + hstep, voffA);
;             PG8_WAIT_V(8); PG8_WAIT_L(0); PG8_BAR; PG8_MMA(0, 0, At, B0); PG8_MMA(0, 1, At, B1); PG8_BAR; PG8_SCHED;
;             PG8_LDA(At, 1, 1); PG8_STAGE(PG8_SB(1, 0), b3, voffB); PG8_STAGE(PG8_SB(1, 1), b3 + hstep, voffB); PG8_STAGE(PG8_SA(1, 0), a3, voffA);
;             PG8_WAIT_V(8); PG8_WAIT_L(0); PG8_BAR; PG8_MMA(1, 0, At, B0); PG8_MMA(1, 1, At, B1); PG8_BAR; PG8_SCHED;
	s_add_i32 s84, 0, 0x18000
	s_add_i32 vcc_hi, 0, 0x1c000
	v_add_u32_e32 v122, s84, v248
	v_add_u32_e32 v154, vcc_hi, v248
	ds_read_b128 v[98:101], v122
	ds_read_b128 v[102:105], v122 offset:1024
	ds_read_b128 v[114:117], v122 offset:2048
	ds_read_b128 v[122:125], v122 offset:3072
	ds_read_b128 v[130:133], v154
	ds_read_b128 v[138:141], v154 offset:1024
	ds_read_b128 v[146:149], v154 offset:2048
	ds_read_b128 v[154:157], v154 offset:3072
	s_add_u32 s4, s8, s100
	s_addc_u32 s5, s9, 0
	s_mov_b32 m0, s71
	ds_read_b128 v[162:165], v249 offset:32768
	ds_read_b128 v[166:169], v249 offset:33792
	ds_read_b128 v[170:173], v249 offset:34816
	ds_read_b128 v[174:177], v249 offset:35840
	ds_read_b128 v[178:181], v249 offset:36864
	ds_read_b128 v[182:185], v249 offset:37888
	ds_read_b128 v[186:189], v249 offset:38912
	ds_read_b128 v[190:193], v249 offset:39936
	global_load_lds_dwordx4 v194, s[4:5]
	s_mov_b32 m0, s12
	s_nop 0
	global_load_lds_dwordx4 v196, s[4:5]
	s_waitcnt vmcnt(8)
	s_waitcnt lgkmcnt(0)
	s_barrier
	s_waitcnt lgkmcnt(0)
	v_mfma_f32_16x16x32_bf16 v[158:161], v[98:101], v[162:165], v[158:161]
	v_mfma_f32_16x16x32_bf16 v[158:161], v[102:105], v[166:169], v[158:161]
	v_mfma_f32_16x16x32_bf16 v[150:153], v[114:117], v[162:165], v[150:153]
	v_mfma_f32_16x16x32_bf16 v[150:153], v[122:125], v[166:169], v[150:153]
	v_mfma_f32_16x16x32_bf16 v[118:121], v[114:117], v[170:173], v[118:121]
	v_mfma_f32_16x16x32_bf16 v[118:121], v[122:125], v[174:177], v[118:121]
	v_mfma_f32_16x16x32_bf16 v[126:129], v[98:101], v[170:173], v[126:129]
	v_mfma_f32_16x16x32_bf16 v[126:129], v[102:105], v[174:177], v[126:129]
	v_mfma_f32_16x16x32_bf16 v[94:97], v[98:101], v[178:181], v[94:97]
	v_mfma_f32_16x16x32_bf16 v[94:97], v[102:105], v[182:185], v[94:97]
	v_mfma_f32_16x16x32_bf16 v[90:93], v[114:117], v[178:181], v[90:93]
	v_mfma_f32_16x16x32_bf16 v[90:93], v[122:125], v[182:185], v[90:93]
	v_mfma_f32_16x16x32_bf16 v[74:77], v[114:117], v[186:189], v[74:77]
	v_mfma_f32_16x16x32_bf16 v[74:77], v[122:125], v[190:193], v[74:77]
	v_mfma_f32_16x16x32_bf16 v[78:81], v[98:101], v[186:189], v[78:81]
	v_mfma_f32_16x16x32_bf16 v[78:81], v[102:105], v[190:193], v[78:81]
	v_mfma_f32_16x16x32_bf16 v[142:145], v[130:133], v[162:165], v[142:145]
	v_mfma_f32_16x16x32_bf16 v[142:145], v[138:141], v[166:169], v[142:145]
	v_mfma_f32_16x16x32_bf16 v[134:137], v[146:149], v[162:165], v[134:137]
	v_mfma_f32_16x16x32_bf16 v[134:137], v[154:157], v[166:169], v[134:137]
	v_mfma_f32_16x16x32_bf16 v[106:109], v[146:149], v[170:173], v[106:109]
	v_mfma_f32_16x16x32_bf16 v[106:109], v[154:157], v[174:177], v[106:109]
	v_mfma_f32_16x16x32_bf16 v[110:113], v[130:133], v[170:173], v[110:113]
	v_mfma_f32_16x16x32_bf16 v[110:113], v[138:141], v[174:177], v[110:113]
	v_mfma_f32_16x16x32_bf16 v[86:89], v[130:133], v[178:181], v[86:89]
	v_mfma_f32_16x16x32_bf16 v[86:89], v[138:141], v[182:185], v[86:89]
	v_mfma_f32_16x16x32_bf16 v[82:85], v[146:149], v[178:181], v[82:85]
	v_mfma_f32_16x16x32_bf16 v[82:85], v[154:157], v[182:185], v[82:85]
	v_mfma_f32_16x16x32_bf16 v[66:69], v[146:149], v[186:189], v[66:69]
	v_mfma_f32_16x16x32_bf16 v[66:69], v[154:157], v[190:193], v[66:69]
	v_mfma_f32_16x16x32_bf16 v[70:73], v[130:133], v[186:189], v[70:73]
	v_mfma_f32_16x16x32_bf16 v[70:73], v[138:141], v[190:193], v[70:73]
	s_barrier
	s_add_u32 s4, s92, s98
	s_addc_u32 s5, s93, 0
	s_add_i32 m0, s84, s80
	ds_read_b128 v[162:165], v249 offset:49152
	ds_read_b128 v[166:169], v249 offset:50176
	ds_read_b128 v[170:173], v249 offset:51200
	ds_read_b128 v[174:177], v249 offset:52224
	ds_read_b128 v[178:181], v249 offset:53248
	ds_read_b128 v[182:185], v249 offset:54272
	ds_read_b128 v[186:189], v249 offset:55296
	ds_read_b128 v[190:193], v249 offset:56320
	global_load_lds_dwordx4 v0, s[4:5]
	s_add_i32 m0, s84, s80
	s_add_i32 m0, m0, 0x2000
	s_nop 0
	global_load_lds_dwordx4 v198, s[4:5]
	s_add_u32 s4, s4, s100
	s_addc_u32 s5, s5, 0
	s_add_i32 m0, vcc_hi, s80
	s_nop 0
	global_load_lds_dwordx4 v0, s[4:5]
	s_add_i32 m0, vcc_hi, s80
	s_add_i32 m0, m0, 0x2000
	s_nop 0
	global_load_lds_dwordx4 v198, s[4:5]
	s_add_u32 s4, s8, s98
	s_addc_u32 s5, s9, 0
	s_mov_b32 m0, s10
	s_nop 0
	global_load_lds_dwordx4 v194, s[4:5]
	s_mov_b32 m0, s11
	s_nop 0
	global_load_lds_dwordx4 v196, s[4:5]
	s_waitcnt vmcnt(8)
	s_waitcnt lgkmcnt(0)
	s_barrier
	s_waitcnt lgkmcnt(0)
	v_mfma_f32_16x16x32_bf16 v[62:65], v[98:101], v[162:165], v[62:65]
	v_mfma_f32_16x16x32_bf16 v[62:65], v[102:105], v[166:169], v[62:65]
	v_mfma_f32_16x16x32_bf16 v[58:61], v[114:117], v[162:165], v[58:61]
	v_mfma_f32_16x16x32_bf16 v[58:61], v[122:125], v[166:169], v[58:61]
	v_mfma_f32_16x16x32_bf16 v[42:45], v[114:117], v[170:173], v[42:45]
	v_mfma_f32_16x16x32_bf16 v[42:45], v[122:125], v[174:177], v[42:45]
	v_mfma_f32_16x16x32_bf16 v[46:49], v[98:101], v[170:173], v[46:49]
	v_mfma_f32_16x16x32_bf16 v[46:49], v[102:105], v[174:177], v[46:49]
	v_mfma_f32_16x16x32_bf16 v[30:33], v[98:101], v[178:181], v[30:33]
	v_mfma_f32_16x16x32_bf16 v[30:33], v[102:105], v[182:185], v[30:33]
	v_mfma_f32_16x16x32_bf16 v[26:29], v[114:117], v[178:181], v[26:29]
	v_mfma_f32_16x16x32_bf16 v[26:29], v[122:125], v[182:185], v[26:29]
	v_mfma_f32_16x16x32_bf16 v[10:13], v[114:117], v[186:189], v[10:13]
	v_mfma_f32_16x16x32_bf16 v[10:13], v[122:125], v[190:193], v[10:13]
	v_mfma_f32_16x16x32_bf16 v[14:17], v[98:101], v[186:189], v[14:17]
	v_mfma_f32_16x16x32_bf16 v[14:17], v[102:105], v[190:193], v[14:17]
	v_mfma_f32_16x16x32_bf16 v[54:57], v[130:133], v[162:165], v[54:57]
	v_mfma_f32_16x16x32_bf16 v[54:57], v[138:141], v[166:169], v[54:57]
	v_mfma_f32_16x16x32_bf16 v[50:53], v[146:149], v[162:165], v[50:53]
	v_mfma_f32_16x16x32_bf16 v[50:53], v[154:157], v[166:169], v[50:53]
	v_mfma_f32_16x16x32_bf16 v[34:37], v[146:149], v[170:173], v[34:37]
	v_mfma_f32_16x16x32_bf16 v[34:37], v[154:157], v[174:177], v[34:37]
	v_mfma_f32_16x16x32_bf16 v[38:41], v[130:133], v[170:173], v[38:41]
	v_mfma_f32_16x16x32_bf16 v[38:41], v[138:141], v[174:177], v[38:41]
	v_mfma_f32_16x16x32_bf16 v[22:25], v[130:133], v[178:181], v[22:25]
	v_mfma_f32_16x16x32_bf16 v[22:25], v[138:141], v[182:185], v[22:25]
	v_mfma_f32_16x16x32_bf16 v[18:21], v[146:149], v[178:181], v[18:21]
	v_mfma_f32_16x16x32_bf16 v[18:21], v[154:157], v[182:185], v[18:21]
	v_mfma_f32_16x16x32_bf16 v[2:5], v[146:149], v[186:189], v[2:5]
	v_mfma_f32_16x16x32_bf16 v[2:5], v[154:157], v[190:193], v[2:5]
	v_mfma_f32_16x16x32_bf16 v[6:9], v[130:133], v[186:189], v[6:9]
	v_mfma_f32_16x16x32_bf16 v[6:9], v[138:141], v[190:193], v[6:9]
	s_barrier
	s_add_u32 s6, s6, s98
	s_addc_u32 s7, s7, 0
	s_add_u32 s6, s6, s98
	s_addc_u32 s7, s7, 0
	s_add_u32 s67, s67, s98
	s_addc_u32 s85, s85, 0
	s_add_u32 s67, s67, s98
	s_addc_u32 s85, s85, 0
	s_cmp_ge_u32 vcc_lo, s69
	s_mov_b32 s8, vcc_lo
	s_cbranch_scc0 .LBB0_175
	s_branch .Lpeelx175
; #define PG8_STAGE(bufoff, gbase, voff) do { _Pragma("unroll") for (int _i = 0; _i < 2; ++_i) \
;         __builtin_amdgcn_global_load_lds((const unsigned*)((const char*)(gbase) + (voff)[_i]), (PG8_LAS unsigned*)(lds + (bufoff) + ldsw + _i * 8192), 16, 0, 0); } while (0)
; #define PG8_LDA(dst, b, h) do { _Pragma("unroll") for (int m = 0; m < 4; ++m) _Pragma("unroll") for (int k = 0; k < 2; ++k) dst[m][k] = *(const PG8_LAS bf16x8*)(lds + PG8_SA(b, h) + aoff + m * 2048 + k * 1024); } while (0)
; #define PG8_LDB(dst, b, h) do { _Pragma("unroll") for (int n = 0; n < 2; ++n) _Pragma("unroll") for (int k = 0; k < 2; ++k) dst[n][k] = *(const PG8_LAS bf16x8*)(lds + PG8_SB(b, h) + boff + n * 2048 + k * 1024); } while (0)
; #define PG8_MMA(ai, bj, At, Bt) do { __builtin_amdgcn_s_setprio(1); _Pragma("unroll") for (int m = 0; m < 4; ++m) _Pragma("unroll") for (int n = 0; n < 2; ++n) _Pragma("unroll") for (int k = 0; k < 2; ++k) \
;         acc[ai][bj][m][n] = mma16<Epi::I8>(Bt[n][k], At[m][k], acc[ai][bj][m][n]); __builtin_amdgcn_s_setprio(0); } while (0)
; #define PG8_WAIT_V(n) asm volatile("s_waitcnt vmcnt(" #n ")" ::: "memory")
; #define PG8_WAIT_L(n) asm volatile("s_waitcnt lgkmcnt(" #n ")" ::: "memory")
; #define PG8_BAR __builtin_amdgcn_s_barrier()
; template <class Epi, class Sched, bool ALIGN_EPI = false, bool SP2 = false>
; __device__ __forceinline__ void gemm_phase(PG8_LAS unsigned char* lds, const Gemm g, const Sched& S, const Epi& E) {
;     ...
;             const bool last = (t == nt - 2);
;             const char* a1 = cA + (size_t)(t + 1) * kstep;
;             const char* a2 = last ? nA : cA + (size_t)(t + 2) * kstep; const char* b2 = last ? nB : cB + (size_t)(t + 2) * kstep;
;             const char* a3 = a2 + kstep; const char* b3 = b2 + kstep;
;             if (last && has_next) S.a_ready(nxt);
;             if constexpr (SP2) {
;             PG8_LDB(B0, 0, 0); PG8_LDB(B1, 0, 1); PG8_SCHED; PG8_LDA(At, 0, 0); PG8_STAGE(PG8_SA(1, 1), a1 + hstep, voffA);
;             PG8_WAIT_V(8); PG8_WAIT_L(0); PG8_BAR; PG8_MMA(0, 0, At, B0); PG8_MMA(0, 1, At, B1); PG8_BAR; PG8_SCHED;
;             PG8_LDA(At, 0, 1); PG8_STAGE(PG8_SB(0, 0), b2, voffB); PG8_STAGE(PG8_SB(0, 1), b2 + hstep, voffB); PG8_STAGE(PG8_SA(0, 0), a2, voffA);
;             PG8_WAIT_V(8); PG8_WAIT_L(0); PG8_BAR; PG8_MMA(1, 0, At, B0); PG8_MMA(1, 1, At, B1); PG8_BAR; PG8_SCHED;
.LBB0_175:
	s_add_i32 vcc_lo, s8, 2
	s_add_u32 s4, s6, s98
	s_addc_u32 s5, s7, 0
	s_add_i32 vcc_hi, 0, 0x10000
	s_cmp_eq_u32 s13, s8
	s_cselect_b32 s9, s1, s5
	s_cselect_b32 s8, s0, s4
	s_cselect_b32 s5, s97, s85
	s_cselect_b32 s4, s96, s67
	s_add_i32 s84, 0, 0x14000
	v_add_u32_e32 v122, vcc_hi, v248
	v_add_u32_e32 v154, s84, v248
	ds_read_b128 v[98:101], v122
	ds_read_b128 v[102:105], v122 offset:1024
	ds_read_b128 v[114:117], v122 offset:2048
	ds_read_b128 v[122:125], v122 offset:3072
	ds_read_b128 v[130:133], v154
	ds_read_b128 v[138:141], v154 offset:1024
	ds_read_b128 v[146:149], v154 offset:2048
	ds_read_b128 v[154:157], v154 offset:3072
	s_add_i32 m0, s81, 0xc000
	ds_read_b128 v[162:165], v249
	ds_read_b128 v[166:169], v249 offset:1024
	ds_read_b128 v[170:173], v249 offset:2048
	ds_read_b128 v[174:177], v249 offset:3072
	ds_read_b128 v[178:181], v249 offset:4096
	ds_read_b128 v[182:185], v249 offset:5120
	ds_read_b128 v[186:189], v249 offset:6144
	ds_read_b128 v[190:193], v249 offset:7168
	global_load_lds_dwordx4 v200, s[6:7]
	s_add_i32 m0, s81, 0xe000
	s_nop 0
	global_load_lds_dwordx4 v210, s[6:7]
	s_waitcnt vmcnt(8)
	s_waitcnt lgkmcnt(0)
	s_barrier
	s_waitcnt lgkmcnt(0)
	v_mfma_f32_16x16x32_bf16 v[158:161], v[98:101], v[162:165], v[158:161]
	v_mfma_f32_16x16x32_bf16 v[158:161], v[102:105], v[166:169], v[158:161]
	v_mfma_f32_16x16x32_bf16 v[150:153], v[114:117], v[162:165], v[150:153]
	v_mfma_f32_16x16x32_bf16 v[150:153], v[122:125], v[166:169], v[150:153]
	v_mfma_f32_16x16x32_bf16 v[118:121], v[114:117], v[170:173], v[118:121]
	v_mfma_f32_16x16x32_bf16 v[118:121], v[122:125], v[174:177], v[118:121]
	v_mfma_f32_16x16x32_bf16 v[126:129], v[98:101], v[170:173], v[126:129]
	v_mfma_f32_16x16x32_bf16 v[126:129], v[102:105], v[174:177], v[126:129]
	v_mfma_f32_16x16x32_bf16 v[94:97], v[98:101], v[178:181], v[94:97]
	v_mfma_f32_16x16x32_bf16 v[94:97], v[102:105], v[182:185], v[94:97]
	v_mfma_f32_16x16x32_bf16 v[90:93], v[114:117], v[178:181], v[90:93]
	v_mfma_f32_16x16x32_bf16 v[90:93], v[122:125], v[182:185], v[90:93]
	v_mfma_f32_16x16x32_bf16 v[74:77], v[114:117], v[186:189], v[74:77]
	v_mfma_f32_16x16x32_bf16 v[74:77], v[122:125], v[190:193], v[74:77]
	v_mfma_f32_16x16x32_bf16 v[78:81], v[98:101], v[186:189], v[78:81]
	v_mfma_f32_16x16x32_bf16 v[78:81], v[102:105], v[190:193], v[78:81]
	v_mfma_f32_16x16x32_bf16 v[142:145], v[130:133], v[162:165], v[142:145]
	v_mfma_f32_16x16x32_bf16 v[142:145], v[138:141], v[166:169], v[142:145]
	v_mfma_f32_16x16x32_bf16 v[134:137], v[146:149], v[162:165], v[134:137]
	v_mfma_f32_16x16x32_bf16 v[134:137], v[154:157], v[166:169], v[134:137]
	v_mfma_f32_16x16x32_bf16 v[106:109], v[146:149], v[170:173], v[106:109]
	v_mfma_f32_16x16x32_bf16 v[106:109], v[154:157], v[174:177], v[106:109]
	v_mfma_f32_16x16x32_bf16 v[110:113], v[130:133], v[170:173], v[110:113]
	v_mfma_f32_16x16x32_bf16 v[110:113], v[138:141], v[174:177], v[110:113]
	v_mfma_f32_16x16x32_bf16 v[86:89], v[130:133], v[178:181], v[86:89]
	v_mfma_f32_16x16x32_bf16 v[86:89], v[138:141], v[182:185], v[86:89]
	v_mfma_f32_16x16x32_bf16 v[82:85], v[146:149], v[178:181], v[82:85]
	v_mfma_f32_16x16x32_bf16 v[82:85], v[154:157], v[182:185], v[82:85]
	v_mfma_f32_16x16x32_bf16 v[66:69], v[146:149], v[186:189], v[66:69]
	v_mfma_f32_16x16x32_bf16 v[66:69], v[154:157], v[190:193], v[66:69]
	v_mfma_f32_16x16x32_bf16 v[70:73], v[130:133], v[186:189], v[70:73]
	v_mfma_f32_16x16x32_bf16 v[70:73], v[138:141], v[190:193], v[70:73]
	s_barrier
	s_add_i32 vcc_hi, vcc_hi, s80
	s_mov_b64 s[92:93], s[4:5]
	s_mov_b32 m0, vcc_hi
	ds_read_b128 v[162:165], v249 offset:16384
	ds_read_b128 v[166:169], v249 offset:17408
	ds_read_b128 v[170:173], v249 offset:18432
	ds_read_b128 v[174:177], v249 offset:19456
	ds_read_b128 v[178:181], v249 offset:20480
	ds_read_b128 v[182:185], v249 offset:21504
	ds_read_b128 v[186:189], v249 offset:22528
	ds_read_b128 v[190:193], v249 offset:23552
	global_load_lds_dwordx4 v0, s[4:5]
	s_add_i32 m0, vcc_hi, 0x2000
	s_add_i32 s84, s84, s80
	global_load_lds_dwordx4 v198, s[4:5]
	s_add_u32 s4, s4, s100
	s_addc_u32 s5, s5, 0
	s_mov_b32 m0, s84
	s_nop 0
	global_load_lds_dwordx4 v0, s[4:5]
	s_add_i32 m0, s84, 0x2000
	s_nop 0
	global_load_lds_dwordx4 v198, s[4:5]
	s_mov_b32 m0, s81
	s_nop 0
	global_load_lds_dwordx4 v194, s[8:9]
	s_mov_b32 m0, s70
	s_nop 0
	global_load_lds_dwordx4 v196, s[8:9]
	s_waitcnt vmcnt(8)
	s_waitcnt lgkmcnt(0)
	s_barrier
	s_waitcnt lgkmcnt(0)
	v_mfma_f32_16x16x32_bf16 v[62:65], v[98:101], v[162:165], v[62:65]
	v_mfma_f32_16x16x32_bf16 v[62:65], v[102:105], v[166:169], v[62:65]
	v_mfma_f32_16x16x32_bf16 v[58:61], v[114:117], v[162:165], v[58:61]
	v_mfma_f32_16x16x32_bf16 v[58:61], v[122:125], v[166:169], v[58:61]
	v_mfma_f32_16x16x32_bf16 v[42:45], v[114:117], v[170:173], v[42:45]
	v_mfma_f32_16x16x32_bf16 v[42:45], v[122:125], v[174:177], v[42:45]
	v_mfma_f32_16x16x32_bf16 v[46:49], v[98:101], v[170:173], v[46:49]
	v_mfma_f32_16x16x32_bf16 v[46:49], v[102:105], v[174:177], v[46:49]
	v_mfma_f32_16x16x32_bf16 v[30:33], v[98:101], v[178:181], v[30:33]
	v_mfma_f32_16x16x32_bf16 v[30:33], v[102:105], v[182:185], v[30:33]
	v_mfma_f32_16x16x32_bf16 v[26:29], v[114:117], v[178:181], v[26:29]
	v_mfma_f32_16x16x32_bf16 v[26:29], v[122:125], v[182:185], v[26:29]
	v_mfma_f32_16x16x32_bf16 v[10:13], v[114:117], v[186:189], v[10:13]
	v_mfma_f32_16x16x32_bf16 v[10:13], v[122:125], v[190:193], v[10:13]
	v_mfma_f32_16x16x32_bf16 v[14:17], v[98:101], v[186:189], v[14:17]
	v_mfma_f32_16x16x32_bf16 v[14:17], v[102:105], v[190:193], v[14:17]
	v_mfma_f32_16x16x32_bf16 v[54:57], v[130:133], v[162:165], v[54:57]
	v_mfma_f32_16x16x32_bf16 v[54:57], v[138:141], v[166:169], v[54:57]
	v_mfma_f32_16x16x32_bf16 v[50:53], v[146:149], v[162:165], v[50:53]
	v_mfma_f32_16x16x32_bf16 v[50:53], v[154:157], v[166:169], v[50:53]
	v_mfma_f32_16x16x32_bf16 v[34:37], v[146:149], v[170:173], v[34:37]
	v_mfma_f32_16x16x32_bf16 v[34:37], v[154:157], v[174:177], v[34:37]
	v_mfma_f32_16x16x32_bf16 v[38:41], v[130:133], v[170:173], v[38:41]
	v_mfma_f32_16x16x32_bf16 v[38:41], v[138:141], v[174:177], v[38:41]
	v_mfma_f32_16x16x32_bf16 v[22:25], v[130:133], v[178:181], v[22:25]
	v_mfma_f32_16x16x32_bf16 v[22:25], v[138:141], v[182:185], v[22:25]
	v_mfma_f32_16x16x32_bf16 v[18:21], v[146:149], v[178:181], v[18:21]
	v_mfma_f32_16x16x32_bf16 v[18:21], v[154:157], v[182:185], v[18:21]
	v_mfma_f32_16x16x32_bf16 v[2:5], v[146:149], v[186:189], v[2:5]
	v_mfma_f32_16x16x32_bf16 v[2:5], v[154:157], v[190:193], v[2:5]
	v_mfma_f32_16x16x32_bf16 v[6:9], v[130:133], v[186:189], v[6:9]
	v_mfma_f32_16x16x32_bf16 v[6:9], v[138:141], v[190:193], v[6:9]
	s_barrier
; #define PG8_STAGE(bufoff, gbase, voff) do { _Pragma("unroll") for (int _i = 0; _i < 2; ++_i) \
;         __builtin_amdgcn_global_load_lds((const unsigned*)((const char*)(gbase) + (voff)[_i]), (PG8_LAS unsigned*)(lds + (bufoff) + ldsw + _i * 8192), 16, 0, 0); } while (0)
; #define PG8_LDA(dst, b, h) do { _Pragma("unroll") for (int m = 0; m < 4; ++m) _Pragma("unroll") for (int k = 0; k < 2; ++k) dst[m][k] = *(const PG8_LAS bf16x8*)(lds + PG8_SA(b, h) + aoff + m * 2048 + k * 1024); } while (0)
; #define PG8_LDB(dst, b, h) do { _Pragma("unroll") for (int n = 0; n < 2; ++n) _Pragma("unroll") for (int k = 0; k < 2; ++k) dst[n][k] = *(const PG8_LAS bf16x8*)(lds + PG8_SB(b, h) + boff + n * 2048 + k * 1024); } while (0)
; #define PG8_MMA(ai, bj, At, Bt) do { __builtin_amdgcn_s_setprio(1); _Pragma("unroll") for (int m = 0; m < 4; ++m) _Pragma("unroll") for (int n = 0; n < 2; ++n) _Pragma("unroll") for (int k = 0; k < 2; ++k) \
;         acc[ai][bj][m][n] = mma16<Epi::I8>(Bt[n][k], At[m][k], acc[ai][bj][m][n]); __builtin_amdgcn_s_setprio(0); } while (0)
; #define PG8_WAIT_V(n) asm volatile("s_waitcnt vmcnt(" #n ")" ::: "memory")
; #define PG8_WAIT_L(n) asm volatile("s_waitcnt lgkmcnt(" #n ")" ::: "memory")
; #define PG8_BAR __builtin_amdgcn_s_barrier()
; #define PG8_SCHED __builtin_amdgcn_sched_barrier(0)
; template <class Epi, class Sched, bool ALIGN_EPI = false, bool SP2 = false>
; __device__ __forceinline__ void gemm_phase(PG8_LAS unsigned char* lds, const Gemm g, const Sched& S, const Epi& E) {
;     ...
;             PG8_LDB(B0, 1, 0); PG8_LDB(B1, 1, 1); PG8_SCHED; PG8_LDA(At, 1, 0); PG8_STAGE(PG8_SA(0, 1), a2 + hstep, voffA);
;             PG8_WAIT_V(8); PG8_WAIT_L(0); PG8_BAR; PG8_MMA(0, 0, At, B0); PG8_MMA(0, 1, At, B1); PG8_BAR; PG8_SCHED;
;             PG8_LDA(At, 1, 1); PG8_STAGE(PG8_SB(1, 0), b3, voffB); PG8_STAGE(PG8_SB(1, 1), b3 + hstep, voffB); PG8_STAGE(PG8_SA(1, 0), a3, voffA);
;             PG8_WAIT_V(8); PG8_WAIT_L(0); PG8_BAR; PG8_MMA(1, 0, At, B0); PG8_MMA(1, 1, At, B1); PG8_BAR; PG8_SCHED;
	s_add_i32 s84, 0, 0x18000
	s_add_i32 vcc_hi, 0, 0x1c000
	v_add_u32_e32 v122, s84, v248
	v_add_u32_e32 v154, vcc_hi, v248
	ds_read_b128 v[98:101], v122
	ds_read_b128 v[102:105], v122 offset:1024
	ds_read_b128 v[114:117], v122 offset:2048
	ds_read_b128 v[122:125], v122 offset:3072
	ds_read_b128 v[130:133], v154
	ds_read_b128 v[138:141], v154 offset:1024
	ds_read_b128 v[146:149], v154 offset:2048
	ds_read_b128 v[154:157], v154 offset:3072
	s_add_u32 s4, s8, s100
	s_addc_u32 s5, s9, 0
	s_mov_b32 m0, s71
	ds_read_b128 v[162:165], v249 offset:32768
	ds_read_b128 v[166:169], v249 offset:33792
	ds_read_b128 v[170:173], v249 offset:34816
	ds_read_b128 v[174:177], v249 offset:35840
	ds_read_b128 v[178:181], v249 offset:36864
	ds_read_b128 v[182:185], v249 offset:37888
	ds_read_b128 v[186:189], v249 offset:38912
	ds_read_b128 v[190:193], v249 offset:39936
	global_load_lds_dwordx4 v194, s[4:5]
	s_mov_b32 m0, s12
	s_nop 0
	global_load_lds_dwordx4 v196, s[4:5]
	s_waitcnt vmcnt(8)
	s_waitcnt lgkmcnt(0)
	s_barrier
	s_waitcnt lgkmcnt(0)
	v_mfma_f32_16x16x32_bf16 v[158:161], v[98:101], v[162:165], v[158:161]
	v_mfma_f32_16x16x32_bf16 v[158:161], v[102:105], v[166:169], v[158:161]
	v_mfma_f32_16x16x32_bf16 v[150:153], v[114:117], v[162:165], v[150:153]
	v_mfma_f32_16x16x32_bf16 v[150:153], v[122:125], v[166:169], v[150:153]
	v_mfma_f32_16x16x32_bf16 v[118:121], v[114:117], v[170:173], v[118:121]
	v_mfma_f32_16x16x32_bf16 v[118:121], v[122:125], v[174:177], v[118:121]
	v_mfma_f32_16x16x32_bf16 v[126:129], v[98:101], v[170:173], v[126:129]
	v_mfma_f32_16x16x32_bf16 v[126:129], v[102:105], v[174:177], v[126:129]
	v_mfma_f32_16x16x32_bf16 v[94:97], v[98:101], v[178:181], v[94:97]
	v_mfma_f32_16x16x32_bf16 v[94:97], v[102:105], v[182:185], v[94:97]
	v_mfma_f32_16x16x32_bf16 v[90:93], v[114:117], v[178:181], v[90:93]
	v_mfma_f32_16x16x32_bf16 v[90:93], v[122:125], v[182:185], v[90:93]
	v_mfma_f32_16x16x32_bf16 v[74:77], v[114:117], v[186:189], v[74:77]
	v_mfma_f32_16x16x32_bf16 v[74:77], v[122:125], v[190:193], v[74:77]
	v_mfma_f32_16x16x32_bf16 v[78:81], v[98:101], v[186:189], v[78:81]
	v_mfma_f32_16x16x32_bf16 v[78:81], v[102:105], v[190:193], v[78:81]
	v_mfma_f32_16x16x32_bf16 v[142:145], v[130:133], v[162:165], v[142:145]
	v_mfma_f32_16x16x32_bf16 v[142:145], v[138:141], v[166:169], v[142:145]
	v_mfma_f32_16x16x32_bf16 v[134:137], v[146:149], v[162:165], v[134:137]
	v_mfma_f32_16x16x32_bf16 v[134:137], v[154:157], v[166:169], v[134:137]
	v_mfma_f32_16x16x32_bf16 v[106:109], v[146:149], v[170:173], v[106:109]
	v_mfma_f32_16x16x32_bf16 v[106:109], v[154:157], v[174:177], v[106:109]
	v_mfma_f32_16x16x32_bf16 v[110:113], v[130:133], v[170:173], v[110:113]
	v_mfma_f32_16x16x32_bf16 v[110:113], v[138:141], v[174:177], v[110:113]
	v_mfma_f32_16x16x32_bf16 v[86:89], v[130:133], v[178:181], v[86:89]
	v_mfma_f32_16x16x32_bf16 v[86:89], v[138:141], v[182:185], v[86:89]
	v_mfma_f32_16x16x32_bf16 v[82:85], v[146:149], v[178:181], v[82:85]
	v_mfma_f32_16x16x32_bf16 v[82:85], v[154:157], v[182:185], v[82:85]
	v_mfma_f32_16x16x32_bf16 v[66:69], v[146:149], v[186:189], v[66:69]
	v_mfma_f32_16x16x32_bf16 v[66:69], v[154:157], v[190:193], v[66:69]
	v_mfma_f32_16x16x32_bf16 v[70:73], v[130:133], v[186:189], v[70:73]
	v_mfma_f32_16x16x32_bf16 v[70:73], v[138:141], v[190:193], v[70:73]
	s_barrier
	s_add_u32 s4, s92, s98
	s_addc_u32 s5, s93, 0
	s_add_i32 m0, s84, s80
	ds_read_b128 v[162:165], v249 offset:49152
	ds_read_b128 v[166:169], v249 offset:50176
	ds_read_b128 v[170:173], v249 offset:51200
	ds_read_b128 v[174:177], v249 offset:52224
	ds_read_b128 v[178:181], v249 offset:53248
	ds_read_b128 v[182:185], v249 offset:54272
	ds_read_b128 v[186:189], v249 offset:55296
	ds_read_b128 v[190:193], v249 offset:56320
	global_load_lds_dwordx4 v0, s[4:5]
	s_add_i32 m0, s84, s80
	s_add_i32 m0, m0, 0x2000
	s_nop 0
	global_load_lds_dwordx4 v198, s[4:5]
	s_add_u32 s4, s4, s100
	s_addc_u32 s5, s5, 0
	s_add_i32 m0, vcc_hi, s80
	s_nop 0
	global_load_lds_dwordx4 v0, s[4:5]
	s_add_i32 m0, vcc_hi, s80
	s_add_i32 m0, m0, 0x2000
	s_nop 0
	global_load_lds_dwordx4 v198, s[4:5]
	s_add_u32 s4, s8, s98
	s_addc_u32 s5, s9, 0
	s_mov_b32 m0, s10
	s_nop 0
	global_load_lds_dwordx4 v194, s[4:5]
	s_mov_b32 m0, s11
	s_nop 0
	global_load_lds_dwordx4 v196, s[4:5]
	s_waitcnt vmcnt(8)
	s_waitcnt lgkmcnt(0)
	s_barrier
	s_waitcnt lgkmcnt(0)
	v_mfma_f32_16x16x32_bf16 v[62:65], v[98:101], v[162:165], v[62:65]
	v_mfma_f32_16x16x32_bf16 v[62:65], v[102:105], v[166:169], v[62:65]
	v_mfma_f32_16x16x32_bf16 v[58:61], v[114:117], v[162:165], v[58:61]
	v_mfma_f32_16x16x32_bf16 v[58:61], v[122:125], v[166:169], v[58:61]
	v_mfma_f32_16x16x32_bf16 v[42:45], v[114:117], v[170:173], v[42:45]
	v_mfma_f32_16x16x32_bf16 v[42:45], v[122:125], v[174:177], v[42:45]
	v_mfma_f32_16x16x32_bf16 v[46:49], v[98:101], v[170:173], v[46:49]
	v_mfma_f32_16x16x32_bf16 v[46:49], v[102:105], v[174:177], v[46:49]
	v_mfma_f32_16x16x32_bf16 v[30:33], v[98:101], v[178:181], v[30:33]
	v_mfma_f32_16x16x32_bf16 v[30:33], v[102:105], v[182:185], v[30:33]
	v_mfma_f32_16x16x32_bf16 v[26:29], v[114:117], v[178:181], v[26:29]
	v_mfma_f32_16x16x32_bf16 v[26:29], v[122:125], v[182:185], v[26:29]
	v_mfma_f32_16x16x32_bf16 v[10:13], v[114:117], v[186:189], v[10:13]
	v_mfma_f32_16x16x32_bf16 v[10:13], v[122:125], v[190:193], v[10:13]
	v_mfma_f32_16x16x32_bf16 v[14:17], v[98:101], v[186:189], v[14:17]
	v_mfma_f32_16x16x32_bf16 v[14:17], v[102:105], v[190:193], v[14:17]
	v_mfma_f32_16x16x32_bf16 v[54:57], v[130:133], v[162:165], v[54:57]
	v_mfma_f32_16x16x32_bf16 v[54:57], v[138:141], v[166:169], v[54:57]
	v_mfma_f32_16x16x32_bf16 v[50:53], v[146:149], v[162:165], v[50:53]
	v_mfma_f32_16x16x32_bf16 v[50:53], v[154:157], v[166:169], v[50:53]
	v_mfma_f32_16x16x32_bf16 v[34:37], v[146:149], v[170:173], v[34:37]
	v_mfma_f32_16x16x32_bf16 v[34:37], v[154:157], v[174:177], v[34:37]
	v_mfma_f32_16x16x32_bf16 v[38:41], v[130:133], v[170:173], v[38:41]
	v_mfma_f32_16x16x32_bf16 v[38:41], v[138:141], v[174:177], v[38:41]
	v_mfma_f32_16x16x32_bf16 v[22:25], v[130:133], v[178:181], v[22:25]
	v_mfma_f32_16x16x32_bf16 v[22:25], v[138:141], v[182:185], v[22:25]
	v_mfma_f32_16x16x32_bf16 v[18:21], v[146:149], v[178:181], v[18:21]
	v_mfma_f32_16x16x32_bf16 v[18:21], v[154:157], v[182:185], v[18:21]
	v_mfma_f32_16x16x32_bf16 v[2:5], v[146:149], v[186:189], v[2:5]
	v_mfma_f32_16x16x32_bf16 v[2:5], v[154:157], v[190:193], v[2:5]
	v_mfma_f32_16x16x32_bf16 v[6:9], v[130:133], v[186:189], v[6:9]
	v_mfma_f32_16x16x32_bf16 v[6:9], v[138:141], v[190:193], v[6:9]
	s_barrier
	s_add_u32 s6, s6, s98
	s_addc_u32 s7, s7, 0
	s_add_u32 s6, s6, s98
	s_addc_u32 s7, s7, 0
	s_add_u32 s67, s67, s98
	s_addc_u32 s85, s85, 0
	s_add_u32 s67, s67, s98
	s_addc_u32 s85, s85, 0
	s_cmp_ge_u32 vcc_lo, s69
	s_mov_b32 s8, vcc_lo
	s_cbranch_scc0 .LBB0_175

; #define PG8_STAGE(bufoff, gbase, voff) do { _Pragma("unroll") for (int _i = 0; _i < 2; ++_i) \
;         __builtin_amdgcn_global_load_lds((const unsigned*)((const char*)(gbase) + (voff)[_i]), (PG8_LAS unsigned*)(lds + (bufoff) + ldsw + _i * 8192), 16, 0, 0); } while (0)
; #define PG8_LDA(dst, b, h) do { _Pragma("unroll") for (int m = 0; m < 4; ++m) _Pragma("unroll") for (int k = 0; k < 2; ++k) dst[m][k] = *(const PG8_LAS bf16x8*)(lds + PG8_SA(b, h) + aoff + m * 2048 + k * 1024); } while (0)
; #define PG8_LDB(dst, b, h) do { _Pragma("unroll") for (int n = 0; n < 2; ++n) _Pragma("unroll") for (int k = 0; k < 2; ++k) dst[n][k] = *(const PG8_LAS bf16x8*)(lds + PG8_SB(b, h) + boff + n * 2048 + k * 1024); } while (0)
; #define PG8_MMA(ai, bj, At, Bt) do { __builtin_amdgcn_s_setprio(1); _Pragma("unroll") for (int m = 0; m < 4; ++m) _Pragma("unroll") for (int n = 0; n < 2; ++n) _Pragma("unroll") for (int k = 0; k < 2; ++k) \
;         acc[ai][bj][m][n] = mma16<Epi::I8>(Bt[n][k], At[m][k], acc[ai][bj][m][n]); __builtin_amdgcn_s_setprio(0); } while (0)
; #define PG8_WAIT_V(n) asm volatile("s_waitcnt vmcnt(" #n ")" ::: "memory")
; #define PG8_WAIT_L(n) asm volatile("s_waitcnt lgkmcnt(" #n ")" ::: "memory")
; #define PG8_BAR __builtin_amdgcn_s_barrier()
; template <class Epi, class Sched, bool ALIGN_EPI = false, bool SP2 = false>
; __device__ __forceinline__ void gemm_phase(PG8_LAS unsigned char* lds, const Gemm g, const Sched& S, const Epi& E) {
;     ...
;             const bool last = (t == nt - 2);
;             const char* a1 = cA + (size_t)(t + 1) * kstep;
;             const char* a2 = last ? nA : cA + (size_t)(t + 2) * kstep; const char* b2 = last ? nB : cB + (size_t)(t + 2) * kstep;
;             const char* a3 = a2 + kstep; const char* b3 = b2 + kstep;
;             if (last && has_next) S.a_ready(nxt);
;             if constexpr (SP2) {
;             PG8_LDB(B0, 0, 0); PG8_LDB(B1, 0, 1); PG8_SCHED; PG8_LDA(At, 0, 0); PG8_STAGE(PG8_SA(1, 1), a1 + hstep, voffA);
;             PG8_WAIT_V(8); PG8_WAIT_L(0); PG8_BAR; PG8_MMA(0, 0, At, B0); PG8_MMA(0, 1, At, B1); PG8_BAR; PG8_SCHED;
;             PG8_LDA(At, 0, 1); PG8_STAGE(PG8_SB(0, 0), b2, voffB); PG8_STAGE(PG8_SB(0, 1), b2 + hstep, voffB); PG8_STAGE(PG8_SA(0, 0), a2, voffA);
;             PG8_WAIT_V(8); PG8_WAIT_L(0); PG8_BAR; PG8_MMA(1, 0, At, B0); PG8_MMA(1, 1, At, B1); PG8_BAR; PG8_SCHED;
.Lpeel291:
	s_add_u32 s84, s8, 0x100
	s_addc_u32 s85, s9, 0
	s_add_i32 s66, 0, 0x10000
	s_cmp_eq_u32 s10, 12
	s_cselect_b32 vcc_hi, s5, s85
	s_cselect_b32 vcc_lo, s7, s84
	s_cselect_b32 s97, s11, s68
	s_cselect_b32 s96, s67, s69
	s_add_i32 s70, 0, 0x14000
	v_add_u32_e32 v110, s66, v175
	v_add_u32_e32 v168, s70, v175
	s_waitcnt vmcnt(0)
	ds_read_b128 v[66:69], v110
	ds_read_b128 v[70:73], v110 offset:1024
	ds_read_b128 v[106:109], v110 offset:2048
	ds_read_b128 v[110:113], v110 offset:3072
	ds_read_b128 v[114:117], v168
	ds_read_b128 v[118:121], v168 offset:1024
	ds_read_b128 v[126:129], v168 offset:2048
	ds_read_b128 v[178:181], v168 offset:3072
	s_add_i32 m0, s1, 0xc000
	ds_read_b128 v[182:185], v177
	ds_read_b128 v[186:189], v177 offset:1024
	ds_read_b128 v[190:193], v177 offset:2048
	ds_read_b128 v[194:197], v177 offset:3072
	ds_read_b128 v[198:201], v177 offset:4096
	ds_read_b128 v[210:213], v177 offset:5120
	ds_read_b128 v[214:217], v177 offset:6144
	ds_read_b128 v[218:221], v177 offset:7168
	global_load_lds_dwordx4 v164, s[8:9]
	s_add_i32 m0, s1, 0xe000
	s_nop 0
	global_load_lds_dwordx4 v166, s[8:9]
	s_waitcnt vmcnt(8)
	s_waitcnt lgkmcnt(0)
	s_barrier
	s_waitcnt lgkmcnt(0)
	v_mfma_i32_16x16x64_i8 v[154:157], v[66:69], v[182:185], 0
	v_mfma_i32_16x16x64_i8 v[154:157], v[70:73], v[186:189], v[154:157]
	v_mfma_i32_16x16x64_i8 v[146:149], v[106:109], v[182:185], 0
	v_mfma_i32_16x16x64_i8 v[146:149], v[110:113], v[186:189], v[146:149]
	v_mfma_i32_16x16x64_i8 v[138:141], v[106:109], v[190:193], 0
	v_mfma_i32_16x16x64_i8 v[138:141], v[110:113], v[194:197], v[138:141]
	v_mfma_i32_16x16x64_i8 v[150:153], v[66:69], v[190:193], 0
	v_mfma_i32_16x16x64_i8 v[150:153], v[70:73], v[194:197], v[150:153]
	v_mfma_i32_16x16x64_i8 v[142:145], v[66:69], v[198:201], 0
	v_mfma_i32_16x16x64_i8 v[142:145], v[70:73], v[210:213], v[142:145]
	v_mfma_i32_16x16x64_i8 v[130:133], v[106:109], v[198:201], 0
	v_mfma_i32_16x16x64_i8 v[130:133], v[110:113], v[210:213], v[130:133]
	v_mfma_i32_16x16x64_i8 v[122:125], v[106:109], v[214:217], 0
	v_mfma_i32_16x16x64_i8 v[122:125], v[110:113], v[218:221], v[122:125]
	v_mfma_i32_16x16x64_i8 v[134:137], v[66:69], v[214:217], 0
	v_mfma_i32_16x16x64_i8 v[134:137], v[70:73], v[218:221], v[134:137]
	v_mfma_i32_16x16x64_i8 v[102:105], v[114:117], v[182:185], 0
	v_mfma_i32_16x16x64_i8 v[102:105], v[118:121], v[186:189], v[102:105]
	v_mfma_i32_16x16x64_i8 v[94:97], v[126:129], v[182:185], 0
	v_mfma_i32_16x16x64_i8 v[94:97], v[178:181], v[186:189], v[94:97]
	v_mfma_i32_16x16x64_i8 v[86:89], v[126:129], v[190:193], 0
	v_mfma_i32_16x16x64_i8 v[86:89], v[178:181], v[194:197], v[86:89]
	v_mfma_i32_16x16x64_i8 v[98:101], v[114:117], v[190:193], 0
	v_mfma_i32_16x16x64_i8 v[98:101], v[118:121], v[194:197], v[98:101]
	v_mfma_i32_16x16x64_i8 v[90:93], v[114:117], v[198:201], 0
	v_mfma_i32_16x16x64_i8 v[90:93], v[118:121], v[210:213], v[90:93]
	v_mfma_i32_16x16x64_i8 v[78:81], v[126:129], v[198:201], 0
	v_mfma_i32_16x16x64_i8 v[78:81], v[178:181], v[210:213], v[78:81]
	v_mfma_i32_16x16x64_i8 v[74:77], v[126:129], v[214:217], 0
	v_mfma_i32_16x16x64_i8 v[74:77], v[178:181], v[218:221], v[74:77]
	v_mfma_i32_16x16x64_i8 v[82:85], v[114:117], v[214:217], 0
	v_mfma_i32_16x16x64_i8 v[82:85], v[118:121], v[218:221], v[82:85]
	s_barrier
	s_add_i32 s8, s66, s81
	s_mov_b32 m0, s8
	ds_read_b128 v[182:185], v177 offset:16384
	ds_read_b128 v[186:189], v177 offset:17408
	ds_read_b128 v[190:193], v177 offset:18432
	ds_read_b128 v[194:197], v177 offset:19456
	ds_read_b128 v[198:201], v177 offset:20480
	ds_read_b128 v[210:213], v177 offset:21504
	ds_read_b128 v[214:217], v177 offset:22528
	ds_read_b128 v[218:221], v177 offset:23552
	global_load_lds_dwordx4 v0, s[96:97]
	s_add_i32 m0, s8, 0x2000
	s_add_u32 s8, s96, 0x40000
	s_addc_u32 s9, s97, 0
	s_add_i32 s66, s70, s81
	global_load_lds_dwordx4 v158, s[96:97]
	s_mov_b32 m0, s66
	s_nop 0
	global_load_lds_dwordx4 v0, s[8:9]
	s_add_i32 m0, s66, 0x2000
	s_nop 0
	global_load_lds_dwordx4 v158, s[8:9]
	s_mov_b32 m0, s1
	s_nop 0
	global_load_lds_dwordx4 v162, vcc
	s_mov_b32 m0, s58
	s_nop 0
	global_load_lds_dwordx4 v160, vcc
	s_waitcnt vmcnt(8)
	s_waitcnt lgkmcnt(0)
	s_barrier
	s_waitcnt lgkmcnt(0)
	v_mfma_i32_16x16x64_i8 v[62:65], v[66:69], v[182:185], 0
	v_mfma_i32_16x16x64_i8 v[62:65], v[70:73], v[186:189], v[62:65]
	v_mfma_i32_16x16x64_i8 v[54:57], v[106:109], v[182:185], 0
	v_mfma_i32_16x16x64_i8 v[54:57], v[110:113], v[186:189], v[54:57]
	v_mfma_i32_16x16x64_i8 v[46:49], v[106:109], v[190:193], 0
	v_mfma_i32_16x16x64_i8 v[46:49], v[110:113], v[194:197], v[46:49]
	v_mfma_i32_16x16x64_i8 v[58:61], v[66:69], v[190:193], 0
	v_mfma_i32_16x16x64_i8 v[58:61], v[70:73], v[194:197], v[58:61]
	v_mfma_i32_16x16x64_i8 v[50:53], v[66:69], v[198:201], 0
	v_mfma_i32_16x16x64_i8 v[50:53], v[70:73], v[210:213], v[50:53]
	v_mfma_i32_16x16x64_i8 v[38:41], v[106:109], v[198:201], 0
	v_mfma_i32_16x16x64_i8 v[38:41], v[110:113], v[210:213], v[38:41]
	v_mfma_i32_16x16x64_i8 v[34:37], v[106:109], v[214:217], 0
	v_mfma_i32_16x16x64_i8 v[34:37], v[110:113], v[218:221], v[34:37]
	v_mfma_i32_16x16x64_i8 v[42:45], v[66:69], v[214:217], 0
	v_mfma_i32_16x16x64_i8 v[42:45], v[70:73], v[218:221], v[42:45]
	v_mfma_i32_16x16x64_i8 v[30:33], v[114:117], v[182:185], 0
	v_mfma_i32_16x16x64_i8 v[30:33], v[118:121], v[186:189], v[30:33]
	v_mfma_i32_16x16x64_i8 v[22:25], v[126:129], v[182:185], 0
	v_mfma_i32_16x16x64_i8 v[22:25], v[178:181], v[186:189], v[22:25]
	v_mfma_i32_16x16x64_i8 v[14:17], v[126:129], v[190:193], 0
	v_mfma_i32_16x16x64_i8 v[14:17], v[178:181], v[194:197], v[14:17]
	v_mfma_i32_16x16x64_i8 v[26:29], v[114:117], v[190:193], 0
	v_mfma_i32_16x16x64_i8 v[26:29], v[118:121], v[194:197], v[26:29]
	v_mfma_i32_16x16x64_i8 v[18:21], v[114:117], v[198:201], 0
	v_mfma_i32_16x16x64_i8 v[18:21], v[118:121], v[210:213], v[18:21]
	v_mfma_i32_16x16x64_i8 v[6:9], v[126:129], v[198:201], 0
	v_mfma_i32_16x16x64_i8 v[6:9], v[178:181], v[210:213], v[6:9]
	v_mfma_i32_16x16x64_i8 v[2:5], v[126:129], v[214:217], 0
	v_mfma_i32_16x16x64_i8 v[2:5], v[178:181], v[218:221], v[2:5]
	v_mfma_i32_16x16x64_i8 v[10:13], v[114:117], v[214:217], 0
	v_mfma_i32_16x16x64_i8 v[10:13], v[118:121], v[218:221], v[10:13]
	s_barrier
; #define PG8_STAGE(bufoff, gbase, voff) do { _Pragma("unroll") for (int _i = 0; _i < 2; ++_i) \
;         __builtin_amdgcn_global_load_lds((const unsigned*)((const char*)(gbase) + (voff)[_i]), (PG8_LAS unsigned*)(lds + (bufoff) + ldsw + _i * 8192), 16, 0, 0); } while (0)
; #define PG8_LDA(dst, b, h) do { _Pragma("unroll") for (int m = 0; m < 4; ++m) _Pragma("unroll") for (int k = 0; k < 2; ++k) dst[m][k] = *(const PG8_LAS bf16x8*)(lds + PG8_SA(b, h) + aoff + m * 2048 + k * 1024); } while (0)
; #define PG8_LDB(dst, b, h) do { _Pragma("unroll") for (int n = 0; n < 2; ++n) _Pragma("unroll") for (int k = 0; k < 2; ++k) dst[n][k] = *(const PG8_LAS bf16x8*)(lds + PG8_SB(b, h) + boff + n * 2048 + k * 1024); } while (0)
; #define PG8_MMA(ai, bj, At, Bt) do { __builtin_amdgcn_s_setprio(1); _Pragma("unroll") for (int m = 0; m < 4; ++m) _Pragma("unroll") for (int n = 0; n < 2; ++n) _Pragma("unroll") for (int k = 0; k < 2; ++k) \
;         acc[ai][bj][m][n] = mma16<Epi::I8>(Bt[n][k], At[m][k], acc[ai][bj][m][n]); __builtin_amdgcn_s_setprio(0); } while (0)
; #define PG8_WAIT_V(n) asm volatile("s_waitcnt vmcnt(" #n ")" ::: "memory")
; #define PG8_WAIT_L(n) asm volatile("s_waitcnt lgkmcnt(" #n ")" ::: "memory")
; #define PG8_BAR __builtin_amdgcn_s_barrier()
; #define PG8_SCHED __builtin_amdgcn_sched_barrier(0)
; template <class Epi, class Sched, bool ALIGN_EPI = false, bool SP2 = false>
; __device__ __forceinline__ void gemm_phase(PG8_LAS unsigned char* lds, const Gemm g, const Sched& S, const Epi& E) {
;     ...
;             PG8_LDB(B0, 1, 0); PG8_LDB(B1, 1, 1); PG8_SCHED; PG8_LDA(At, 1, 0); PG8_STAGE(PG8_SA(0, 1), a2 + hstep, voffA);
;             PG8_WAIT_V(8); PG8_WAIT_L(0); PG8_BAR; PG8_MMA(0, 0, At, B0); PG8_MMA(0, 1, At, B1); PG8_BAR; PG8_SCHED;
;             PG8_LDA(At, 1, 1); PG8_STAGE(PG8_SB(1, 0), b3, voffB); PG8_STAGE(PG8_SB(1, 1), b3 + hstep, voffB); PG8_STAGE(PG8_SA(1, 0), a3, voffA);
;             PG8_WAIT_V(8); PG8_WAIT_L(0); PG8_BAR; PG8_MMA(1, 0, At, B0); PG8_MMA(1, 1, At, B1); PG8_BAR; PG8_SCHED;
	s_add_i32 s66, 0, 0x18000
	s_add_i32 s70, 0, 0x1c000
	v_add_u32_e32 v110, s66, v175
	v_add_u32_e32 v170, s70, v175
	ds_read_b128 v[66:69], v110
	ds_read_b128 v[70:73], v110 offset:1024
	ds_read_b128 v[106:109], v110 offset:2048
	ds_read_b128 v[110:113], v110 offset:3072
	ds_read_b128 v[114:117], v170
	ds_read_b128 v[118:121], v170 offset:1024
	ds_read_b128 v[126:129], v170 offset:2048
	ds_read_b128 v[178:181], v170 offset:3072
	s_add_u32 s8, vcc_lo, 0x40000
	s_addc_u32 s9, vcc_hi, 0
	s_mov_b32 m0, s80
	ds_read_b128 v[182:185], v177 offset:32768
	ds_read_b128 v[186:189], v177 offset:33792
	ds_read_b128 v[190:193], v177 offset:34816
	ds_read_b128 v[194:197], v177 offset:35840
	ds_read_b128 v[198:201], v177 offset:36864
	ds_read_b128 v[210:213], v177 offset:37888
	ds_read_b128 v[214:217], v177 offset:38912
	ds_read_b128 v[218:221], v177 offset:39936
	global_load_lds_dwordx4 v162, s[8:9]
	s_mov_b32 m0, s0
	s_nop 0
	global_load_lds_dwordx4 v160, s[8:9]
	s_waitcnt vmcnt(8)
	s_waitcnt lgkmcnt(0)
	s_barrier
	s_waitcnt lgkmcnt(0)
	v_mfma_i32_16x16x64_i8 v[154:157], v[66:69], v[182:185], v[154:157]
	v_mfma_i32_16x16x64_i8 v[154:157], v[70:73], v[186:189], v[154:157]
	v_mfma_i32_16x16x64_i8 v[146:149], v[106:109], v[182:185], v[146:149]
	v_mfma_i32_16x16x64_i8 v[146:149], v[110:113], v[186:189], v[146:149]
	v_mfma_i32_16x16x64_i8 v[138:141], v[106:109], v[190:193], v[138:141]
	v_mfma_i32_16x16x64_i8 v[138:141], v[110:113], v[194:197], v[138:141]
	v_mfma_i32_16x16x64_i8 v[150:153], v[66:69], v[190:193], v[150:153]
	v_mfma_i32_16x16x64_i8 v[150:153], v[70:73], v[194:197], v[150:153]
	v_mfma_i32_16x16x64_i8 v[142:145], v[66:69], v[198:201], v[142:145]
	v_mfma_i32_16x16x64_i8 v[142:145], v[70:73], v[210:213], v[142:145]
	v_mfma_i32_16x16x64_i8 v[130:133], v[106:109], v[198:201], v[130:133]
	v_mfma_i32_16x16x64_i8 v[130:133], v[110:113], v[210:213], v[130:133]
	v_mfma_i32_16x16x64_i8 v[122:125], v[106:109], v[214:217], v[122:125]
	v_mfma_i32_16x16x64_i8 v[122:125], v[110:113], v[218:221], v[122:125]
	v_mfma_i32_16x16x64_i8 v[134:137], v[66:69], v[214:217], v[134:137]
	v_mfma_i32_16x16x64_i8 v[134:137], v[70:73], v[218:221], v[134:137]
	v_mfma_i32_16x16x64_i8 v[102:105], v[114:117], v[182:185], v[102:105]
	v_mfma_i32_16x16x64_i8 v[102:105], v[118:121], v[186:189], v[102:105]
	v_mfma_i32_16x16x64_i8 v[94:97], v[126:129], v[182:185], v[94:97]
	v_mfma_i32_16x16x64_i8 v[94:97], v[178:181], v[186:189], v[94:97]
	v_mfma_i32_16x16x64_i8 v[86:89], v[126:129], v[190:193], v[86:89]
	v_mfma_i32_16x16x64_i8 v[86:89], v[178:181], v[194:197], v[86:89]
	v_mfma_i32_16x16x64_i8 v[98:101], v[114:117], v[190:193], v[98:101]
	v_mfma_i32_16x16x64_i8 v[98:101], v[118:121], v[194:197], v[98:101]
	v_mfma_i32_16x16x64_i8 v[90:93], v[114:117], v[198:201], v[90:93]
	v_mfma_i32_16x16x64_i8 v[90:93], v[118:121], v[210:213], v[90:93]
	v_mfma_i32_16x16x64_i8 v[78:81], v[126:129], v[198:201], v[78:81]
	v_mfma_i32_16x16x64_i8 v[78:81], v[178:181], v[210:213], v[78:81]
	v_mfma_i32_16x16x64_i8 v[74:77], v[126:129], v[214:217], v[74:77]
	v_mfma_i32_16x16x64_i8 v[74:77], v[178:181], v[218:221], v[74:77]
	v_mfma_i32_16x16x64_i8 v[82:85], v[114:117], v[214:217], v[82:85]
	v_mfma_i32_16x16x64_i8 v[82:85], v[118:121], v[218:221], v[82:85]
	s_barrier
	s_add_i32 s8, s66, s81
	s_add_u32 s98, s96, 0x80
	s_addc_u32 s99, s97, 0
	s_add_u32 s100, vcc_lo, 0x80
	s_addc_u32 s101, vcc_hi, 0
	s_mov_b32 m0, s8
	ds_read_b128 v[182:185], v177 offset:49152
	ds_read_b128 v[186:189], v177 offset:50176
	ds_read_b128 v[190:193], v177 offset:51200
	ds_read_b128 v[194:197], v177 offset:52224
	ds_read_b128 v[198:201], v177 offset:53248
	ds_read_b128 v[210:213], v177 offset:54272
	ds_read_b128 v[214:217], v177 offset:55296
	ds_read_b128 v[218:221], v177 offset:56320
	global_load_lds_dwordx4 v0, s[98:99]
	s_add_i32 m0, s8, 0x2000
	s_add_u32 s8, s96, 0x40080
	s_addc_u32 s9, s97, 0
	s_add_i32 s66, s70, s81
	global_load_lds_dwordx4 v158, s[98:99]
	s_mov_b32 m0, s66
	s_nop 0
	global_load_lds_dwordx4 v0, s[8:9]
	s_add_i32 m0, s66, 0x2000
	s_nop 0
	global_load_lds_dwordx4 v158, s[8:9]
	s_mov_b32 m0, s13
	s_nop 0
	global_load_lds_dwordx4 v162, s[100:101]
	s_mov_b32 m0, s12
	s_nop 0
	global_load_lds_dwordx4 v160, s[100:101]
	s_waitcnt vmcnt(8)
	s_waitcnt lgkmcnt(0)
	s_barrier
	s_waitcnt lgkmcnt(0)
	v_mfma_i32_16x16x64_i8 v[62:65], v[66:69], v[182:185], v[62:65]
	v_mfma_i32_16x16x64_i8 v[62:65], v[70:73], v[186:189], v[62:65]
	v_mfma_i32_16x16x64_i8 v[54:57], v[106:109], v[182:185], v[54:57]
	v_mfma_i32_16x16x64_i8 v[54:57], v[110:113], v[186:189], v[54:57]
	v_mfma_i32_16x16x64_i8 v[46:49], v[106:109], v[190:193], v[46:49]
	v_mfma_i32_16x16x64_i8 v[46:49], v[110:113], v[194:197], v[46:49]
	v_mfma_i32_16x16x64_i8 v[58:61], v[66:69], v[190:193], v[58:61]
	v_mfma_i32_16x16x64_i8 v[58:61], v[70:73], v[194:197], v[58:61]
	v_mfma_i32_16x16x64_i8 v[50:53], v[66:69], v[198:201], v[50:53]
	v_mfma_i32_16x16x64_i8 v[50:53], v[70:73], v[210:213], v[50:53]
	v_mfma_i32_16x16x64_i8 v[38:41], v[106:109], v[198:201], v[38:41]
	v_mfma_i32_16x16x64_i8 v[38:41], v[110:113], v[210:213], v[38:41]
	v_mfma_i32_16x16x64_i8 v[34:37], v[106:109], v[214:217], v[34:37]
	v_mfma_i32_16x16x64_i8 v[34:37], v[110:113], v[218:221], v[34:37]
	v_mfma_i32_16x16x64_i8 v[42:45], v[66:69], v[214:217], v[42:45]
	v_mfma_i32_16x16x64_i8 v[42:45], v[70:73], v[218:221], v[42:45]
	v_mfma_i32_16x16x64_i8 v[30:33], v[114:117], v[182:185], v[30:33]
	v_mfma_i32_16x16x64_i8 v[30:33], v[118:121], v[186:189], v[30:33]
	v_mfma_i32_16x16x64_i8 v[22:25], v[126:129], v[182:185], v[22:25]
	v_mfma_i32_16x16x64_i8 v[22:25], v[178:181], v[186:189], v[22:25]
	v_mfma_i32_16x16x64_i8 v[14:17], v[126:129], v[190:193], v[14:17]
	v_mfma_i32_16x16x64_i8 v[14:17], v[178:181], v[194:197], v[14:17]
	v_mfma_i32_16x16x64_i8 v[26:29], v[114:117], v[190:193], v[26:29]
	v_mfma_i32_16x16x64_i8 v[26:29], v[118:121], v[194:197], v[26:29]
	v_mfma_i32_16x16x64_i8 v[18:21], v[114:117], v[198:201], v[18:21]
	v_mfma_i32_16x16x64_i8 v[18:21], v[118:121], v[210:213], v[18:21]
	v_mfma_i32_16x16x64_i8 v[6:9], v[126:129], v[198:201], v[6:9]
	v_mfma_i32_16x16x64_i8 v[6:9], v[178:181], v[210:213], v[6:9]
	v_mfma_i32_16x16x64_i8 v[2:5], v[126:129], v[214:217], v[2:5]
	v_mfma_i32_16x16x64_i8 v[2:5], v[178:181], v[218:221], v[2:5]
	v_mfma_i32_16x16x64_i8 v[10:13], v[114:117], v[214:217], v[10:13]
	v_mfma_i32_16x16x64_i8 v[10:13], v[118:121], v[218:221], v[10:13]
	s_barrier
	s_add_i32 s10, s10, 2
	s_add_u32 s69, s69, 0x100
	s_addc_u32 s68, s68, 0
	s_cmp_gt_u32 s10, 13
	s_mov_b64 s[8:9], s[84:85]
	s_cbranch_scc0 .LBB0_291
	s_branch .Lpeelx291
; #define PG8_STAGE(bufoff, gbase, voff) do { _Pragma("unroll") for (int _i = 0; _i < 2; ++_i) \
;         __builtin_amdgcn_global_load_lds((const unsigned*)((const char*)(gbase) + (voff)[_i]), (PG8_LAS unsigned*)(lds + (bufoff) + ldsw + _i * 8192), 16, 0, 0); } while (0)
; #define PG8_LDA(dst, b, h) do { _Pragma("unroll") for (int m = 0; m < 4; ++m) _Pragma("unroll") for (int k = 0; k < 2; ++k) dst[m][k] = *(const PG8_LAS bf16x8*)(lds + PG8_SA(b, h) + aoff + m * 2048 + k * 1024); } while (0)
; #define PG8_LDB(dst, b, h) do { _Pragma("unroll") for (int n = 0; n < 2; ++n) _Pragma("unroll") for (int k = 0; k < 2; ++k) dst[n][k] = *(const PG8_LAS bf16x8*)(lds + PG8_SB(b, h) + boff + n * 2048 + k * 1024); } while (0)
; #define PG8_MMA(ai, bj, At, Bt) do { __builtin_amdgcn_s_setprio(1); _Pragma("unroll") for (int m = 0; m < 4; ++m) _Pragma("unroll") for (int n = 0; n < 2; ++n) _Pragma("unroll") for (int k = 0; k < 2; ++k) \
;         acc[ai][bj][m][n] = mma16<Epi::I8>(Bt[n][k], At[m][k], acc[ai][bj][m][n]); __builtin_amdgcn_s_setprio(0); } while (0)
; #define PG8_WAIT_V(n) asm volatile("s_waitcnt vmcnt(" #n ")" ::: "memory")
; #define PG8_WAIT_L(n) asm volatile("s_waitcnt lgkmcnt(" #n ")" ::: "memory")
; template <class Epi, class Sched, bool ALIGN_EPI = false, bool SP2 = false>
; __device__ __forceinline__ void gemm_phase(PG8_LAS unsigned char* lds, const Gemm g, const Sched& S, const Epi& E) {
;     ...
;         for (int t = 0; t < nt; t += 2) {
;             const bool last = (t == nt - 2);
;             const char* a1 = cA + (size_t)(t + 1) * kstep;
;             const char* a2 = last ? nA : cA + (size_t)(t + 2) * kstep; const char* b2 = last ? nB : cB + (size_t)(t + 2) * kstep;
;             const char* a3 = a2 + kstep; const char* b3 = b2 + kstep;
;             if (last && has_next) S.a_ready(nxt);
;             if constexpr (SP2) {
;             PG8_LDB(B0, 0, 0); PG8_LDB(B1, 0, 1); PG8_SCHED; PG8_LDA(At, 0, 0); PG8_STAGE(PG8_SA(1, 1), a1 + hstep, voffA);
;             PG8_WAIT_V(8); PG8_WAIT_L(0); PG8_BAR; PG8_MMA(0, 0, At, B0); PG8_MMA(0, 1, At, B1); PG8_BAR; PG8_SCHED;
;             PG8_LDA(At, 0, 1); PG8_STAGE(PG8_SB(0, 0), b2, voffB); PG8_STAGE(PG8_SB(0, 1), b2 + hstep, voffB); PG8_STAGE(PG8_SA(0, 0), a2, voffA);
;             PG8_WAIT_V(8); PG8_WAIT_L(0); PG8_BAR; PG8_MMA(1, 0, At, B0); PG8_MMA(1, 1, At, B1); PG8_BAR; PG8_SCHED;
.LBB0_291:
	s_add_u32 s84, s8, 0x100
	s_addc_u32 s85, s9, 0
	s_add_i32 s66, 0, 0x10000
	s_cmp_eq_u32 s10, 12
	s_cselect_b32 vcc_hi, s5, s85
	s_cselect_b32 vcc_lo, s7, s84
	s_cselect_b32 s97, s11, s68
	s_cselect_b32 s96, s67, s69
	s_add_i32 s70, 0, 0x14000
	v_add_u32_e32 v110, s66, v175
	v_add_u32_e32 v168, s70, v175
	s_waitcnt vmcnt(0)
	ds_read_b128 v[66:69], v110
	ds_read_b128 v[70:73], v110 offset:1024
	ds_read_b128 v[106:109], v110 offset:2048
	ds_read_b128 v[110:113], v110 offset:3072
	ds_read_b128 v[114:117], v168
	ds_read_b128 v[118:121], v168 offset:1024
	ds_read_b128 v[126:129], v168 offset:2048
	ds_read_b128 v[178:181], v168 offset:3072
	s_add_i32 m0, s1, 0xc000
	ds_read_b128 v[182:185], v177
	ds_read_b128 v[186:189], v177 offset:1024
	ds_read_b128 v[190:193], v177 offset:2048
	ds_read_b128 v[194:197], v177 offset:3072
	ds_read_b128 v[198:201], v177 offset:4096
	ds_read_b128 v[210:213], v177 offset:5120
	ds_read_b128 v[214:217], v177 offset:6144
	ds_read_b128 v[218:221], v177 offset:7168
	global_load_lds_dwordx4 v164, s[8:9]
	s_add_i32 m0, s1, 0xe000
	s_nop 0
	global_load_lds_dwordx4 v166, s[8:9]
	s_waitcnt vmcnt(8)
	s_waitcnt lgkmcnt(0)
	s_barrier
	s_waitcnt lgkmcnt(0)
	v_mfma_i32_16x16x64_i8 v[154:157], v[66:69], v[182:185], v[154:157]
	v_mfma_i32_16x16x64_i8 v[154:157], v[70:73], v[186:189], v[154:157]
	v_mfma_i32_16x16x64_i8 v[146:149], v[106:109], v[182:185], v[146:149]
	v_mfma_i32_16x16x64_i8 v[146:149], v[110:113], v[186:189], v[146:149]
	v_mfma_i32_16x16x64_i8 v[138:141], v[106:109], v[190:193], v[138:141]
	v_mfma_i32_16x16x64_i8 v[138:141], v[110:113], v[194:197], v[138:141]
	v_mfma_i32_16x16x64_i8 v[150:153], v[66:69], v[190:193], v[150:153]
	v_mfma_i32_16x16x64_i8 v[150:153], v[70:73], v[194:197], v[150:153]
	v_mfma_i32_16x16x64_i8 v[142:145], v[66:69], v[198:201], v[142:145]
	v_mfma_i32_16x16x64_i8 v[142:145], v[70:73], v[210:213], v[142:145]
	v_mfma_i32_16x16x64_i8 v[130:133], v[106:109], v[198:201], v[130:133]
	v_mfma_i32_16x16x64_i8 v[130:133], v[110:113], v[210:213], v[130:133]
	v_mfma_i32_16x16x64_i8 v[122:125], v[106:109], v[214:217], v[122:125]
	v_mfma_i32_16x16x64_i8 v[122:125], v[110:113], v[218:221], v[122:125]
	v_mfma_i32_16x16x64_i8 v[134:137], v[66:69], v[214:217], v[134:137]
	v_mfma_i32_16x16x64_i8 v[134:137], v[70:73], v[218:221], v[134:137]
	v_mfma_i32_16x16x64_i8 v[102:105], v[114:117], v[182:185], v[102:105]
	v_mfma_i32_16x16x64_i8 v[102:105], v[118:121], v[186:189], v[102:105]
	v_mfma_i32_16x16x64_i8 v[94:97], v[126:129], v[182:185], v[94:97]
	v_mfma_i32_16x16x64_i8 v[94:97], v[178:181], v[186:189], v[94:97]
	v_mfma_i32_16x16x64_i8 v[86:89], v[126:129], v[190:193], v[86:89]
	v_mfma_i32_16x16x64_i8 v[86:89], v[178:181], v[194:197], v[86:89]
	v_mfma_i32_16x16x64_i8 v[98:101], v[114:117], v[190:193], v[98:101]
	v_mfma_i32_16x16x64_i8 v[98:101], v[118:121], v[194:197], v[98:101]
	v_mfma_i32_16x16x64_i8 v[90:93], v[114:117], v[198:201], v[90:93]
	v_mfma_i32_16x16x64_i8 v[90:93], v[118:121], v[210:213], v[90:93]
	v_mfma_i32_16x16x64_i8 v[78:81], v[126:129], v[198:201], v[78:81]
	v_mfma_i32_16x16x64_i8 v[78:81], v[178:181], v[210:213], v[78:81]
	v_mfma_i32_16x16x64_i8 v[74:77], v[126:129], v[214:217], v[74:77]
	v_mfma_i32_16x16x64_i8 v[74:77], v[178:181], v[218:221], v[74:77]
	v_mfma_i32_16x16x64_i8 v[82:85], v[114:117], v[214:217], v[82:85]
	v_mfma_i32_16x16x64_i8 v[82:85], v[118:121], v[218:221], v[82:85]
	s_barrier
	s_add_i32 s8, s66, s81
	s_mov_b32 m0, s8
	ds_read_b128 v[182:185], v177 offset:16384
	ds_read_b128 v[186:189], v177 offset:17408
	ds_read_b128 v[190:193], v177 offset:18432
	ds_read_b128 v[194:197], v177 offset:19456
	ds_read_b128 v[198:201], v177 offset:20480
	ds_read_b128 v[210:213], v177 offset:21504
	ds_read_b128 v[214:217], v177 offset:22528
	ds_read_b128 v[218:221], v177 offset:23552
	global_load_lds_dwordx4 v0, s[96:97]
	s_add_i32 m0, s8, 0x2000
	s_add_u32 s8, s96, 0x40000
	s_addc_u32 s9, s97, 0
	s_add_i32 s66, s70, s81
	global_load_lds_dwordx4 v158, s[96:97]
	s_mov_b32 m0, s66
	s_nop 0
	global_load_lds_dwordx4 v0, s[8:9]
	s_add_i32 m0, s66, 0x2000
	s_nop 0
	global_load_lds_dwordx4 v158, s[8:9]
	s_mov_b32 m0, s1
	s_nop 0
	global_load_lds_dwordx4 v162, vcc
	s_mov_b32 m0, s58
	s_nop 0
	global_load_lds_dwordx4 v160, vcc
	s_waitcnt vmcnt(8)
	s_waitcnt lgkmcnt(0)
	s_barrier
	s_waitcnt lgkmcnt(0)
	v_mfma_i32_16x16x64_i8 v[62:65], v[66:69], v[182:185], v[62:65]
	v_mfma_i32_16x16x64_i8 v[62:65], v[70:73], v[186:189], v[62:65]
	v_mfma_i32_16x16x64_i8 v[54:57], v[106:109], v[182:185], v[54:57]
	v_mfma_i32_16x16x64_i8 v[54:57], v[110:113], v[186:189], v[54:57]
	v_mfma_i32_16x16x64_i8 v[46:49], v[106:109], v[190:193], v[46:49]
	v_mfma_i32_16x16x64_i8 v[46:49], v[110:113], v[194:197], v[46:49]
	v_mfma_i32_16x16x64_i8 v[58:61], v[66:69], v[190:193], v[58:61]
	v_mfma_i32_16x16x64_i8 v[58:61], v[70:73], v[194:197], v[58:61]
	v_mfma_i32_16x16x64_i8 v[50:53], v[66:69], v[198:201], v[50:53]
	v_mfma_i32_16x16x64_i8 v[50:53], v[70:73], v[210:213], v[50:53]
	v_mfma_i32_16x16x64_i8 v[38:41], v[106:109], v[198:201], v[38:41]
	v_mfma_i32_16x16x64_i8 v[38:41], v[110:113], v[210:213], v[38:41]
	v_mfma_i32_16x16x64_i8 v[34:37], v[106:109], v[214:217], v[34:37]
	v_mfma_i32_16x16x64_i8 v[34:37], v[110:113], v[218:221], v[34:37]
	v_mfma_i32_16x16x64_i8 v[42:45], v[66:69], v[214:217], v[42:45]
	v_mfma_i32_16x16x64_i8 v[42:45], v[70:73], v[218:221], v[42:45]
	v_mfma_i32_16x16x64_i8 v[30:33], v[114:117], v[182:185], v[30:33]
	v_mfma_i32_16x16x64_i8 v[30:33], v[118:121], v[186:189], v[30:33]
	v_mfma_i32_16x16x64_i8 v[22:25], v[126:129], v[182:185], v[22:25]
	v_mfma_i32_16x16x64_i8 v[22:25], v[178:181], v[186:189], v[22:25]
	v_mfma_i32_16x16x64_i8 v[14:17], v[126:129], v[190:193], v[14:17]
	v_mfma_i32_16x16x64_i8 v[14:17], v[178:181], v[194:197], v[14:17]
	v_mfma_i32_16x16x64_i8 v[26:29], v[114:117], v[190:193], v[26:29]
	v_mfma_i32_16x16x64_i8 v[26:29], v[118:121], v[194:197], v[26:29]
	v_mfma_i32_16x16x64_i8 v[18:21], v[114:117], v[198:201], v[18:21]
	v_mfma_i32_16x16x64_i8 v[18:21], v[118:121], v[210:213], v[18:21]
	v_mfma_i32_16x16x64_i8 v[6:9], v[126:129], v[198:201], v[6:9]
	v_mfma_i32_16x16x64_i8 v[6:9], v[178:181], v[210:213], v[6:9]
	v_mfma_i32_16x16x64_i8 v[2:5], v[126:129], v[214:217], v[2:5]
	v_mfma_i32_16x16x64_i8 v[2:5], v[178:181], v[218:221], v[2:5]
	v_mfma_i32_16x16x64_i8 v[10:13], v[114:117], v[214:217], v[10:13]
	v_mfma_i32_16x16x64_i8 v[10:13], v[118:121], v[218:221], v[10:13]
	s_barrier
; #define PG8_STAGE(bufoff, gbase, voff) do { _Pragma("unroll") for (int _i = 0; _i < 2; ++_i) \
;         __builtin_amdgcn_global_load_lds((const unsigned*)((const char*)(gbase) + (voff)[_i]), (PG8_LAS unsigned*)(lds + (bufoff) + ldsw + _i * 8192), 16, 0, 0); } while (0)
; #define PG8_LDA(dst, b, h) do { _Pragma("unroll") for (int m = 0; m < 4; ++m) _Pragma("unroll") for (int k = 0; k < 2; ++k) dst[m][k] = *(const PG8_LAS bf16x8*)(lds + PG8_SA(b, h) + aoff + m * 2048 + k * 1024); } while (0)
; #define PG8_LDB(dst, b, h) do { _Pragma("unroll") for (int n = 0; n < 2; ++n) _Pragma("unroll") for (int k = 0; k < 2; ++k) dst[n][k] = *(const PG8_LAS bf16x8*)(lds + PG8_SB(b, h) + boff + n * 2048 + k * 1024); } while (0)
; #define PG8_MMA(ai, bj, At, Bt) do { __builtin_amdgcn_s_setprio(1); _Pragma("unroll") for (int m = 0; m < 4; ++m) _Pragma("unroll") for (int n = 0; n < 2; ++n) _Pragma("unroll") for (int k = 0; k < 2; ++k) \
;         acc[ai][bj][m][n] = mma16<Epi::I8>(Bt[n][k], At[m][k], acc[ai][bj][m][n]); __builtin_amdgcn_s_setprio(0); } while (0)
; #define PG8_WAIT_V(n) asm volatile("s_waitcnt vmcnt(" #n ")" ::: "memory")
; #define PG8_WAIT_L(n) asm volatile("s_waitcnt lgkmcnt(" #n ")" ::: "memory")
; #define PG8_BAR __builtin_amdgcn_s_barrier()
; template <class Epi, class Sched, bool ALIGN_EPI = false, bool SP2 = false>
; __device__ __forceinline__ void gemm_phase(PG8_LAS unsigned char* lds, const Gemm g, const Sched& S, const Epi& E) {
;     ...
;         for (int t = 0; t < nt; t += 2) {
;             const bool last = (t == nt - 2);
;             const char* a1 = cA + (size_t)(t + 1) * kstep;
;             const char* a2 = last ? nA : cA + (size_t)(t + 2) * kstep; const char* b2 = last ? nB : cB + (size_t)(t + 2) * kstep;
;             const char* a3 = a2 + kstep; const char* b3 = b2 + kstep;
;             if (last && has_next) S.a_ready(nxt);
;     ...
;             PG8_LDB(B0, 1, 0); PG8_LDB(B1, 1, 1); PG8_SCHED; PG8_LDA(At, 1, 0); PG8_STAGE(PG8_SA(0, 1), a2 + hstep, voffA);
;             PG8_WAIT_V(8); PG8_WAIT_L(0); PG8_BAR; PG8_MMA(0, 0, At, B0); PG8_MMA(0, 1, At, B1); PG8_BAR; PG8_SCHED;
;             PG8_LDA(At, 1, 1); PG8_STAGE(PG8_SB(1, 0), b3, voffB); PG8_STAGE(PG8_SB(1, 1), b3 + hstep, voffB); PG8_STAGE(PG8_SA(1, 0), a3, voffA);
;             PG8_WAIT_V(8); PG8_WAIT_L(0); PG8_BAR; PG8_MMA(1, 0, At, B0); PG8_MMA(1, 1, At, B1); PG8_BAR; PG8_SCHED;
	s_add_i32 s66, 0, 0x18000
	s_add_i32 s70, 0, 0x1c000
	v_add_u32_e32 v110, s66, v175
	v_add_u32_e32 v170, s70, v175
	ds_read_b128 v[66:69], v110
	ds_read_b128 v[70:73], v110 offset:1024
	ds_read_b128 v[106:109], v110 offset:2048
	ds_read_b128 v[110:113], v110 offset:3072
	ds_read_b128 v[114:117], v170
	ds_read_b128 v[118:121], v170 offset:1024
	ds_read_b128 v[126:129], v170 offset:2048
	ds_read_b128 v[178:181], v170 offset:3072
	s_add_u32 s8, vcc_lo, 0x40000
	s_addc_u32 s9, vcc_hi, 0
	s_mov_b32 m0, s80
	ds_read_b128 v[182:185], v177 offset:32768
	ds_read_b128 v[186:189], v177 offset:33792
	ds_read_b128 v[190:193], v177 offset:34816
	ds_read_b128 v[194:197], v177 offset:35840
	ds_read_b128 v[198:201], v177 offset:36864
	ds_read_b128 v[210:213], v177 offset:37888
	ds_read_b128 v[214:217], v177 offset:38912
	ds_read_b128 v[218:221], v177 offset:39936
	global_load_lds_dwordx4 v162, s[8:9]
	s_mov_b32 m0, s0
	s_nop 0
	global_load_lds_dwordx4 v160, s[8:9]
	s_waitcnt vmcnt(8)
	s_waitcnt lgkmcnt(0)
	s_barrier
	s_waitcnt lgkmcnt(0)
	v_mfma_i32_16x16x64_i8 v[154:157], v[66:69], v[182:185], v[154:157]
	v_mfma_i32_16x16x64_i8 v[154:157], v[70:73], v[186:189], v[154:157]
	v_mfma_i32_16x16x64_i8 v[146:149], v[106:109], v[182:185], v[146:149]
	v_mfma_i32_16x16x64_i8 v[146:149], v[110:113], v[186:189], v[146:149]
	v_mfma_i32_16x16x64_i8 v[138:141], v[106:109], v[190:193], v[138:141]
	v_mfma_i32_16x16x64_i8 v[138:141], v[110:113], v[194:197], v[138:141]
	v_mfma_i32_16x16x64_i8 v[150:153], v[66:69], v[190:193], v[150:153]
	v_mfma_i32_16x16x64_i8 v[150:153], v[70:73], v[194:197], v[150:153]
	v_mfma_i32_16x16x64_i8 v[142:145], v[66:69], v[198:201], v[142:145]
	v_mfma_i32_16x16x64_i8 v[142:145], v[70:73], v[210:213], v[142:145]
	v_mfma_i32_16x16x64_i8 v[130:133], v[106:109], v[198:201], v[130:133]
	v_mfma_i32_16x16x64_i8 v[130:133], v[110:113], v[210:213], v[130:133]
	v_mfma_i32_16x16x64_i8 v[122:125], v[106:109], v[214:217], v[122:125]
	v_mfma_i32_16x16x64_i8 v[122:125], v[110:113], v[218:221], v[122:125]
	v_mfma_i32_16x16x64_i8 v[134:137], v[66:69], v[214:217], v[134:137]
	v_mfma_i32_16x16x64_i8 v[134:137], v[70:73], v[218:221], v[134:137]
	v_mfma_i32_16x16x64_i8 v[102:105], v[114:117], v[182:185], v[102:105]
	v_mfma_i32_16x16x64_i8 v[102:105], v[118:121], v[186:189], v[102:105]
	v_mfma_i32_16x16x64_i8 v[94:97], v[126:129], v[182:185], v[94:97]
	v_mfma_i32_16x16x64_i8 v[94:97], v[178:181], v[186:189], v[94:97]
	v_mfma_i32_16x16x64_i8 v[86:89], v[126:129], v[190:193], v[86:89]
	v_mfma_i32_16x16x64_i8 v[86:89], v[178:181], v[194:197], v[86:89]
	v_mfma_i32_16x16x64_i8 v[98:101], v[114:117], v[190:193], v[98:101]
	v_mfma_i32_16x16x64_i8 v[98:101], v[118:121], v[194:197], v[98:101]
	v_mfma_i32_16x16x64_i8 v[90:93], v[114:117], v[198:201], v[90:93]
	v_mfma_i32_16x16x64_i8 v[90:93], v[118:121], v[210:213], v[90:93]
	v_mfma_i32_16x16x64_i8 v[78:81], v[126:129], v[198:201], v[78:81]
	v_mfma_i32_16x16x64_i8 v[78:81], v[178:181], v[210:213], v[78:81]
	v_mfma_i32_16x16x64_i8 v[74:77], v[126:129], v[214:217], v[74:77]
	v_mfma_i32_16x16x64_i8 v[74:77], v[178:181], v[218:221], v[74:77]
	v_mfma_i32_16x16x64_i8 v[82:85], v[114:117], v[214:217], v[82:85]
	v_mfma_i32_16x16x64_i8 v[82:85], v[118:121], v[218:221], v[82:85]
	s_barrier
	s_add_i32 s8, s66, s81
	s_add_u32 s98, s96, 0x80
	s_addc_u32 s99, s97, 0
	s_add_u32 s100, vcc_lo, 0x80
	s_addc_u32 s101, vcc_hi, 0
	s_mov_b32 m0, s8
	ds_read_b128 v[182:185], v177 offset:49152
	ds_read_b128 v[186:189], v177 offset:50176
	ds_read_b128 v[190:193], v177 offset:51200
	ds_read_b128 v[194:197], v177 offset:52224
	ds_read_b128 v[198:201], v177 offset:53248
	ds_read_b128 v[210:213], v177 offset:54272
	ds_read_b128 v[214:217], v177 offset:55296
	ds_read_b128 v[218:221], v177 offset:56320
	global_load_lds_dwordx4 v0, s[98:99]
	s_add_i32 m0, s8, 0x2000
	s_add_u32 s8, s96, 0x40080
	s_addc_u32 s9, s97, 0
	s_add_i32 s66, s70, s81
	global_load_lds_dwordx4 v158, s[98:99]
	s_mov_b32 m0, s66
	s_nop 0
	global_load_lds_dwordx4 v0, s[8:9]
	s_add_i32 m0, s66, 0x2000
	s_nop 0
	global_load_lds_dwordx4 v158, s[8:9]
	s_mov_b32 m0, s13
	s_nop 0
	global_load_lds_dwordx4 v162, s[100:101]
	s_mov_b32 m0, s12
	s_nop 0
	global_load_lds_dwordx4 v160, s[100:101]
	s_waitcnt vmcnt(8)
	s_waitcnt lgkmcnt(0)
	s_barrier
	s_waitcnt lgkmcnt(0)
	v_mfma_i32_16x16x64_i8 v[62:65], v[66:69], v[182:185], v[62:65]
	v_mfma_i32_16x16x64_i8 v[62:65], v[70:73], v[186:189], v[62:65]
	v_mfma_i32_16x16x64_i8 v[54:57], v[106:109], v[182:185], v[54:57]
	v_mfma_i32_16x16x64_i8 v[54:57], v[110:113], v[186:189], v[54:57]
	v_mfma_i32_16x16x64_i8 v[46:49], v[106:109], v[190:193], v[46:49]
	v_mfma_i32_16x16x64_i8 v[46:49], v[110:113], v[194:197], v[46:49]
	v_mfma_i32_16x16x64_i8 v[58:61], v[66:69], v[190:193], v[58:61]
	v_mfma_i32_16x16x64_i8 v[58:61], v[70:73], v[194:197], v[58:61]
	v_mfma_i32_16x16x64_i8 v[50:53], v[66:69], v[198:201], v[50:53]
	v_mfma_i32_16x16x64_i8 v[50:53], v[70:73], v[210:213], v[50:53]
	v_mfma_i32_16x16x64_i8 v[38:41], v[106:109], v[198:201], v[38:41]
	v_mfma_i32_16x16x64_i8 v[38:41], v[110:113], v[210:213], v[38:41]
	v_mfma_i32_16x16x64_i8 v[34:37], v[106:109], v[214:217], v[34:37]
	v_mfma_i32_16x16x64_i8 v[34:37], v[110:113], v[218:221], v[34:37]
	v_mfma_i32_16x16x64_i8 v[42:45], v[66:69], v[214:217], v[42:45]
	v_mfma_i32_16x16x64_i8 v[42:45], v[70:73], v[218:221], v[42:45]
	v_mfma_i32_16x16x64_i8 v[30:33], v[114:117], v[182:185], v[30:33]
	v_mfma_i32_16x16x64_i8 v[30:33], v[118:121], v[186:189], v[30:33]
	v_mfma_i32_16x16x64_i8 v[22:25], v[126:129], v[182:185], v[22:25]
	v_mfma_i32_16x16x64_i8 v[22:25], v[178:181], v[186:189], v[22:25]
	v_mfma_i32_16x16x64_i8 v[14:17], v[126:129], v[190:193], v[14:17]
	v_mfma_i32_16x16x64_i8 v[14:17], v[178:181], v[194:197], v[14:17]
	v_mfma_i32_16x16x64_i8 v[26:29], v[114:117], v[190:193], v[26:29]
	v_mfma_i32_16x16x64_i8 v[26:29], v[118:121], v[194:197], v[26:29]
	v_mfma_i32_16x16x64_i8 v[18:21], v[114:117], v[198:201], v[18:21]
	v_mfma_i32_16x16x64_i8 v[18:21], v[118:121], v[210:213], v[18:21]
	v_mfma_i32_16x16x64_i8 v[6:9], v[126:129], v[198:201], v[6:9]
	v_mfma_i32_16x16x64_i8 v[6:9], v[178:181], v[210:213], v[6:9]
	v_mfma_i32_16x16x64_i8 v[2:5], v[126:129], v[214:217], v[2:5]
	v_mfma_i32_16x16x64_i8 v[2:5], v[178:181], v[218:221], v[2:5]
	v_mfma_i32_16x16x64_i8 v[10:13], v[114:117], v[214:217], v[10:13]
	v_mfma_i32_16x16x64_i8 v[10:13], v[118:121], v[218:221], v[10:13]
	s_barrier
	s_add_i32 s10, s10, 2
	s_add_u32 s69, s69, 0x100
	s_addc_u32 s68, s68, 0
	s_cmp_gt_u32 s10, 13
	s_mov_b64 s[8:9], s[84:85]
	s_cbranch_scc0 .LBB0_291

; #define PG8_STAGE(bufoff, gbase, voff) do { _Pragma("unroll") for (int _i = 0; _i < 2; ++_i) \
;         __builtin_amdgcn_global_load_lds((const unsigned*)((const char*)(gbase) + (voff)[_i]), (PG8_LAS unsigned*)(lds + (bufoff) + ldsw + _i * 8192), 16, 0, 0); } while (0)
; #define PG8_LDA(dst, b, h) do { _Pragma("unroll") for (int m = 0; m < 4; ++m) _Pragma("unroll") for (int k = 0; k < 2; ++k) dst[m][k] = *(const PG8_LAS bf16x8*)(lds + PG8_SA(b, h) + aoff + m * 2048 + k * 1024); } while (0)
; #define PG8_LDB(dst, b, h) do { _Pragma("unroll") for (int n = 0; n < 2; ++n) _Pragma("unroll") for (int k = 0; k < 2; ++k) dst[n][k] = *(const PG8_LAS bf16x8*)(lds + PG8_SB(b, h) + boff + n * 2048 + k * 1024); } while (0)
; #define PG8_MMA(ai, bj, At, Bt) do { __builtin_amdgcn_s_setprio(1); _Pragma("unroll") for (int m = 0; m < 4; ++m) _Pragma("unroll") for (int n = 0; n < 2; ++n) _Pragma("unroll") for (int k = 0; k < 2; ++k) \
;         acc[ai][bj][m][n] = mma16<Epi::I8>(Bt[n][k], At[m][k], acc[ai][bj][m][n]); __builtin_amdgcn_s_setprio(0); } while (0)
; #define PG8_WAIT_V(n) asm volatile("s_waitcnt vmcnt(" #n ")" ::: "memory")
; #define PG8_WAIT_L(n) asm volatile("s_waitcnt lgkmcnt(" #n ")" ::: "memory")
; #define PG8_BAR __builtin_amdgcn_s_barrier()
; template <class Epi, class Sched, bool ALIGN_EPI = false, bool SP2 = false>
; __device__ __forceinline__ void gemm_phase(PG8_LAS unsigned char* lds, const Gemm g, const Sched& S, const Epi& E) {
;     ...
;             const bool last = (t == nt - 2);
;             const char* a1 = cA + (size_t)(t + 1) * kstep;
;             const char* a2 = last ? nA : cA + (size_t)(t + 2) * kstep; const char* b2 = last ? nB : cB + (size_t)(t + 2) * kstep;
;             const char* a3 = a2 + kstep; const char* b3 = b2 + kstep;
;             if (last && has_next) S.a_ready(nxt);
;             if constexpr (SP2) {
;             PG8_LDB(B0, 0, 0); PG8_LDB(B1, 0, 1); PG8_SCHED; PG8_LDA(At, 0, 0); PG8_STAGE(PG8_SA(1, 1), a1 + hstep, voffA);
;             PG8_WAIT_V(8); PG8_WAIT_L(0); PG8_BAR; PG8_MMA(0, 0, At, B0); PG8_MMA(0, 1, At, B1); PG8_BAR; PG8_SCHED;
;             PG8_LDA(At, 0, 1); PG8_STAGE(PG8_SB(0, 0), b2, voffB); PG8_STAGE(PG8_SB(0, 1), b2 + hstep, voffB); PG8_STAGE(PG8_SA(0, 0), a2, voffA);
;             PG8_WAIT_V(8); PG8_WAIT_L(0); PG8_BAR; PG8_MMA(1, 0, At, B0); PG8_MMA(1, 1, At, B1); PG8_BAR; PG8_SCHED;
.Lpeel327:
	s_add_u32 s68, s8, 0x100
	s_addc_u32 s69, s9, 0
	s_add_i32 s84, 0, 0x10000
	s_cmp_eq_u32 s4, 28
	s_cselect_b32 vcc_hi, s1, s69
	s_cselect_b32 vcc_lo, s5, s68
	v_add_u32_e32 v0, s84, v188
	s_cselect_b32 s71, s7, s96
	s_cselect_b32 s70, s85, s97
	s_add_i32 s10, 0, 0x14000
	ds_read_b128 v[52:55], v0
	ds_read_b128 v[56:59], v0 offset:1024
	ds_read_b128 v[76:79], v0 offset:2048
	ds_read_b128 v[80:83], v0 offset:3072
	v_add_u32_e32 v0, s10, v188
	ds_read_b128 v[116:119], v0
	ds_read_b128 v[120:123], v0 offset:1024
	ds_read_b128 v[168:171], v0 offset:2048
	ds_read_b128 v[172:175], v0 offset:3072
	s_add_i32 m0, s58, 0xc000
	ds_read_b128 v[176:179], v189
	ds_read_b128 v[180:183], v189 offset:1024
	ds_read_b128 v[190:193], v189 offset:2048
	ds_read_b128 v[194:197], v189 offset:3072
	ds_read_b128 v[198:201], v189 offset:4096
	ds_read_b128 v[210:213], v189 offset:5120
	ds_read_b128 v[214:217], v189 offset:6144
	ds_read_b128 v[218:221], v189 offset:7168
	global_load_lds_dwordx4 v164, s[8:9]
	s_add_i32 m0, s58, 0xe000
	s_nop 0
	global_load_lds_dwordx4 v166, s[8:9]
	s_waitcnt vmcnt(8)
	s_waitcnt lgkmcnt(0)
	s_barrier
	s_waitcnt lgkmcnt(0)
	v_mfma_f32_16x16x32_bf16 v[152:155], v[52:55], v[176:179], 0
	v_mfma_f32_16x16x32_bf16 v[152:155], v[56:59], v[180:183], v[152:155]
	v_mfma_f32_16x16x32_bf16 v[144:147], v[76:79], v[176:179], 0
	v_mfma_f32_16x16x32_bf16 v[144:147], v[80:83], v[180:183], v[144:147]
	v_mfma_f32_16x16x32_bf16 v[140:143], v[76:79], v[190:193], 0
	v_mfma_f32_16x16x32_bf16 v[140:143], v[80:83], v[194:197], v[140:143]
	v_mfma_f32_16x16x32_bf16 v[148:151], v[52:55], v[190:193], 0
	v_mfma_f32_16x16x32_bf16 v[148:151], v[56:59], v[194:197], v[148:151]
	v_mfma_f32_16x16x32_bf16 v[136:139], v[52:55], v[198:201], 0
	v_mfma_f32_16x16x32_bf16 v[136:139], v[56:59], v[210:213], v[136:139]
	v_mfma_f32_16x16x32_bf16 v[132:135], v[76:79], v[198:201], 0
	v_mfma_f32_16x16x32_bf16 v[132:135], v[80:83], v[210:213], v[132:135]
	v_mfma_f32_16x16x32_bf16 v[124:127], v[76:79], v[214:217], 0
	v_mfma_f32_16x16x32_bf16 v[124:127], v[80:83], v[218:221], v[124:127]
	v_mfma_f32_16x16x32_bf16 v[128:131], v[52:55], v[214:217], 0
	v_mfma_f32_16x16x32_bf16 v[128:131], v[56:59], v[218:221], v[128:131]
	v_mfma_f32_16x16x32_bf16 v[112:115], v[116:119], v[176:179], 0
	v_mfma_f32_16x16x32_bf16 v[112:115], v[120:123], v[180:183], v[112:115]
	v_mfma_f32_16x16x32_bf16 v[104:107], v[168:171], v[176:179], 0
	v_mfma_f32_16x16x32_bf16 v[104:107], v[172:175], v[180:183], v[104:107]
	v_mfma_f32_16x16x32_bf16 v[100:103], v[168:171], v[190:193], 0
	v_mfma_f32_16x16x32_bf16 v[100:103], v[172:175], v[194:197], v[100:103]
	v_mfma_f32_16x16x32_bf16 v[108:111], v[116:119], v[190:193], 0
	v_mfma_f32_16x16x32_bf16 v[108:111], v[120:123], v[194:197], v[108:111]
	v_mfma_f32_16x16x32_bf16 v[96:99], v[116:119], v[198:201], 0
	v_mfma_f32_16x16x32_bf16 v[96:99], v[120:123], v[210:213], v[96:99]
	v_mfma_f32_16x16x32_bf16 v[92:95], v[168:171], v[198:201], 0
	v_mfma_f32_16x16x32_bf16 v[92:95], v[172:175], v[210:213], v[92:95]
	v_mfma_f32_16x16x32_bf16 v[84:87], v[168:171], v[214:217], 0
	v_mfma_f32_16x16x32_bf16 v[84:87], v[172:175], v[218:221], v[84:87]
	v_mfma_f32_16x16x32_bf16 v[88:91], v[116:119], v[214:217], 0
	v_mfma_f32_16x16x32_bf16 v[88:91], v[120:123], v[218:221], v[88:91]
	s_barrier
	s_add_i32 s8, s84, s80
	s_mov_b32 m0, s8
	ds_read_b128 v[176:179], v189 offset:16384
	ds_read_b128 v[180:183], v189 offset:17408
	ds_read_b128 v[190:193], v189 offset:18432
	ds_read_b128 v[194:197], v189 offset:19456
	ds_read_b128 v[198:201], v189 offset:20480
	ds_read_b128 v[210:213], v189 offset:21504
	ds_read_b128 v[214:217], v189 offset:22528
	ds_read_b128 v[218:221], v189 offset:23552
	global_load_lds_dwordx4 v158, s[70:71]
	s_add_i32 m0, s8, 0x2000
	s_add_u32 s8, s70, 0x80000
	s_addc_u32 s9, s71, 0
	s_add_i32 s10, s10, s80
	global_load_lds_dwordx4 v162, s[70:71]
	s_mov_b32 m0, s10
	s_nop 0
	global_load_lds_dwordx4 v158, s[8:9]
	s_add_i32 m0, s10, 0x2000
	s_nop 0
	global_load_lds_dwordx4 v162, s[8:9]
	s_mov_b32 m0, s58
	s_nop 0
	global_load_lds_dwordx4 v156, vcc
	s_mov_b32 m0, s12
	s_nop 0
	global_load_lds_dwordx4 v160, vcc
	s_waitcnt vmcnt(8)
	s_waitcnt lgkmcnt(0)
	s_barrier
	s_waitcnt lgkmcnt(0)
	v_mfma_f32_16x16x32_bf16 v[72:75], v[52:55], v[176:179], 0
	v_mfma_f32_16x16x32_bf16 v[72:75], v[56:59], v[180:183], v[72:75]
	v_mfma_f32_16x16x32_bf16 v[64:67], v[76:79], v[176:179], 0
	v_mfma_f32_16x16x32_bf16 v[64:67], v[80:83], v[180:183], v[64:67]
	v_mfma_f32_16x16x32_bf16 v[60:63], v[76:79], v[190:193], 0
	v_mfma_f32_16x16x32_bf16 v[60:63], v[80:83], v[194:197], v[60:63]
	v_mfma_f32_16x16x32_bf16 v[68:71], v[52:55], v[190:193], 0
	v_mfma_f32_16x16x32_bf16 v[68:71], v[56:59], v[194:197], v[68:71]
	v_mfma_f32_16x16x32_bf16 v[48:51], v[52:55], v[198:201], 0
	v_mfma_f32_16x16x32_bf16 v[48:51], v[56:59], v[210:213], v[48:51]
	v_mfma_f32_16x16x32_bf16 v[44:47], v[76:79], v[198:201], 0
	v_mfma_f32_16x16x32_bf16 v[44:47], v[80:83], v[210:213], v[44:47]
	v_mfma_f32_16x16x32_bf16 v[36:39], v[76:79], v[214:217], 0
	v_mfma_f32_16x16x32_bf16 v[36:39], v[80:83], v[218:221], v[36:39]
	v_mfma_f32_16x16x32_bf16 v[40:43], v[52:55], v[214:217], 0
	v_mfma_f32_16x16x32_bf16 v[40:43], v[56:59], v[218:221], v[40:43]
	v_mfma_f32_16x16x32_bf16 v[32:35], v[116:119], v[176:179], 0
	v_mfma_f32_16x16x32_bf16 v[32:35], v[120:123], v[180:183], v[32:35]
	v_mfma_f32_16x16x32_bf16 v[24:27], v[168:171], v[176:179], 0
	v_mfma_f32_16x16x32_bf16 v[24:27], v[172:175], v[180:183], v[24:27]
	v_mfma_f32_16x16x32_bf16 v[20:23], v[168:171], v[190:193], 0
	v_mfma_f32_16x16x32_bf16 v[20:23], v[172:175], v[194:197], v[20:23]
	v_mfma_f32_16x16x32_bf16 v[28:31], v[116:119], v[190:193], 0
	v_mfma_f32_16x16x32_bf16 v[28:31], v[120:123], v[194:197], v[28:31]
	v_mfma_f32_16x16x32_bf16 v[16:19], v[116:119], v[198:201], 0
	v_mfma_f32_16x16x32_bf16 v[16:19], v[120:123], v[210:213], v[16:19]
	v_mfma_f32_16x16x32_bf16 v[12:15], v[168:171], v[198:201], 0
	v_mfma_f32_16x16x32_bf16 v[12:15], v[172:175], v[210:213], v[12:15]
	v_mfma_f32_16x16x32_bf16 v[2:5], v[168:171], v[214:217], 0
	v_mfma_f32_16x16x32_bf16 v[2:5], v[172:175], v[218:221], v[2:5]
	v_mfma_f32_16x16x32_bf16 v[8:11], v[116:119], v[214:217], 0
	v_mfma_f32_16x16x32_bf16 v[8:11], v[120:123], v[218:221], v[8:11]
	s_barrier
; #define PG8_STAGE(bufoff, gbase, voff) do { _Pragma("unroll") for (int _i = 0; _i < 2; ++_i) \
;         __builtin_amdgcn_global_load_lds((const unsigned*)((const char*)(gbase) + (voff)[_i]), (PG8_LAS unsigned*)(lds + (bufoff) + ldsw + _i * 8192), 16, 0, 0); } while (0)
; #define PG8_LDA(dst, b, h) do { _Pragma("unroll") for (int m = 0; m < 4; ++m) _Pragma("unroll") for (int k = 0; k < 2; ++k) dst[m][k] = *(const PG8_LAS bf16x8*)(lds + PG8_SA(b, h) + aoff + m * 2048 + k * 1024); } while (0)
; #define PG8_LDB(dst, b, h) do { _Pragma("unroll") for (int n = 0; n < 2; ++n) _Pragma("unroll") for (int k = 0; k < 2; ++k) dst[n][k] = *(const PG8_LAS bf16x8*)(lds + PG8_SB(b, h) + boff + n * 2048 + k * 1024); } while (0)
; #define PG8_MMA(ai, bj, At, Bt) do { __builtin_amdgcn_s_setprio(1); _Pragma("unroll") for (int m = 0; m < 4; ++m) _Pragma("unroll") for (int n = 0; n < 2; ++n) _Pragma("unroll") for (int k = 0; k < 2; ++k) \
;         acc[ai][bj][m][n] = mma16<Epi::I8>(Bt[n][k], At[m][k], acc[ai][bj][m][n]); __builtin_amdgcn_s_setprio(0); } while (0)
; #define PG8_WAIT_V(n) asm volatile("s_waitcnt vmcnt(" #n ")" ::: "memory")
; #define PG8_WAIT_L(n) asm volatile("s_waitcnt lgkmcnt(" #n ")" ::: "memory")
; #define PG8_BAR __builtin_amdgcn_s_barrier()
; #define PG8_SCHED __builtin_amdgcn_sched_barrier(0)
; template <class Epi, class Sched, bool ALIGN_EPI = false, bool SP2 = false>
; __device__ __forceinline__ void gemm_phase(PG8_LAS unsigned char* lds, const Gemm g, const Sched& S, const Epi& E) {
;     ...
;             PG8_LDB(B0, 1, 0); PG8_LDB(B1, 1, 1); PG8_SCHED; PG8_LDA(At, 1, 0); PG8_STAGE(PG8_SA(0, 1), a2 + hstep, voffA);
;             PG8_WAIT_V(8); PG8_WAIT_L(0); PG8_BAR; PG8_MMA(0, 0, At, B0); PG8_MMA(0, 1, At, B1); PG8_BAR; PG8_SCHED;
;             PG8_LDA(At, 1, 1); PG8_STAGE(PG8_SB(1, 0), b3, voffB); PG8_STAGE(PG8_SB(1, 1), b3 + hstep, voffB); PG8_STAGE(PG8_SA(1, 0), a3, voffA);
;             PG8_WAIT_V(8); PG8_WAIT_L(0); PG8_BAR; PG8_MMA(1, 0, At, B0); PG8_MMA(1, 1, At, B1); PG8_BAR; PG8_SCHED;
	s_add_i32 s10, 0, 0x18000
	v_add_u32_e32 v0, s10, v188
	s_add_i32 s11, 0, 0x1c000
	ds_read_b128 v[52:55], v0
	ds_read_b128 v[56:59], v0 offset:1024
	ds_read_b128 v[76:79], v0 offset:2048
	ds_read_b128 v[80:83], v0 offset:3072
	v_add_u32_e32 v0, s11, v188
	ds_read_b128 v[116:119], v0
	ds_read_b128 v[120:123], v0 offset:1024
	ds_read_b128 v[168:171], v0 offset:2048
	ds_read_b128 v[172:175], v0 offset:3072
	s_add_u32 s8, vcc_lo, 0x80000
	s_addc_u32 s9, vcc_hi, 0
	s_mov_b32 m0, s13
	ds_read_b128 v[176:179], v189 offset:32768
	ds_read_b128 v[180:183], v189 offset:33792
	ds_read_b128 v[190:193], v189 offset:34816
	ds_read_b128 v[194:197], v189 offset:35840
	ds_read_b128 v[198:201], v189 offset:36864
	ds_read_b128 v[210:213], v189 offset:37888
	ds_read_b128 v[214:217], v189 offset:38912
	ds_read_b128 v[218:221], v189 offset:39936
	global_load_lds_dwordx4 v156, s[8:9]
	s_mov_b32 m0, s66
	s_nop 0
	global_load_lds_dwordx4 v160, s[8:9]
	s_waitcnt vmcnt(8)
	s_waitcnt lgkmcnt(0)
	s_barrier
	s_waitcnt lgkmcnt(0)
	v_mfma_f32_16x16x32_bf16 v[152:155], v[52:55], v[176:179], v[152:155]
	v_mfma_f32_16x16x32_bf16 v[152:155], v[56:59], v[180:183], v[152:155]
	v_mfma_f32_16x16x32_bf16 v[144:147], v[76:79], v[176:179], v[144:147]
	v_mfma_f32_16x16x32_bf16 v[144:147], v[80:83], v[180:183], v[144:147]
	v_mfma_f32_16x16x32_bf16 v[140:143], v[76:79], v[190:193], v[140:143]
	v_mfma_f32_16x16x32_bf16 v[140:143], v[80:83], v[194:197], v[140:143]
	v_mfma_f32_16x16x32_bf16 v[148:151], v[52:55], v[190:193], v[148:151]
	v_mfma_f32_16x16x32_bf16 v[148:151], v[56:59], v[194:197], v[148:151]
	v_mfma_f32_16x16x32_bf16 v[136:139], v[52:55], v[198:201], v[136:139]
	v_mfma_f32_16x16x32_bf16 v[136:139], v[56:59], v[210:213], v[136:139]
	v_mfma_f32_16x16x32_bf16 v[132:135], v[76:79], v[198:201], v[132:135]
	v_mfma_f32_16x16x32_bf16 v[132:135], v[80:83], v[210:213], v[132:135]
	v_mfma_f32_16x16x32_bf16 v[124:127], v[76:79], v[214:217], v[124:127]
	v_mfma_f32_16x16x32_bf16 v[124:127], v[80:83], v[218:221], v[124:127]
	v_mfma_f32_16x16x32_bf16 v[128:131], v[52:55], v[214:217], v[128:131]
	v_mfma_f32_16x16x32_bf16 v[128:131], v[56:59], v[218:221], v[128:131]
	v_mfma_f32_16x16x32_bf16 v[112:115], v[116:119], v[176:179], v[112:115]
	v_mfma_f32_16x16x32_bf16 v[112:115], v[120:123], v[180:183], v[112:115]
	v_mfma_f32_16x16x32_bf16 v[104:107], v[168:171], v[176:179], v[104:107]
	v_mfma_f32_16x16x32_bf16 v[104:107], v[172:175], v[180:183], v[104:107]
	v_mfma_f32_16x16x32_bf16 v[100:103], v[168:171], v[190:193], v[100:103]
	v_mfma_f32_16x16x32_bf16 v[100:103], v[172:175], v[194:197], v[100:103]
	v_mfma_f32_16x16x32_bf16 v[108:111], v[116:119], v[190:193], v[108:111]
	v_mfma_f32_16x16x32_bf16 v[108:111], v[120:123], v[194:197], v[108:111]
	v_mfma_f32_16x16x32_bf16 v[96:99], v[116:119], v[198:201], v[96:99]
	v_mfma_f32_16x16x32_bf16 v[96:99], v[120:123], v[210:213], v[96:99]
	v_mfma_f32_16x16x32_bf16 v[92:95], v[168:171], v[198:201], v[92:95]
	v_mfma_f32_16x16x32_bf16 v[92:95], v[172:175], v[210:213], v[92:95]
	v_mfma_f32_16x16x32_bf16 v[84:87], v[168:171], v[214:217], v[84:87]
	v_mfma_f32_16x16x32_bf16 v[84:87], v[172:175], v[218:221], v[84:87]
	v_mfma_f32_16x16x32_bf16 v[88:91], v[116:119], v[214:217], v[88:91]
	v_mfma_f32_16x16x32_bf16 v[88:91], v[120:123], v[218:221], v[88:91]
	s_barrier
	s_add_i32 s8, s10, s80
	s_add_u32 s98, s70, 0x80
	s_addc_u32 s99, s71, 0
	s_add_u32 s100, vcc_lo, 0x80
	s_addc_u32 s101, vcc_hi, 0
	s_mov_b32 m0, s8
	ds_read_b128 v[176:179], v189 offset:49152
	ds_read_b128 v[180:183], v189 offset:50176
	ds_read_b128 v[190:193], v189 offset:51200
	ds_read_b128 v[194:197], v189 offset:52224
	ds_read_b128 v[198:201], v189 offset:53248
	ds_read_b128 v[210:213], v189 offset:54272
	ds_read_b128 v[214:217], v189 offset:55296
	ds_read_b128 v[218:221], v189 offset:56320
	global_load_lds_dwordx4 v158, s[98:99]
	s_add_i32 m0, s8, 0x2000
	s_add_u32 s8, s70, 0x80080
	s_addc_u32 s9, s71, 0
	s_add_i32 s10, s11, s80
	global_load_lds_dwordx4 v162, s[98:99]
	s_mov_b32 m0, s10
	s_nop 0
	global_load_lds_dwordx4 v158, s[8:9]
	s_add_i32 m0, s10, 0x2000
	s_nop 0
	global_load_lds_dwordx4 v162, s[8:9]
	s_mov_b32 m0, s67
	s_nop 0
	global_load_lds_dwordx4 v156, s[100:101]
	s_mov_b32 m0, s81
	s_nop 0
	global_load_lds_dwordx4 v160, s[100:101]
	s_waitcnt vmcnt(8)
	s_waitcnt lgkmcnt(0)
	s_barrier
	s_waitcnt lgkmcnt(0)
	v_mfma_f32_16x16x32_bf16 v[72:75], v[52:55], v[176:179], v[72:75]
	v_mfma_f32_16x16x32_bf16 v[72:75], v[56:59], v[180:183], v[72:75]
	v_mfma_f32_16x16x32_bf16 v[64:67], v[76:79], v[176:179], v[64:67]
	v_mfma_f32_16x16x32_bf16 v[64:67], v[80:83], v[180:183], v[64:67]
	v_mfma_f32_16x16x32_bf16 v[60:63], v[76:79], v[190:193], v[60:63]
	v_mfma_f32_16x16x32_bf16 v[60:63], v[80:83], v[194:197], v[60:63]
	v_mfma_f32_16x16x32_bf16 v[68:71], v[52:55], v[190:193], v[68:71]
	v_mfma_f32_16x16x32_bf16 v[68:71], v[56:59], v[194:197], v[68:71]
	v_mfma_f32_16x16x32_bf16 v[48:51], v[52:55], v[198:201], v[48:51]
	v_mfma_f32_16x16x32_bf16 v[48:51], v[56:59], v[210:213], v[48:51]
	v_mfma_f32_16x16x32_bf16 v[44:47], v[76:79], v[198:201], v[44:47]
	v_mfma_f32_16x16x32_bf16 v[44:47], v[80:83], v[210:213], v[44:47]
	v_mfma_f32_16x16x32_bf16 v[36:39], v[76:79], v[214:217], v[36:39]
	v_mfma_f32_16x16x32_bf16 v[36:39], v[80:83], v[218:221], v[36:39]
	v_mfma_f32_16x16x32_bf16 v[40:43], v[52:55], v[214:217], v[40:43]
	v_mfma_f32_16x16x32_bf16 v[40:43], v[56:59], v[218:221], v[40:43]
	v_mfma_f32_16x16x32_bf16 v[32:35], v[116:119], v[176:179], v[32:35]
	v_mfma_f32_16x16x32_bf16 v[32:35], v[120:123], v[180:183], v[32:35]
	v_mfma_f32_16x16x32_bf16 v[24:27], v[168:171], v[176:179], v[24:27]
	v_mfma_f32_16x16x32_bf16 v[24:27], v[172:175], v[180:183], v[24:27]
	v_mfma_f32_16x16x32_bf16 v[20:23], v[168:171], v[190:193], v[20:23]
	v_mfma_f32_16x16x32_bf16 v[20:23], v[172:175], v[194:197], v[20:23]
	v_mfma_f32_16x16x32_bf16 v[28:31], v[116:119], v[190:193], v[28:31]
	v_mfma_f32_16x16x32_bf16 v[28:31], v[120:123], v[194:197], v[28:31]
	v_mfma_f32_16x16x32_bf16 v[16:19], v[116:119], v[198:201], v[16:19]
	v_mfma_f32_16x16x32_bf16 v[16:19], v[120:123], v[210:213], v[16:19]
	v_mfma_f32_16x16x32_bf16 v[12:15], v[168:171], v[198:201], v[12:15]
	v_mfma_f32_16x16x32_bf16 v[12:15], v[172:175], v[210:213], v[12:15]
	v_mfma_f32_16x16x32_bf16 v[2:5], v[168:171], v[214:217], v[2:5]
	v_mfma_f32_16x16x32_bf16 v[6:9], v[116:119], v[214:217], v[8:11]
	v_mfma_f32_16x16x32_bf16 v[8:11], v[120:123], v[218:221], v[6:9]
	v_mfma_f32_16x16x32_bf16 v[4:7], v[172:175], v[218:221], v[2:5]
	s_barrier
	s_add_i32 s4, s4, 2
	s_add_u32 s97, s97, 0x100
	s_addc_u32 s96, s96, 0
	s_cmp_gt_u32 s4, 29
	s_mov_b64 s[8:9], s[68:69]
	s_cbranch_scc0 .LBB0_327
	s_branch .Lpeelx327
; #define PG8_STAGE(bufoff, gbase, voff) do { _Pragma("unroll") for (int _i = 0; _i < 2; ++_i) \
;         __builtin_amdgcn_global_load_lds((const unsigned*)((const char*)(gbase) + (voff)[_i]), (PG8_LAS unsigned*)(lds + (bufoff) + ldsw + _i * 8192), 16, 0, 0); } while (0)
; #define PG8_LDA(dst, b, h) do { _Pragma("unroll") for (int m = 0; m < 4; ++m) _Pragma("unroll") for (int k = 0; k < 2; ++k) dst[m][k] = *(const PG8_LAS bf16x8*)(lds + PG8_SA(b, h) + aoff + m * 2048 + k * 1024); } while (0)
; #define PG8_LDB(dst, b, h) do { _Pragma("unroll") for (int n = 0; n < 2; ++n) _Pragma("unroll") for (int k = 0; k < 2; ++k) dst[n][k] = *(const PG8_LAS bf16x8*)(lds + PG8_SB(b, h) + boff + n * 2048 + k * 1024); } while (0)
; #define PG8_MMA(ai, bj, At, Bt) do { __builtin_amdgcn_s_setprio(1); _Pragma("unroll") for (int m = 0; m < 4; ++m) _Pragma("unroll") for (int n = 0; n < 2; ++n) _Pragma("unroll") for (int k = 0; k < 2; ++k) \
;         acc[ai][bj][m][n] = mma16<Epi::I8>(Bt[n][k], At[m][k], acc[ai][bj][m][n]); __builtin_amdgcn_s_setprio(0); } while (0)
; #define PG8_WAIT_V(n) asm volatile("s_waitcnt vmcnt(" #n ")" ::: "memory")
; #define PG8_WAIT_L(n) asm volatile("s_waitcnt lgkmcnt(" #n ")" ::: "memory")
; template <class Epi, class Sched, bool ALIGN_EPI = false, bool SP2 = false>
; __device__ __forceinline__ void gemm_phase(PG8_LAS unsigned char* lds, const Gemm g, const Sched& S, const Epi& E) {
;     ...
;         for (int t = 0; t < nt; t += 2) {
;             const bool last = (t == nt - 2);
;             const char* a1 = cA + (size_t)(t + 1) * kstep;
;             const char* a2 = last ? nA : cA + (size_t)(t + 2) * kstep; const char* b2 = last ? nB : cB + (size_t)(t + 2) * kstep;
;             const char* a3 = a2 + kstep; const char* b3 = b2 + kstep;
;             if (last && has_next) S.a_ready(nxt);
;             if constexpr (SP2) {
;             PG8_LDB(B0, 0, 0); PG8_LDB(B1, 0, 1); PG8_SCHED; PG8_LDA(At, 0, 0); PG8_STAGE(PG8_SA(1, 1), a1 + hstep, voffA);
;             PG8_WAIT_V(8); PG8_WAIT_L(0); PG8_BAR; PG8_MMA(0, 0, At, B0); PG8_MMA(0, 1, At, B1); PG8_BAR; PG8_SCHED;
;             PG8_LDA(At, 0, 1); PG8_STAGE(PG8_SB(0, 0), b2, voffB); PG8_STAGE(PG8_SB(0, 1), b2 + hstep, voffB); PG8_STAGE(PG8_SA(0, 0), a2, voffA);
;             PG8_WAIT_V(8); PG8_WAIT_L(0); PG8_BAR; PG8_MMA(1, 0, At, B0); PG8_MMA(1, 1, At, B1); PG8_BAR; PG8_SCHED;
.LBB0_327:
	s_add_u32 s68, s8, 0x100
	s_addc_u32 s69, s9, 0
	s_add_i32 s84, 0, 0x10000
	s_cmp_eq_u32 s4, 28
	s_cselect_b32 vcc_hi, s1, s69
	s_cselect_b32 vcc_lo, s5, s68
	v_add_u32_e32 v0, s84, v188
	s_cselect_b32 s71, s7, s96
	s_cselect_b32 s70, s85, s97
	s_add_i32 s10, 0, 0x14000
	ds_read_b128 v[52:55], v0
	ds_read_b128 v[56:59], v0 offset:1024
	ds_read_b128 v[76:79], v0 offset:2048
	ds_read_b128 v[80:83], v0 offset:3072
	v_add_u32_e32 v0, s10, v188
	ds_read_b128 v[116:119], v0
	ds_read_b128 v[120:123], v0 offset:1024
	ds_read_b128 v[168:171], v0 offset:2048
	ds_read_b128 v[172:175], v0 offset:3072
	s_add_i32 m0, s58, 0xc000
	ds_read_b128 v[176:179], v189
	ds_read_b128 v[180:183], v189 offset:1024
	ds_read_b128 v[190:193], v189 offset:2048
	ds_read_b128 v[194:197], v189 offset:3072
	ds_read_b128 v[198:201], v189 offset:4096
	ds_read_b128 v[210:213], v189 offset:5120
	ds_read_b128 v[214:217], v189 offset:6144
	ds_read_b128 v[218:221], v189 offset:7168
	global_load_lds_dwordx4 v164, s[8:9]
	s_add_i32 m0, s58, 0xe000
	s_nop 0
	global_load_lds_dwordx4 v166, s[8:9]
	s_waitcnt vmcnt(8)
	s_waitcnt lgkmcnt(0)
	s_barrier
	s_waitcnt lgkmcnt(0)
	v_mfma_f32_16x16x32_bf16 v[152:155], v[52:55], v[176:179], v[152:155]
	v_mfma_f32_16x16x32_bf16 v[152:155], v[56:59], v[180:183], v[152:155]
	v_mfma_f32_16x16x32_bf16 v[144:147], v[76:79], v[176:179], v[144:147]
	v_mfma_f32_16x16x32_bf16 v[144:147], v[80:83], v[180:183], v[144:147]
	v_mfma_f32_16x16x32_bf16 v[140:143], v[76:79], v[190:193], v[140:143]
	v_mfma_f32_16x16x32_bf16 v[140:143], v[80:83], v[194:197], v[140:143]
	v_mfma_f32_16x16x32_bf16 v[148:151], v[52:55], v[190:193], v[148:151]
	v_mfma_f32_16x16x32_bf16 v[148:151], v[56:59], v[194:197], v[148:151]
	v_mfma_f32_16x16x32_bf16 v[136:139], v[52:55], v[198:201], v[136:139]
	v_mfma_f32_16x16x32_bf16 v[136:139], v[56:59], v[210:213], v[136:139]
	v_mfma_f32_16x16x32_bf16 v[132:135], v[76:79], v[198:201], v[132:135]
	v_mfma_f32_16x16x32_bf16 v[132:135], v[80:83], v[210:213], v[132:135]
	v_mfma_f32_16x16x32_bf16 v[124:127], v[76:79], v[214:217], v[124:127]
	v_mfma_f32_16x16x32_bf16 v[124:127], v[80:83], v[218:221], v[124:127]
	v_mfma_f32_16x16x32_bf16 v[128:131], v[52:55], v[214:217], v[128:131]
	v_mfma_f32_16x16x32_bf16 v[128:131], v[56:59], v[218:221], v[128:131]
	v_mfma_f32_16x16x32_bf16 v[112:115], v[116:119], v[176:179], v[112:115]
	v_mfma_f32_16x16x32_bf16 v[112:115], v[120:123], v[180:183], v[112:115]
	v_mfma_f32_16x16x32_bf16 v[104:107], v[168:171], v[176:179], v[104:107]
	v_mfma_f32_16x16x32_bf16 v[104:107], v[172:175], v[180:183], v[104:107]
	v_mfma_f32_16x16x32_bf16 v[100:103], v[168:171], v[190:193], v[100:103]
	v_mfma_f32_16x16x32_bf16 v[100:103], v[172:175], v[194:197], v[100:103]
	v_mfma_f32_16x16x32_bf16 v[108:111], v[116:119], v[190:193], v[108:111]
	v_mfma_f32_16x16x32_bf16 v[108:111], v[120:123], v[194:197], v[108:111]
	v_mfma_f32_16x16x32_bf16 v[96:99], v[116:119], v[198:201], v[96:99]
	v_mfma_f32_16x16x32_bf16 v[96:99], v[120:123], v[210:213], v[96:99]
	v_mfma_f32_16x16x32_bf16 v[92:95], v[168:171], v[198:201], v[92:95]
	v_mfma_f32_16x16x32_bf16 v[92:95], v[172:175], v[210:213], v[92:95]
	v_mfma_f32_16x16x32_bf16 v[84:87], v[168:171], v[214:217], v[84:87]
	v_mfma_f32_16x16x32_bf16 v[84:87], v[172:175], v[218:221], v[84:87]
	v_mfma_f32_16x16x32_bf16 v[88:91], v[116:119], v[214:217], v[88:91]
	v_mfma_f32_16x16x32_bf16 v[88:91], v[120:123], v[218:221], v[88:91]
	s_barrier
	s_add_i32 s8, s84, s80
	s_mov_b32 m0, s8
	ds_read_b128 v[176:179], v189 offset:16384
	ds_read_b128 v[180:183], v189 offset:17408
	ds_read_b128 v[190:193], v189 offset:18432
	ds_read_b128 v[194:197], v189 offset:19456
	ds_read_b128 v[198:201], v189 offset:20480
	ds_read_b128 v[210:213], v189 offset:21504
	ds_read_b128 v[214:217], v189 offset:22528
	ds_read_b128 v[218:221], v189 offset:23552
	global_load_lds_dwordx4 v158, s[70:71]
	s_add_i32 m0, s8, 0x2000
	s_add_u32 s8, s70, 0x80000
	s_addc_u32 s9, s71, 0
	s_add_i32 s10, s10, s80
	global_load_lds_dwordx4 v162, s[70:71]
	s_mov_b32 m0, s10
	s_nop 0
	global_load_lds_dwordx4 v158, s[8:9]
	s_add_i32 m0, s10, 0x2000
	s_nop 0
	global_load_lds_dwordx4 v162, s[8:9]
	s_mov_b32 m0, s58
	s_nop 0
	global_load_lds_dwordx4 v156, vcc
	s_mov_b32 m0, s12
	s_nop 0
	global_load_lds_dwordx4 v160, vcc
	s_waitcnt vmcnt(8)
	s_waitcnt lgkmcnt(0)
	s_barrier
	s_waitcnt lgkmcnt(0)
	v_mfma_f32_16x16x32_bf16 v[72:75], v[52:55], v[176:179], v[72:75]
	v_mfma_f32_16x16x32_bf16 v[72:75], v[56:59], v[180:183], v[72:75]
	v_mfma_f32_16x16x32_bf16 v[64:67], v[76:79], v[176:179], v[64:67]
	v_mfma_f32_16x16x32_bf16 v[64:67], v[80:83], v[180:183], v[64:67]
	v_mfma_f32_16x16x32_bf16 v[60:63], v[76:79], v[190:193], v[60:63]
	v_mfma_f32_16x16x32_bf16 v[60:63], v[80:83], v[194:197], v[60:63]
	v_mfma_f32_16x16x32_bf16 v[68:71], v[52:55], v[190:193], v[68:71]
	v_mfma_f32_16x16x32_bf16 v[68:71], v[56:59], v[194:197], v[68:71]
	v_mfma_f32_16x16x32_bf16 v[48:51], v[52:55], v[198:201], v[48:51]
	v_mfma_f32_16x16x32_bf16 v[48:51], v[56:59], v[210:213], v[48:51]
	v_mfma_f32_16x16x32_bf16 v[44:47], v[76:79], v[198:201], v[44:47]
	v_mfma_f32_16x16x32_bf16 v[44:47], v[80:83], v[210:213], v[44:47]
	v_mfma_f32_16x16x32_bf16 v[36:39], v[76:79], v[214:217], v[36:39]
	v_mfma_f32_16x16x32_bf16 v[36:39], v[80:83], v[218:221], v[36:39]
	v_mfma_f32_16x16x32_bf16 v[40:43], v[52:55], v[214:217], v[40:43]
	v_mfma_f32_16x16x32_bf16 v[40:43], v[56:59], v[218:221], v[40:43]
	v_mfma_f32_16x16x32_bf16 v[32:35], v[116:119], v[176:179], v[32:35]
	v_mfma_f32_16x16x32_bf16 v[32:35], v[120:123], v[180:183], v[32:35]
	v_mfma_f32_16x16x32_bf16 v[24:27], v[168:171], v[176:179], v[24:27]
	v_mfma_f32_16x16x32_bf16 v[24:27], v[172:175], v[180:183], v[24:27]
	v_mfma_f32_16x16x32_bf16 v[20:23], v[168:171], v[190:193], v[20:23]
	v_mfma_f32_16x16x32_bf16 v[20:23], v[172:175], v[194:197], v[20:23]
	v_mfma_f32_16x16x32_bf16 v[28:31], v[116:119], v[190:193], v[28:31]
	v_mfma_f32_16x16x32_bf16 v[28:31], v[120:123], v[194:197], v[28:31]
	v_mfma_f32_16x16x32_bf16 v[16:19], v[116:119], v[198:201], v[16:19]
	v_mfma_f32_16x16x32_bf16 v[16:19], v[120:123], v[210:213], v[16:19]
	v_mfma_f32_16x16x32_bf16 v[12:15], v[168:171], v[198:201], v[12:15]
	v_mfma_f32_16x16x32_bf16 v[12:15], v[172:175], v[210:213], v[12:15]
	v_mfma_f32_16x16x32_bf16 v[2:5], v[168:171], v[214:217], v[4:7]
	v_mfma_f32_16x16x32_bf16 v[2:5], v[172:175], v[218:221], v[2:5]
	v_mfma_f32_16x16x32_bf16 v[8:11], v[116:119], v[214:217], v[8:11]
	v_mfma_f32_16x16x32_bf16 v[8:11], v[120:123], v[218:221], v[8:11]
	s_barrier
; #define PG8_STAGE(bufoff, gbase, voff) do { _Pragma("unroll") for (int _i = 0; _i < 2; ++_i) \
;         __builtin_amdgcn_global_load_lds((const unsigned*)((const char*)(gbase) + (voff)[_i]), (PG8_LAS unsigned*)(lds + (bufoff) + ldsw + _i * 8192), 16, 0, 0); } while (0)
; #define PG8_LDA(dst, b, h) do { _Pragma("unroll") for (int m = 0; m < 4; ++m) _Pragma("unroll") for (int k = 0; k < 2; ++k) dst[m][k] = *(const PG8_LAS bf16x8*)(lds + PG8_SA(b, h) + aoff + m * 2048 + k * 1024); } while (0)
; #define PG8_LDB(dst, b, h) do { _Pragma("unroll") for (int n = 0; n < 2; ++n) _Pragma("unroll") for (int k = 0; k < 2; ++k) dst[n][k] = *(const PG8_LAS bf16x8*)(lds + PG8_SB(b, h) + boff + n * 2048 + k * 1024); } while (0)
; #define PG8_MMA(ai, bj, At, Bt) do { __builtin_amdgcn_s_setprio(1); _Pragma("unroll") for (int m = 0; m < 4; ++m) _Pragma("unroll") for (int n = 0; n < 2; ++n) _Pragma("unroll") for (int k = 0; k < 2; ++k) \
;         acc[ai][bj][m][n] = mma16<Epi::I8>(Bt[n][k], At[m][k], acc[ai][bj][m][n]); __builtin_amdgcn_s_setprio(0); } while (0)
; #define PG8_WAIT_V(n) asm volatile("s_waitcnt vmcnt(" #n ")" ::: "memory")
; #define PG8_WAIT_L(n) asm volatile("s_waitcnt lgkmcnt(" #n ")" ::: "memory")
; #define PG8_BAR __builtin_amdgcn_s_barrier()
; template <class Epi, class Sched, bool ALIGN_EPI = false, bool SP2 = false>
; __device__ __forceinline__ void gemm_phase(PG8_LAS unsigned char* lds, const Gemm g, const Sched& S, const Epi& E) {
;     ...
;         for (int t = 0; t < nt; t += 2) {
;             const bool last = (t == nt - 2);
;             const char* a1 = cA + (size_t)(t + 1) * kstep;
;             const char* a2 = last ? nA : cA + (size_t)(t + 2) * kstep; const char* b2 = last ? nB : cB + (size_t)(t + 2) * kstep;
;             const char* a3 = a2 + kstep; const char* b3 = b2 + kstep;
;             if (last && has_next) S.a_ready(nxt);
;     ...
;             PG8_LDB(B0, 1, 0); PG8_LDB(B1, 1, 1); PG8_SCHED; PG8_LDA(At, 1, 0); PG8_STAGE(PG8_SA(0, 1), a2 + hstep, voffA);
;             PG8_WAIT_V(8); PG8_WAIT_L(0); PG8_BAR; PG8_MMA(0, 0, At, B0); PG8_MMA(0, 1, At, B1); PG8_BAR; PG8_SCHED;
;             PG8_LDA(At, 1, 1); PG8_STAGE(PG8_SB(1, 0), b3, voffB); PG8_STAGE(PG8_SB(1, 1), b3 + hstep, voffB); PG8_STAGE(PG8_SA(1, 0), a3, voffA);
;             PG8_WAIT_V(8); PG8_WAIT_L(0); PG8_BAR; PG8_MMA(1, 0, At, B0); PG8_MMA(1, 1, At, B1); PG8_BAR; PG8_SCHED;
	s_add_i32 s10, 0, 0x18000
	v_add_u32_e32 v0, s10, v188
	s_add_i32 s11, 0, 0x1c000
	ds_read_b128 v[52:55], v0
	ds_read_b128 v[56:59], v0 offset:1024
	ds_read_b128 v[76:79], v0 offset:2048
	ds_read_b128 v[80:83], v0 offset:3072
	v_add_u32_e32 v0, s11, v188
	ds_read_b128 v[116:119], v0
	ds_read_b128 v[120:123], v0 offset:1024
	ds_read_b128 v[168:171], v0 offset:2048
	ds_read_b128 v[172:175], v0 offset:3072
	s_add_u32 s8, vcc_lo, 0x80000
	s_addc_u32 s9, vcc_hi, 0
	s_mov_b32 m0, s13
	ds_read_b128 v[176:179], v189 offset:32768
	ds_read_b128 v[180:183], v189 offset:33792
	ds_read_b128 v[190:193], v189 offset:34816
	ds_read_b128 v[194:197], v189 offset:35840
	ds_read_b128 v[198:201], v189 offset:36864
	ds_read_b128 v[210:213], v189 offset:37888
	ds_read_b128 v[214:217], v189 offset:38912
	ds_read_b128 v[218:221], v189 offset:39936
	global_load_lds_dwordx4 v156, s[8:9]
	s_mov_b32 m0, s66
	s_nop 0
	global_load_lds_dwordx4 v160, s[8:9]
	s_waitcnt vmcnt(8)
	s_waitcnt lgkmcnt(0)
	s_barrier
	s_waitcnt lgkmcnt(0)
	v_mfma_f32_16x16x32_bf16 v[152:155], v[52:55], v[176:179], v[152:155]
	v_mfma_f32_16x16x32_bf16 v[152:155], v[56:59], v[180:183], v[152:155]
	v_mfma_f32_16x16x32_bf16 v[144:147], v[76:79], v[176:179], v[144:147]
	v_mfma_f32_16x16x32_bf16 v[144:147], v[80:83], v[180:183], v[144:147]
	v_mfma_f32_16x16x32_bf16 v[140:143], v[76:79], v[190:193], v[140:143]
	v_mfma_f32_16x16x32_bf16 v[140:143], v[80:83], v[194:197], v[140:143]
	v_mfma_f32_16x16x32_bf16 v[148:151], v[52:55], v[190:193], v[148:151]
	v_mfma_f32_16x16x32_bf16 v[148:151], v[56:59], v[194:197], v[148:151]
	v_mfma_f32_16x16x32_bf16 v[136:139], v[52:55], v[198:201], v[136:139]
	v_mfma_f32_16x16x32_bf16 v[136:139], v[56:59], v[210:213], v[136:139]
	v_mfma_f32_16x16x32_bf16 v[132:135], v[76:79], v[198:201], v[132:135]
	v_mfma_f32_16x16x32_bf16 v[132:135], v[80:83], v[210:213], v[132:135]
	v_mfma_f32_16x16x32_bf16 v[124:127], v[76:79], v[214:217], v[124:127]
	v_mfma_f32_16x16x32_bf16 v[124:127], v[80:83], v[218:221], v[124:127]
	v_mfma_f32_16x16x32_bf16 v[128:131], v[52:55], v[214:217], v[128:131]
	v_mfma_f32_16x16x32_bf16 v[128:131], v[56:59], v[218:221], v[128:131]
	v_mfma_f32_16x16x32_bf16 v[112:115], v[116:119], v[176:179], v[112:115]
	v_mfma_f32_16x16x32_bf16 v[112:115], v[120:123], v[180:183], v[112:115]
	v_mfma_f32_16x16x32_bf16 v[104:107], v[168:171], v[176:179], v[104:107]
	v_mfma_f32_16x16x32_bf16 v[104:107], v[172:175], v[180:183], v[104:107]
	v_mfma_f32_16x16x32_bf16 v[100:103], v[168:171], v[190:193], v[100:103]
	v_mfma_f32_16x16x32_bf16 v[100:103], v[172:175], v[194:197], v[100:103]
	v_mfma_f32_16x16x32_bf16 v[108:111], v[116:119], v[190:193], v[108:111]
	v_mfma_f32_16x16x32_bf16 v[108:111], v[120:123], v[194:197], v[108:111]
	v_mfma_f32_16x16x32_bf16 v[96:99], v[116:119], v[198:201], v[96:99]
	v_mfma_f32_16x16x32_bf16 v[96:99], v[120:123], v[210:213], v[96:99]
	v_mfma_f32_16x16x32_bf16 v[92:95], v[168:171], v[198:201], v[92:95]
	v_mfma_f32_16x16x32_bf16 v[92:95], v[172:175], v[210:213], v[92:95]
	v_mfma_f32_16x16x32_bf16 v[84:87], v[168:171], v[214:217], v[84:87]
	v_mfma_f32_16x16x32_bf16 v[84:87], v[172:175], v[218:221], v[84:87]
	v_mfma_f32_16x16x32_bf16 v[88:91], v[116:119], v[214:217], v[88:91]
	v_mfma_f32_16x16x32_bf16 v[88:91], v[120:123], v[218:221], v[88:91]
	s_barrier
	s_add_i32 s8, s10, s80
	s_add_u32 s98, s70, 0x80
	s_addc_u32 s99, s71, 0
	s_add_u32 s100, vcc_lo, 0x80
	s_addc_u32 s101, vcc_hi, 0
	s_mov_b32 m0, s8
	ds_read_b128 v[176:179], v189 offset:49152
	ds_read_b128 v[180:183], v189 offset:50176
	ds_read_b128 v[190:193], v189 offset:51200
	ds_read_b128 v[194:197], v189 offset:52224
	ds_read_b128 v[198:201], v189 offset:53248
	ds_read_b128 v[210:213], v189 offset:54272
	ds_read_b128 v[214:217], v189 offset:55296
	ds_read_b128 v[218:221], v189 offset:56320
	global_load_lds_dwordx4 v158, s[98:99]
	s_add_i32 m0, s8, 0x2000
	s_add_u32 s8, s70, 0x80080
	s_addc_u32 s9, s71, 0
	s_add_i32 s10, s11, s80
	global_load_lds_dwordx4 v162, s[98:99]
	s_mov_b32 m0, s10
	s_nop 0
	global_load_lds_dwordx4 v158, s[8:9]
	s_add_i32 m0, s10, 0x2000
	s_nop 0
	global_load_lds_dwordx4 v162, s[8:9]
	s_mov_b32 m0, s67
	s_nop 0
	global_load_lds_dwordx4 v156, s[100:101]
	s_mov_b32 m0, s81
	s_nop 0
	global_load_lds_dwordx4 v160, s[100:101]
	s_waitcnt vmcnt(8)
	s_waitcnt lgkmcnt(0)
	s_barrier
	s_waitcnt lgkmcnt(0)
	v_mfma_f32_16x16x32_bf16 v[72:75], v[52:55], v[176:179], v[72:75]
	v_mfma_f32_16x16x32_bf16 v[72:75], v[56:59], v[180:183], v[72:75]
	v_mfma_f32_16x16x32_bf16 v[64:67], v[76:79], v[176:179], v[64:67]
	v_mfma_f32_16x16x32_bf16 v[64:67], v[80:83], v[180:183], v[64:67]
	v_mfma_f32_16x16x32_bf16 v[60:63], v[76:79], v[190:193], v[60:63]
	v_mfma_f32_16x16x32_bf16 v[60:63], v[80:83], v[194:197], v[60:63]
	v_mfma_f32_16x16x32_bf16 v[68:71], v[52:55], v[190:193], v[68:71]
	v_mfma_f32_16x16x32_bf16 v[68:71], v[56:59], v[194:197], v[68:71]
	v_mfma_f32_16x16x32_bf16 v[48:51], v[52:55], v[198:201], v[48:51]
	v_mfma_f32_16x16x32_bf16 v[48:51], v[56:59], v[210:213], v[48:51]
	v_mfma_f32_16x16x32_bf16 v[44:47], v[76:79], v[198:201], v[44:47]
	v_mfma_f32_16x16x32_bf16 v[44:47], v[80:83], v[210:213], v[44:47]
	v_mfma_f32_16x16x32_bf16 v[36:39], v[76:79], v[214:217], v[36:39]
	v_mfma_f32_16x16x32_bf16 v[36:39], v[80:83], v[218:221], v[36:39]
	v_mfma_f32_16x16x32_bf16 v[40:43], v[52:55], v[214:217], v[40:43]
	v_mfma_f32_16x16x32_bf16 v[40:43], v[56:59], v[218:221], v[40:43]
	v_mfma_f32_16x16x32_bf16 v[32:35], v[116:119], v[176:179], v[32:35]
	v_mfma_f32_16x16x32_bf16 v[32:35], v[120:123], v[180:183], v[32:35]
	v_mfma_f32_16x16x32_bf16 v[24:27], v[168:171], v[176:179], v[24:27]
	v_mfma_f32_16x16x32_bf16 v[24:27], v[172:175], v[180:183], v[24:27]
	v_mfma_f32_16x16x32_bf16 v[20:23], v[168:171], v[190:193], v[20:23]
	v_mfma_f32_16x16x32_bf16 v[20:23], v[172:175], v[194:197], v[20:23]
	v_mfma_f32_16x16x32_bf16 v[28:31], v[116:119], v[190:193], v[28:31]
	v_mfma_f32_16x16x32_bf16 v[28:31], v[120:123], v[194:197], v[28:31]
	v_mfma_f32_16x16x32_bf16 v[16:19], v[116:119], v[198:201], v[16:19]
	v_mfma_f32_16x16x32_bf16 v[16:19], v[120:123], v[210:213], v[16:19]
	v_mfma_f32_16x16x32_bf16 v[12:15], v[168:171], v[198:201], v[12:15]
	v_mfma_f32_16x16x32_bf16 v[12:15], v[172:175], v[210:213], v[12:15]
	v_mfma_f32_16x16x32_bf16 v[2:5], v[168:171], v[214:217], v[2:5]
	v_mfma_f32_16x16x32_bf16 v[6:9], v[116:119], v[214:217], v[8:11]
	v_mfma_f32_16x16x32_bf16 v[8:11], v[120:123], v[218:221], v[6:9]
	v_mfma_f32_16x16x32_bf16 v[4:7], v[172:175], v[218:221], v[2:5]
	s_barrier
	s_add_i32 s4, s4, 2
	s_add_u32 s97, s97, 0x100
	s_addc_u32 s96, s96, 0
	s_cmp_gt_u32 s4, 29
	s_mov_b64 s[8:9], s[68:69]
	s_cbranch_scc0 .LBB0_327

; #define PG8_STAGE(bufoff, gbase, voff) do { _Pragma("unroll") for (int _i = 0; _i < 2; ++_i) \
;         __builtin_amdgcn_global_load_lds((const unsigned*)((const char*)(gbase) + (voff)[_i]), (PG8_LAS unsigned*)(lds + (bufoff) + ldsw + _i * 8192), 16, 0, 0); } while (0)
; #define PG8_LDA(dst, b, h) do { _Pragma("unroll") for (int m = 0; m < 4; ++m) _Pragma("unroll") for (int k = 0; k < 2; ++k) dst[m][k] = *(const PG8_LAS bf16x8*)(lds + PG8_SA(b, h) + aoff + m * 2048 + k * 1024); } while (0)
; #define PG8_LDB(dst, b, h) do { _Pragma("unroll") for (int n = 0; n < 2; ++n) _Pragma("unroll") for (int k = 0; k < 2; ++k) dst[n][k] = *(const PG8_LAS bf16x8*)(lds + PG8_SB(b, h) + boff + n * 2048 + k * 1024); } while (0)
; #define PG8_MMA(ai, bj, At, Bt) do { __builtin_amdgcn_s_setprio(1); _Pragma("unroll") for (int m = 0; m < 4; ++m) _Pragma("unroll") for (int n = 0; n < 2; ++n) _Pragma("unroll") for (int k = 0; k < 2; ++k) \
;         acc[ai][bj][m][n] = mma16<Epi::I8>(Bt[n][k], At[m][k], acc[ai][bj][m][n]); __builtin_amdgcn_s_setprio(0); } while (0)
; #define PG8_WAIT_V(n) asm volatile("s_waitcnt vmcnt(" #n ")" ::: "memory")
; #define PG8_WAIT_L(n) asm volatile("s_waitcnt lgkmcnt(" #n ")" ::: "memory")
; #define PG8_BAR __builtin_amdgcn_s_barrier()
; template <class Epi, class Sched, bool ALIGN_EPI = false, bool SP2 = false>
; __device__ __forceinline__ void gemm_phase(PG8_LAS unsigned char* lds, const Gemm g, const Sched& S, const Epi& E) {
;     ...
;             const bool last = (t == nt - 2);
;             const char* a1 = cA + (size_t)(t + 1) * kstep;
;             const char* a2 = last ? nA : cA + (size_t)(t + 2) * kstep; const char* b2 = last ? nB : cB + (size_t)(t + 2) * kstep;
;             const char* a3 = a2 + kstep; const char* b3 = b2 + kstep;
;             if (last && has_next) S.a_ready(nxt);
;             if constexpr (SP2) {
;             PG8_LDB(B0, 0, 0); PG8_LDB(B1, 0, 1); PG8_SCHED; PG8_LDA(At, 0, 0); PG8_STAGE(PG8_SA(1, 1), a1 + hstep, voffA);
;             PG8_WAIT_V(8); PG8_WAIT_L(0); PG8_BAR; PG8_MMA(0, 0, At, B0); PG8_MMA(0, 1, At, B1); PG8_BAR; PG8_SCHED;
;             PG8_LDA(At, 0, 1); PG8_STAGE(PG8_SB(0, 0), b2, voffB); PG8_STAGE(PG8_SB(0, 1), b2 + hstep, voffB); PG8_STAGE(PG8_SA(0, 0), a2, voffA);
;             PG8_WAIT_V(8); PG8_WAIT_L(0); PG8_BAR; PG8_MMA(1, 0, At, B0); PG8_MMA(1, 1, At, B1); PG8_BAR; PG8_SCHED;
.Lpeel385:
	s_add_u32 s70, s8, 0x100
	s_addc_u32 s71, s9, 0
	s_add_i32 s84, 0, 0x10000
	s_cmp_eq_u32 s5, 12
	s_cselect_b32 vcc_hi, s1, s71
	s_cselect_b32 vcc_lo, s7, s70
	v_add_u32_e32 v0, s84, v214
	s_cselect_b32 s83, s69, s68
	s_cselect_b32 s82, s81, s85
	s_add_i32 s10, 0, 0x14000
	ds_read_b128 v[44:47], v0
	ds_read_b128 v[52:55], v0 offset:1024
	ds_read_b128 v[60:63], v0 offset:2048
	ds_read_b128 v[64:67], v0 offset:3072
	v_add_u32_e32 v0, s10, v214
	ds_read_b128 v[84:87], v0
	ds_read_b128 v[88:91], v0 offset:1024
	ds_read_b128 v[92:95], v0 offset:2048
	ds_read_b128 v[100:103], v0 offset:3072
	s_add_i32 m0, s13, 0xc000
	ds_read_b128 v[124:127], v215
	ds_read_b128 v[128:131], v215 offset:1024
	ds_read_b128 v[140:143], v215 offset:2048
	ds_read_b128 v[188:191], v215 offset:3072
	ds_read_b128 v[192:195], v215 offset:4096
	ds_read_b128 v[196:199], v215 offset:5120
	ds_read_b128 v[216:219], v215 offset:6144
	ds_read_b128 v[220:223], v215 offset:7168
	global_load_lds_dwordx4 v184, s[8:9]
	s_add_i32 m0, s13, 0xe000
	s_nop 0
	global_load_lds_dwordx4 v186, s[8:9]
	s_waitcnt vmcnt(8)
	s_waitcnt lgkmcnt(0)
	s_barrier
	s_waitcnt lgkmcnt(0)
	v_mfma_i32_16x16x64_i8 v[172:175], v[44:47], v[124:127], 0
	v_mfma_i32_16x16x64_i8 v[172:175], v[52:55], v[128:131], v[172:175]
	v_mfma_i32_16x16x64_i8 v[164:167], v[60:63], v[124:127], 0
	v_mfma_i32_16x16x64_i8 v[164:167], v[64:67], v[128:131], v[164:167]
	v_mfma_i32_16x16x64_i8 v[160:163], v[60:63], v[140:143], 0
	v_mfma_i32_16x16x64_i8 v[160:163], v[64:67], v[188:191], v[160:163]
	v_mfma_i32_16x16x64_i8 v[168:171], v[44:47], v[140:143], 0
	v_mfma_i32_16x16x64_i8 v[168:171], v[52:55], v[188:191], v[168:171]
	v_mfma_i32_16x16x64_i8 v[156:159], v[44:47], v[192:195], 0
	v_mfma_i32_16x16x64_i8 v[156:159], v[52:55], v[196:199], v[156:159]
	v_mfma_i32_16x16x64_i8 v[152:155], v[60:63], v[192:195], 0
	v_mfma_i32_16x16x64_i8 v[152:155], v[64:67], v[196:199], v[152:155]
	v_mfma_i32_16x16x64_i8 v[144:147], v[60:63], v[216:219], 0
	v_mfma_i32_16x16x64_i8 v[144:147], v[64:67], v[220:223], v[144:147]
	v_mfma_i32_16x16x64_i8 v[148:151], v[44:47], v[216:219], 0
	v_mfma_i32_16x16x64_i8 v[148:151], v[52:55], v[220:223], v[148:151]
	v_mfma_i32_16x16x64_i8 v[136:139], v[84:87], v[124:127], 0
	v_mfma_i32_16x16x64_i8 v[136:139], v[88:91], v[128:131], v[136:139]
	v_mfma_i32_16x16x64_i8 v[120:123], v[92:95], v[124:127], 0
	v_mfma_i32_16x16x64_i8 v[120:123], v[100:103], v[128:131], v[120:123]
	v_mfma_i32_16x16x64_i8 v[116:119], v[92:95], v[140:143], 0
	v_mfma_i32_16x16x64_i8 v[116:119], v[100:103], v[188:191], v[116:119]
	v_mfma_i32_16x16x64_i8 v[108:111], v[92:95], v[192:195], 0
	v_mfma_i32_16x16x64_i8 v[108:111], v[100:103], v[196:199], v[108:111]
	v_mfma_i32_16x16x64_i8 v[112:115], v[84:87], v[192:195], 0
	v_mfma_i32_16x16x64_i8 v[112:115], v[88:91], v[196:199], v[112:115]
	v_mfma_i32_16x16x64_i8 v[104:107], v[84:87], v[216:219], 0
	v_mfma_i32_16x16x64_i8 v[104:107], v[88:91], v[220:223], v[104:107]
	v_mfma_i32_16x16x64_i8 v[96:99], v[92:95], v[216:219], 0
	v_mfma_i32_16x16x64_i8 v[96:99], v[100:103], v[220:223], v[96:99]
	v_mfma_i32_16x16x64_i8 v[124:127], v[84:87], v[140:143], 0
	v_mfma_i32_16x16x64_i8 v[124:127], v[88:91], v[188:191], v[124:127]
	s_barrier
	s_add_i32 s8, s84, s12
	s_mov_b32 m0, s8
	ds_read_b128 v[128:131], v215 offset:16384
	ds_read_b128 v[132:135], v215 offset:17408
	ds_read_b128 v[140:143], v215 offset:18432
	ds_read_b128 v[188:191], v215 offset:19456
	ds_read_b128 v[192:195], v215 offset:20480
	ds_read_b128 v[196:199], v215 offset:21504
	ds_read_b128 v[216:219], v215 offset:22528
	ds_read_b128 v[220:223], v215 offset:23552
	global_load_lds_dwordx4 v178, s[82:83]
	s_add_i32 m0, s8, 0x2000
	s_add_u32 s8, s82, 0x40000
	s_addc_u32 s9, s83, 0
	s_add_i32 s10, s10, s12
	global_load_lds_dwordx4 v182, s[82:83]
	s_mov_b32 m0, s10
	s_nop 0
	global_load_lds_dwordx4 v178, s[8:9]
	s_add_i32 m0, s10, 0x2000
	s_nop 0
	global_load_lds_dwordx4 v182, s[8:9]
	s_mov_b32 m0, s13
	s_nop 0
	global_load_lds_dwordx4 v176, vcc
	s_mov_b32 m0, s66
	s_nop 0
	global_load_lds_dwordx4 v180, vcc
	s_waitcnt vmcnt(8)
	s_waitcnt lgkmcnt(0)
	s_barrier
	s_waitcnt lgkmcnt(0)
	v_mfma_i32_16x16x64_i8 v[80:83], v[44:47], v[128:131], 0
	v_mfma_i32_16x16x64_i8 v[80:83], v[52:55], v[132:135], v[80:83]
	v_mfma_i32_16x16x64_i8 v[72:75], v[60:63], v[128:131], 0
	v_mfma_i32_16x16x64_i8 v[72:75], v[64:67], v[132:135], v[72:75]
	v_mfma_i32_16x16x64_i8 v[68:71], v[60:63], v[140:143], 0
	v_mfma_i32_16x16x64_i8 v[68:71], v[64:67], v[188:191], v[68:71]
	v_mfma_i32_16x16x64_i8 v[76:79], v[44:47], v[140:143], 0
	v_mfma_i32_16x16x64_i8 v[76:79], v[52:55], v[188:191], v[76:79]
	v_mfma_i32_16x16x64_i8 v[56:59], v[44:47], v[192:195], 0
	v_mfma_i32_16x16x64_i8 v[56:59], v[52:55], v[196:199], v[56:59]
	v_mfma_i32_16x16x64_i8 v[48:51], v[60:63], v[192:195], 0
	v_mfma_i32_16x16x64_i8 v[48:51], v[64:67], v[196:199], v[48:51]
	v_mfma_i32_16x16x64_i8 v[36:39], v[60:63], v[216:219], 0
	v_mfma_i32_16x16x64_i8 v[36:39], v[64:67], v[220:223], v[36:39]
	v_mfma_i32_16x16x64_i8 v[40:43], v[44:47], v[216:219], 0
	v_mfma_i32_16x16x64_i8 v[40:43], v[52:55], v[220:223], v[40:43]
	v_mfma_i32_16x16x64_i8 v[32:35], v[84:87], v[128:131], 0
	v_mfma_i32_16x16x64_i8 v[32:35], v[88:91], v[132:135], v[32:35]
	v_mfma_i32_16x16x64_i8 v[24:27], v[92:95], v[128:131], 0
	v_mfma_i32_16x16x64_i8 v[24:27], v[100:103], v[132:135], v[24:27]
	v_mfma_i32_16x16x64_i8 v[20:23], v[92:95], v[140:143], 0
	v_mfma_i32_16x16x64_i8 v[20:23], v[100:103], v[188:191], v[20:23]
	v_mfma_i32_16x16x64_i8 v[28:31], v[84:87], v[140:143], 0
	v_mfma_i32_16x16x64_i8 v[28:31], v[88:91], v[188:191], v[28:31]
	v_mfma_i32_16x16x64_i8 v[16:19], v[84:87], v[192:195], 0
	v_mfma_i32_16x16x64_i8 v[16:19], v[88:91], v[196:199], v[16:19]
	v_mfma_i32_16x16x64_i8 v[12:15], v[92:95], v[192:195], 0
	v_mfma_i32_16x16x64_i8 v[12:15], v[100:103], v[196:199], v[12:15]
	v_mfma_i32_16x16x64_i8 v[2:5], v[92:95], v[216:219], 0
	v_mfma_i32_16x16x64_i8 v[2:5], v[100:103], v[220:223], v[2:5]
	v_mfma_i32_16x16x64_i8 v[8:11], v[84:87], v[216:219], 0
	v_mfma_i32_16x16x64_i8 v[8:11], v[88:91], v[220:223], v[8:11]
	s_barrier
; #define PG8_STAGE(bufoff, gbase, voff) do { _Pragma("unroll") for (int _i = 0; _i < 2; ++_i) \
;         __builtin_amdgcn_global_load_lds((const unsigned*)((const char*)(gbase) + (voff)[_i]), (PG8_LAS unsigned*)(lds + (bufoff) + ldsw + _i * 8192), 16, 0, 0); } while (0)
; #define PG8_LDA(dst, b, h) do { _Pragma("unroll") for (int m = 0; m < 4; ++m) _Pragma("unroll") for (int k = 0; k < 2; ++k) dst[m][k] = *(const PG8_LAS bf16x8*)(lds + PG8_SA(b, h) + aoff + m * 2048 + k * 1024); } while (0)
; #define PG8_LDB(dst, b, h) do { _Pragma("unroll") for (int n = 0; n < 2; ++n) _Pragma("unroll") for (int k = 0; k < 2; ++k) dst[n][k] = *(const PG8_LAS bf16x8*)(lds + PG8_SB(b, h) + boff + n * 2048 + k * 1024); } while (0)
; #define PG8_MMA(ai, bj, At, Bt) do { __builtin_amdgcn_s_setprio(1); _Pragma("unroll") for (int m = 0; m < 4; ++m) _Pragma("unroll") for (int n = 0; n < 2; ++n) _Pragma("unroll") for (int k = 0; k < 2; ++k) \
;         acc[ai][bj][m][n] = mma16<Epi::I8>(Bt[n][k], At[m][k], acc[ai][bj][m][n]); __builtin_amdgcn_s_setprio(0); } while (0)
; #define PG8_WAIT_V(n) asm volatile("s_waitcnt vmcnt(" #n ")" ::: "memory")
; #define PG8_WAIT_L(n) asm volatile("s_waitcnt lgkmcnt(" #n ")" ::: "memory")
; #define PG8_BAR __builtin_amdgcn_s_barrier()
; #define PG8_SCHED __builtin_amdgcn_sched_barrier(0)
; template <class Epi, class Sched, bool ALIGN_EPI = false, bool SP2 = false>
; __device__ __forceinline__ void gemm_phase(PG8_LAS unsigned char* lds, const Gemm g, const Sched& S, const Epi& E) {
;     ...
;             PG8_LDB(B0, 1, 0); PG8_LDB(B1, 1, 1); PG8_SCHED; PG8_LDA(At, 1, 0); PG8_STAGE(PG8_SA(0, 1), a2 + hstep, voffA);
;             PG8_WAIT_V(8); PG8_WAIT_L(0); PG8_BAR; PG8_MMA(0, 0, At, B0); PG8_MMA(0, 1, At, B1); PG8_BAR; PG8_SCHED;
;             PG8_LDA(At, 1, 1); PG8_STAGE(PG8_SB(1, 0), b3, voffB); PG8_STAGE(PG8_SB(1, 1), b3 + hstep, voffB); PG8_STAGE(PG8_SA(1, 0), a3, voffA);
;             PG8_WAIT_V(8); PG8_WAIT_L(0); PG8_BAR; PG8_MMA(1, 0, At, B0); PG8_MMA(1, 1, At, B1); PG8_BAR; PG8_SCHED;
	s_add_i32 s10, 0, 0x18000
	v_add_u32_e32 v0, s10, v214
	s_add_i32 s11, 0, 0x1c000
	ds_read_b128 v[44:47], v0
	ds_read_b128 v[52:55], v0 offset:1024
	ds_read_b128 v[60:63], v0 offset:2048
	ds_read_b128 v[64:67], v0 offset:3072
	v_add_u32_e32 v0, s11, v214
	ds_read_b128 v[84:87], v0
	ds_read_b128 v[88:91], v0 offset:1024
	ds_read_b128 v[92:95], v0 offset:2048
	ds_read_b128 v[100:103], v0 offset:3072
	s_add_u32 s8, vcc_lo, 0x40000
	s_addc_u32 s9, vcc_hi, 0
	s_mov_b32 m0, s67
	ds_read_b128 v[128:131], v215 offset:32768
	ds_read_b128 v[132:135], v215 offset:33792
	ds_read_b128 v[140:143], v215 offset:34816
	ds_read_b128 v[188:191], v215 offset:35840
	ds_read_b128 v[192:195], v215 offset:36864
	ds_read_b128 v[196:199], v215 offset:37888
	ds_read_b128 v[216:219], v215 offset:38912
	ds_read_b128 v[220:223], v215 offset:39936
	global_load_lds_dwordx4 v176, s[8:9]
	s_mov_b32 m0, s80
	s_nop 0
	global_load_lds_dwordx4 v180, s[8:9]
	s_waitcnt vmcnt(8)
	s_waitcnt lgkmcnt(0)
	s_barrier
	s_waitcnt lgkmcnt(0)
	v_mfma_i32_16x16x64_i8 v[172:175], v[44:47], v[128:131], v[172:175]
	v_mfma_i32_16x16x64_i8 v[172:175], v[52:55], v[132:135], v[172:175]
	v_mfma_i32_16x16x64_i8 v[164:167], v[60:63], v[128:131], v[164:167]
	v_mfma_i32_16x16x64_i8 v[164:167], v[64:67], v[132:135], v[164:167]
	v_mfma_i32_16x16x64_i8 v[160:163], v[60:63], v[140:143], v[160:163]
	v_mfma_i32_16x16x64_i8 v[160:163], v[64:67], v[188:191], v[160:163]
	v_mfma_i32_16x16x64_i8 v[168:171], v[44:47], v[140:143], v[168:171]
	v_mfma_i32_16x16x64_i8 v[168:171], v[52:55], v[188:191], v[168:171]
	v_mfma_i32_16x16x64_i8 v[156:159], v[44:47], v[192:195], v[156:159]
	v_mfma_i32_16x16x64_i8 v[156:159], v[52:55], v[196:199], v[156:159]
	v_mfma_i32_16x16x64_i8 v[152:155], v[60:63], v[192:195], v[152:155]
	v_mfma_i32_16x16x64_i8 v[152:155], v[64:67], v[196:199], v[152:155]
	v_mfma_i32_16x16x64_i8 v[144:147], v[60:63], v[216:219], v[144:147]
	v_mfma_i32_16x16x64_i8 v[144:147], v[64:67], v[220:223], v[144:147]
	v_mfma_i32_16x16x64_i8 v[148:151], v[44:47], v[216:219], v[148:151]
	v_mfma_i32_16x16x64_i8 v[148:151], v[52:55], v[220:223], v[148:151]
	v_mfma_i32_16x16x64_i8 v[136:139], v[84:87], v[128:131], v[136:139]
	v_mfma_i32_16x16x64_i8 v[136:139], v[88:91], v[132:135], v[136:139]
	v_mfma_i32_16x16x64_i8 v[120:123], v[92:95], v[128:131], v[120:123]
	v_mfma_i32_16x16x64_i8 v[120:123], v[100:103], v[132:135], v[120:123]
	v_mfma_i32_16x16x64_i8 v[116:119], v[92:95], v[140:143], v[116:119]
	v_mfma_i32_16x16x64_i8 v[116:119], v[100:103], v[188:191], v[116:119]
	v_mfma_i32_16x16x64_i8 v[124:127], v[84:87], v[140:143], v[124:127]
	v_mfma_i32_16x16x64_i8 v[132:135], v[88:91], v[188:191], v[124:127]
	v_mfma_i32_16x16x64_i8 v[112:115], v[84:87], v[192:195], v[112:115]
	v_mfma_i32_16x16x64_i8 v[112:115], v[88:91], v[196:199], v[112:115]
	v_mfma_i32_16x16x64_i8 v[108:111], v[92:95], v[192:195], v[108:111]
	v_mfma_i32_16x16x64_i8 v[108:111], v[100:103], v[196:199], v[108:111]
	v_mfma_i32_16x16x64_i8 v[96:99], v[92:95], v[216:219], v[96:99]
	v_mfma_i32_16x16x64_i8 v[96:99], v[100:103], v[220:223], v[96:99]
	v_mfma_i32_16x16x64_i8 v[104:107], v[84:87], v[216:219], v[104:107]
	v_mfma_i32_16x16x64_i8 v[104:107], v[88:91], v[220:223], v[104:107]
	s_barrier
	s_add_i32 s8, s10, s12
	s_add_u32 s98, s82, 0x80
	s_addc_u32 s99, s83, 0
	s_add_u32 s100, vcc_lo, 0x80
	s_addc_u32 s101, vcc_hi, 0
	s_mov_b32 m0, s8
	ds_read_b128 v[124:127], v215 offset:49152
	ds_read_b128 v[128:131], v215 offset:50176
	ds_read_b128 v[140:143], v215 offset:51200
	ds_read_b128 v[188:191], v215 offset:52224
	ds_read_b128 v[192:195], v215 offset:53248
	ds_read_b128 v[196:199], v215 offset:54272
	ds_read_b128 v[216:219], v215 offset:55296
	ds_read_b128 v[220:223], v215 offset:56320
	global_load_lds_dwordx4 v178, s[98:99]
	s_add_i32 m0, s8, 0x2000
	s_add_u32 s8, s82, 0x40080
	s_addc_u32 s9, s83, 0
	s_add_i32 s10, s11, s12
	global_load_lds_dwordx4 v182, s[98:99]
	s_mov_b32 m0, s10
	s_nop 0
	global_load_lds_dwordx4 v178, s[8:9]
	s_add_i32 m0, s10, 0x2000
	s_nop 0
	global_load_lds_dwordx4 v182, s[8:9]
	s_mov_b32 m0, s58
	s_nop 0
	global_load_lds_dwordx4 v176, s[100:101]
	s_mov_b32 m0, s4
	s_nop 0
	global_load_lds_dwordx4 v180, s[100:101]
	s_waitcnt vmcnt(8)
	s_waitcnt lgkmcnt(0)
	s_barrier
	s_waitcnt lgkmcnt(0)
	v_mfma_i32_16x16x64_i8 v[80:83], v[44:47], v[124:127], v[80:83]
	v_mfma_i32_16x16x64_i8 v[80:83], v[52:55], v[128:131], v[80:83]
	v_mfma_i32_16x16x64_i8 v[72:75], v[60:63], v[124:127], v[72:75]
	v_mfma_i32_16x16x64_i8 v[72:75], v[64:67], v[128:131], v[72:75]
	v_mfma_i32_16x16x64_i8 v[68:71], v[60:63], v[140:143], v[68:71]
	v_mfma_i32_16x16x64_i8 v[68:71], v[64:67], v[188:191], v[68:71]
	v_mfma_i32_16x16x64_i8 v[76:79], v[44:47], v[140:143], v[76:79]
	v_mfma_i32_16x16x64_i8 v[76:79], v[52:55], v[188:191], v[76:79]
	v_mfma_i32_16x16x64_i8 v[56:59], v[44:47], v[192:195], v[56:59]
	v_mfma_i32_16x16x64_i8 v[56:59], v[52:55], v[196:199], v[56:59]
	v_mfma_i32_16x16x64_i8 v[48:51], v[60:63], v[192:195], v[48:51]
	v_mfma_i32_16x16x64_i8 v[48:51], v[64:67], v[196:199], v[48:51]
	v_mfma_i32_16x16x64_i8 v[36:39], v[60:63], v[216:219], v[36:39]
	v_mfma_i32_16x16x64_i8 v[36:39], v[64:67], v[220:223], v[36:39]
	v_mfma_i32_16x16x64_i8 v[40:43], v[44:47], v[216:219], v[40:43]
	v_mfma_i32_16x16x64_i8 v[40:43], v[52:55], v[220:223], v[40:43]
	v_mfma_i32_16x16x64_i8 v[32:35], v[84:87], v[124:127], v[32:35]
	v_mfma_i32_16x16x64_i8 v[32:35], v[88:91], v[128:131], v[32:35]
	v_mfma_i32_16x16x64_i8 v[24:27], v[92:95], v[124:127], v[24:27]
	v_mfma_i32_16x16x64_i8 v[24:27], v[100:103], v[128:131], v[24:27]
	v_mfma_i32_16x16x64_i8 v[20:23], v[92:95], v[140:143], v[20:23]
	v_mfma_i32_16x16x64_i8 v[20:23], v[100:103], v[188:191], v[20:23]
	v_mfma_i32_16x16x64_i8 v[28:31], v[84:87], v[140:143], v[28:31]
	v_mfma_i32_16x16x64_i8 v[28:31], v[88:91], v[188:191], v[28:31]
	v_mfma_i32_16x16x64_i8 v[16:19], v[84:87], v[192:195], v[16:19]
	v_mfma_i32_16x16x64_i8 v[16:19], v[88:91], v[196:199], v[16:19]
	v_mfma_i32_16x16x64_i8 v[12:15], v[92:95], v[192:195], v[12:15]
	v_mfma_i32_16x16x64_i8 v[12:15], v[100:103], v[196:199], v[12:15]
	v_mfma_i32_16x16x64_i8 v[2:5], v[92:95], v[216:219], v[2:5]
	v_mfma_i32_16x16x64_i8 v[6:9], v[84:87], v[216:219], v[8:11]
	v_mfma_i32_16x16x64_i8 v[8:11], v[88:91], v[220:223], v[6:9]
	v_mfma_i32_16x16x64_i8 v[4:7], v[100:103], v[220:223], v[2:5]
	s_barrier
	s_add_i32 s5, s5, 2
	s_add_u32 s85, s85, 0x100
	s_addc_u32 s68, s68, 0
	s_cmp_gt_u32 s5, 13
	s_mov_b64 s[8:9], s[70:71]
	s_cbranch_scc0 .LBB0_385
	s_branch .Lpeelx385
; #define PG8_STAGE(bufoff, gbase, voff) do { _Pragma("unroll") for (int _i = 0; _i < 2; ++_i) \
;         __builtin_amdgcn_global_load_lds((const unsigned*)((const char*)(gbase) + (voff)[_i]), (PG8_LAS unsigned*)(lds + (bufoff) + ldsw + _i * 8192), 16, 0, 0); } while (0)
; #define PG8_LDA(dst, b, h) do { _Pragma("unroll") for (int m = 0; m < 4; ++m) _Pragma("unroll") for (int k = 0; k < 2; ++k) dst[m][k] = *(const PG8_LAS bf16x8*)(lds + PG8_SA(b, h) + aoff + m * 2048 + k * 1024); } while (0)
; #define PG8_LDB(dst, b, h) do { _Pragma("unroll") for (int n = 0; n < 2; ++n) _Pragma("unroll") for (int k = 0; k < 2; ++k) dst[n][k] = *(const PG8_LAS bf16x8*)(lds + PG8_SB(b, h) + boff + n * 2048 + k * 1024); } while (0)
; #define PG8_MMA(ai, bj, At, Bt) do { __builtin_amdgcn_s_setprio(1); _Pragma("unroll") for (int m = 0; m < 4; ++m) _Pragma("unroll") for (int n = 0; n < 2; ++n) _Pragma("unroll") for (int k = 0; k < 2; ++k) \
;         acc[ai][bj][m][n] = mma16<Epi::I8>(Bt[n][k], At[m][k], acc[ai][bj][m][n]); __builtin_amdgcn_s_setprio(0); } while (0)
; #define PG8_WAIT_V(n) asm volatile("s_waitcnt vmcnt(" #n ")" ::: "memory")
; #define PG8_WAIT_L(n) asm volatile("s_waitcnt lgkmcnt(" #n ")" ::: "memory")
; template <class Epi, class Sched, bool ALIGN_EPI = false, bool SP2 = false>
; __device__ __forceinline__ void gemm_phase(PG8_LAS unsigned char* lds, const Gemm g, const Sched& S, const Epi& E) {
;     ...
;         for (int t = 0; t < nt; t += 2) {
;             const bool last = (t == nt - 2);
;             const char* a1 = cA + (size_t)(t + 1) * kstep;
;             const char* a2 = last ? nA : cA + (size_t)(t + 2) * kstep; const char* b2 = last ? nB : cB + (size_t)(t + 2) * kstep;
;             const char* a3 = a2 + kstep; const char* b3 = b2 + kstep;
;             if (last && has_next) S.a_ready(nxt);
;             if constexpr (SP2) {
;             PG8_LDB(B0, 0, 0); PG8_LDB(B1, 0, 1); PG8_SCHED; PG8_LDA(At, 0, 0); PG8_STAGE(PG8_SA(1, 1), a1 + hstep, voffA);
;             PG8_WAIT_V(8); PG8_WAIT_L(0); PG8_BAR; PG8_MMA(0, 0, At, B0); PG8_MMA(0, 1, At, B1); PG8_BAR; PG8_SCHED;
;             PG8_LDA(At, 0, 1); PG8_STAGE(PG8_SB(0, 0), b2, voffB); PG8_STAGE(PG8_SB(0, 1), b2 + hstep, voffB); PG8_STAGE(PG8_SA(0, 0), a2, voffA);
;             PG8_WAIT_V(8); PG8_WAIT_L(0); PG8_BAR; PG8_MMA(1, 0, At, B0); PG8_MMA(1, 1, At, B1); PG8_BAR; PG8_SCHED;
.LBB0_385:
	s_add_u32 s70, s8, 0x100
	s_addc_u32 s71, s9, 0
	s_add_i32 s84, 0, 0x10000
	s_cmp_eq_u32 s5, 12
	s_cselect_b32 vcc_hi, s1, s71
	s_cselect_b32 vcc_lo, s7, s70
	v_add_u32_e32 v0, s84, v214
	s_cselect_b32 s83, s69, s68
	s_cselect_b32 s82, s81, s85
	s_add_i32 s10, 0, 0x14000
	ds_read_b128 v[44:47], v0
	ds_read_b128 v[52:55], v0 offset:1024
	ds_read_b128 v[60:63], v0 offset:2048
	ds_read_b128 v[64:67], v0 offset:3072
	v_add_u32_e32 v0, s10, v214
	ds_read_b128 v[84:87], v0
	ds_read_b128 v[88:91], v0 offset:1024
	ds_read_b128 v[92:95], v0 offset:2048
	ds_read_b128 v[100:103], v0 offset:3072
	s_add_i32 m0, s13, 0xc000
	ds_read_b128 v[124:127], v215
	ds_read_b128 v[128:131], v215 offset:1024
	ds_read_b128 v[140:143], v215 offset:2048
	ds_read_b128 v[188:191], v215 offset:3072
	ds_read_b128 v[192:195], v215 offset:4096
	ds_read_b128 v[196:199], v215 offset:5120
	ds_read_b128 v[216:219], v215 offset:6144
	ds_read_b128 v[220:223], v215 offset:7168
	global_load_lds_dwordx4 v184, s[8:9]
	s_add_i32 m0, s13, 0xe000
	s_nop 0
	global_load_lds_dwordx4 v186, s[8:9]
	s_waitcnt vmcnt(8)
	s_waitcnt lgkmcnt(0)
	s_barrier
	s_waitcnt lgkmcnt(0)
	v_mfma_i32_16x16x64_i8 v[172:175], v[44:47], v[124:127], v[172:175]
	v_mfma_i32_16x16x64_i8 v[172:175], v[52:55], v[128:131], v[172:175]
	v_mfma_i32_16x16x64_i8 v[164:167], v[60:63], v[124:127], v[164:167]
	v_mfma_i32_16x16x64_i8 v[164:167], v[64:67], v[128:131], v[164:167]
	v_mfma_i32_16x16x64_i8 v[160:163], v[60:63], v[140:143], v[160:163]
	v_mfma_i32_16x16x64_i8 v[160:163], v[64:67], v[188:191], v[160:163]
	v_mfma_i32_16x16x64_i8 v[168:171], v[44:47], v[140:143], v[168:171]
	v_mfma_i32_16x16x64_i8 v[168:171], v[52:55], v[188:191], v[168:171]
	v_mfma_i32_16x16x64_i8 v[156:159], v[44:47], v[192:195], v[156:159]
	v_mfma_i32_16x16x64_i8 v[156:159], v[52:55], v[196:199], v[156:159]
	v_mfma_i32_16x16x64_i8 v[152:155], v[60:63], v[192:195], v[152:155]
	v_mfma_i32_16x16x64_i8 v[152:155], v[64:67], v[196:199], v[152:155]
	v_mfma_i32_16x16x64_i8 v[144:147], v[60:63], v[216:219], v[144:147]
	v_mfma_i32_16x16x64_i8 v[144:147], v[64:67], v[220:223], v[144:147]
	v_mfma_i32_16x16x64_i8 v[148:151], v[44:47], v[216:219], v[148:151]
	v_mfma_i32_16x16x64_i8 v[148:151], v[52:55], v[220:223], v[148:151]
	v_mfma_i32_16x16x64_i8 v[136:139], v[84:87], v[124:127], v[136:139]
	v_mfma_i32_16x16x64_i8 v[136:139], v[88:91], v[128:131], v[136:139]
	v_mfma_i32_16x16x64_i8 v[120:123], v[92:95], v[124:127], v[120:123]
	v_mfma_i32_16x16x64_i8 v[120:123], v[100:103], v[128:131], v[120:123]
	v_mfma_i32_16x16x64_i8 v[116:119], v[92:95], v[140:143], v[116:119]
	v_mfma_i32_16x16x64_i8 v[116:119], v[100:103], v[188:191], v[116:119]
	v_mfma_i32_16x16x64_i8 v[108:111], v[92:95], v[192:195], v[108:111]
	v_mfma_i32_16x16x64_i8 v[108:111], v[100:103], v[196:199], v[108:111]
	v_mfma_i32_16x16x64_i8 v[112:115], v[84:87], v[192:195], v[112:115]
	v_mfma_i32_16x16x64_i8 v[112:115], v[88:91], v[196:199], v[112:115]
	v_mfma_i32_16x16x64_i8 v[104:107], v[84:87], v[216:219], v[104:107]
	v_mfma_i32_16x16x64_i8 v[104:107], v[88:91], v[220:223], v[104:107]
	v_mfma_i32_16x16x64_i8 v[96:99], v[92:95], v[216:219], v[96:99]
	v_mfma_i32_16x16x64_i8 v[96:99], v[100:103], v[220:223], v[96:99]
	v_mfma_i32_16x16x64_i8 v[124:127], v[84:87], v[140:143], v[132:135]
	v_mfma_i32_16x16x64_i8 v[124:127], v[88:91], v[188:191], v[124:127]
	s_barrier
	s_add_i32 s8, s84, s12
	s_mov_b32 m0, s8
	ds_read_b128 v[128:131], v215 offset:16384
	ds_read_b128 v[132:135], v215 offset:17408
	ds_read_b128 v[140:143], v215 offset:18432
	ds_read_b128 v[188:191], v215 offset:19456
	ds_read_b128 v[192:195], v215 offset:20480
	ds_read_b128 v[196:199], v215 offset:21504
	ds_read_b128 v[216:219], v215 offset:22528
	ds_read_b128 v[220:223], v215 offset:23552
	global_load_lds_dwordx4 v178, s[82:83]
	s_add_i32 m0, s8, 0x2000
	s_add_u32 s8, s82, 0x40000
	s_addc_u32 s9, s83, 0
	s_add_i32 s10, s10, s12
	global_load_lds_dwordx4 v182, s[82:83]
	s_mov_b32 m0, s10
	s_nop 0
	global_load_lds_dwordx4 v178, s[8:9]
	s_add_i32 m0, s10, 0x2000
	s_nop 0
	global_load_lds_dwordx4 v182, s[8:9]
	s_mov_b32 m0, s13
	s_nop 0
	global_load_lds_dwordx4 v176, vcc
	s_mov_b32 m0, s66
	s_nop 0
	global_load_lds_dwordx4 v180, vcc
	s_waitcnt vmcnt(8)
	s_waitcnt lgkmcnt(0)
	s_barrier
	s_waitcnt lgkmcnt(0)
	v_mfma_i32_16x16x64_i8 v[80:83], v[44:47], v[128:131], v[80:83]
	v_mfma_i32_16x16x64_i8 v[80:83], v[52:55], v[132:135], v[80:83]
	v_mfma_i32_16x16x64_i8 v[72:75], v[60:63], v[128:131], v[72:75]
	v_mfma_i32_16x16x64_i8 v[72:75], v[64:67], v[132:135], v[72:75]
	v_mfma_i32_16x16x64_i8 v[68:71], v[60:63], v[140:143], v[68:71]
	v_mfma_i32_16x16x64_i8 v[68:71], v[64:67], v[188:191], v[68:71]
	v_mfma_i32_16x16x64_i8 v[76:79], v[44:47], v[140:143], v[76:79]
	v_mfma_i32_16x16x64_i8 v[76:79], v[52:55], v[188:191], v[76:79]
	v_mfma_i32_16x16x64_i8 v[56:59], v[44:47], v[192:195], v[56:59]
	v_mfma_i32_16x16x64_i8 v[56:59], v[52:55], v[196:199], v[56:59]
	v_mfma_i32_16x16x64_i8 v[48:51], v[60:63], v[192:195], v[48:51]
	v_mfma_i32_16x16x64_i8 v[48:51], v[64:67], v[196:199], v[48:51]
	v_mfma_i32_16x16x64_i8 v[36:39], v[60:63], v[216:219], v[36:39]
	v_mfma_i32_16x16x64_i8 v[36:39], v[64:67], v[220:223], v[36:39]
	v_mfma_i32_16x16x64_i8 v[40:43], v[44:47], v[216:219], v[40:43]
	v_mfma_i32_16x16x64_i8 v[40:43], v[52:55], v[220:223], v[40:43]
	v_mfma_i32_16x16x64_i8 v[32:35], v[84:87], v[128:131], v[32:35]
	v_mfma_i32_16x16x64_i8 v[32:35], v[88:91], v[132:135], v[32:35]
	v_mfma_i32_16x16x64_i8 v[24:27], v[92:95], v[128:131], v[24:27]
	v_mfma_i32_16x16x64_i8 v[24:27], v[100:103], v[132:135], v[24:27]
	v_mfma_i32_16x16x64_i8 v[20:23], v[92:95], v[140:143], v[20:23]
	v_mfma_i32_16x16x64_i8 v[20:23], v[100:103], v[188:191], v[20:23]
	v_mfma_i32_16x16x64_i8 v[28:31], v[84:87], v[140:143], v[28:31]
	v_mfma_i32_16x16x64_i8 v[28:31], v[88:91], v[188:191], v[28:31]
	v_mfma_i32_16x16x64_i8 v[16:19], v[84:87], v[192:195], v[16:19]
	v_mfma_i32_16x16x64_i8 v[16:19], v[88:91], v[196:199], v[16:19]
	v_mfma_i32_16x16x64_i8 v[12:15], v[92:95], v[192:195], v[12:15]
	v_mfma_i32_16x16x64_i8 v[12:15], v[100:103], v[196:199], v[12:15]
	v_mfma_i32_16x16x64_i8 v[2:5], v[92:95], v[216:219], v[4:7]
	v_mfma_i32_16x16x64_i8 v[2:5], v[100:103], v[220:223], v[2:5]
	v_mfma_i32_16x16x64_i8 v[8:11], v[84:87], v[216:219], v[8:11]
	v_mfma_i32_16x16x64_i8 v[8:11], v[88:91], v[220:223], v[8:11]
	s_barrier
; #define PG8_STAGE(bufoff, gbase, voff) do { _Pragma("unroll") for (int _i = 0; _i < 2; ++_i) \
;         __builtin_amdgcn_global_load_lds((const unsigned*)((const char*)(gbase) + (voff)[_i]), (PG8_LAS unsigned*)(lds + (bufoff) + ldsw + _i * 8192), 16, 0, 0); } while (0)
; #define PG8_LDA(dst, b, h) do { _Pragma("unroll") for (int m = 0; m < 4; ++m) _Pragma("unroll") for (int k = 0; k < 2; ++k) dst[m][k] = *(const PG8_LAS bf16x8*)(lds + PG8_SA(b, h) + aoff + m * 2048 + k * 1024); } while (0)
; #define PG8_LDB(dst, b, h) do { _Pragma("unroll") for (int n = 0; n < 2; ++n) _Pragma("unroll") for (int k = 0; k < 2; ++k) dst[n][k] = *(const PG8_LAS bf16x8*)(lds + PG8_SB(b, h) + boff + n * 2048 + k * 1024); } while (0)
; #define PG8_MMA(ai, bj, At, Bt) do { __builtin_amdgcn_s_setprio(1); _Pragma("unroll") for (int m = 0; m < 4; ++m) _Pragma("unroll") for (int n = 0; n < 2; ++n) _Pragma("unroll") for (int k = 0; k < 2; ++k) \
;         acc[ai][bj][m][n] = mma16<Epi::I8>(Bt[n][k], At[m][k], acc[ai][bj][m][n]); __builtin_amdgcn_s_setprio(0); } while (0)
; #define PG8_WAIT_V(n) asm volatile("s_waitcnt vmcnt(" #n ")" ::: "memory")
; #define PG8_WAIT_L(n) asm volatile("s_waitcnt lgkmcnt(" #n ")" ::: "memory")
; #define PG8_BAR __builtin_amdgcn_s_barrier()
; #define PG8_SCHED __builtin_amdgcn_sched_barrier(0)
; template <class Epi, class Sched, bool ALIGN_EPI = false, bool SP2 = false>
; __device__ __forceinline__ void gemm_phase(PG8_LAS unsigned char* lds, const Gemm g, const Sched& S, const Epi& E) {
;     ...
;             PG8_LDB(B0, 1, 0); PG8_LDB(B1, 1, 1); PG8_SCHED; PG8_LDA(At, 1, 0); PG8_STAGE(PG8_SA(0, 1), a2 + hstep, voffA);
;             PG8_WAIT_V(8); PG8_WAIT_L(0); PG8_BAR; PG8_MMA(0, 0, At, B0); PG8_MMA(0, 1, At, B1); PG8_BAR; PG8_SCHED;
;             PG8_LDA(At, 1, 1); PG8_STAGE(PG8_SB(1, 0), b3, voffB); PG8_STAGE(PG8_SB(1, 1), b3 + hstep, voffB); PG8_STAGE(PG8_SA(1, 0), a3, voffA);
;             PG8_WAIT_V(8); PG8_WAIT_L(0); PG8_BAR; PG8_MMA(1, 0, At, B0); PG8_MMA(1, 1, At, B1); PG8_BAR; PG8_SCHED;
	s_add_i32 s10, 0, 0x18000
	v_add_u32_e32 v0, s10, v214
	s_add_i32 s11, 0, 0x1c000
	ds_read_b128 v[44:47], v0
	ds_read_b128 v[52:55], v0 offset:1024
	ds_read_b128 v[60:63], v0 offset:2048
	ds_read_b128 v[64:67], v0 offset:3072
	v_add_u32_e32 v0, s11, v214
	ds_read_b128 v[84:87], v0
	ds_read_b128 v[88:91], v0 offset:1024
	ds_read_b128 v[92:95], v0 offset:2048
	ds_read_b128 v[100:103], v0 offset:3072
	s_add_u32 s8, vcc_lo, 0x40000
	s_addc_u32 s9, vcc_hi, 0
	s_mov_b32 m0, s67
	ds_read_b128 v[128:131], v215 offset:32768
	ds_read_b128 v[132:135], v215 offset:33792
	ds_read_b128 v[140:143], v215 offset:34816
	ds_read_b128 v[188:191], v215 offset:35840
	ds_read_b128 v[192:195], v215 offset:36864
	ds_read_b128 v[196:199], v215 offset:37888
	ds_read_b128 v[216:219], v215 offset:38912
	ds_read_b128 v[220:223], v215 offset:39936
	global_load_lds_dwordx4 v176, s[8:9]
	s_mov_b32 m0, s80
	s_nop 0
	global_load_lds_dwordx4 v180, s[8:9]
	s_waitcnt vmcnt(8)
	s_waitcnt lgkmcnt(0)
	s_barrier
	s_waitcnt lgkmcnt(0)
	v_mfma_i32_16x16x64_i8 v[172:175], v[44:47], v[128:131], v[172:175]
	v_mfma_i32_16x16x64_i8 v[172:175], v[52:55], v[132:135], v[172:175]
	v_mfma_i32_16x16x64_i8 v[164:167], v[60:63], v[128:131], v[164:167]
	v_mfma_i32_16x16x64_i8 v[164:167], v[64:67], v[132:135], v[164:167]
	v_mfma_i32_16x16x64_i8 v[160:163], v[60:63], v[140:143], v[160:163]
	v_mfma_i32_16x16x64_i8 v[160:163], v[64:67], v[188:191], v[160:163]
	v_mfma_i32_16x16x64_i8 v[168:171], v[44:47], v[140:143], v[168:171]
	v_mfma_i32_16x16x64_i8 v[168:171], v[52:55], v[188:191], v[168:171]
	v_mfma_i32_16x16x64_i8 v[156:159], v[44:47], v[192:195], v[156:159]
	v_mfma_i32_16x16x64_i8 v[156:159], v[52:55], v[196:199], v[156:159]
	v_mfma_i32_16x16x64_i8 v[152:155], v[60:63], v[192:195], v[152:155]
	v_mfma_i32_16x16x64_i8 v[152:155], v[64:67], v[196:199], v[152:155]
	v_mfma_i32_16x16x64_i8 v[144:147], v[60:63], v[216:219], v[144:147]
	v_mfma_i32_16x16x64_i8 v[144:147], v[64:67], v[220:223], v[144:147]
	v_mfma_i32_16x16x64_i8 v[148:151], v[44:47], v[216:219], v[148:151]
	v_mfma_i32_16x16x64_i8 v[148:151], v[52:55], v[220:223], v[148:151]
	v_mfma_i32_16x16x64_i8 v[136:139], v[84:87], v[128:131], v[136:139]
	v_mfma_i32_16x16x64_i8 v[136:139], v[88:91], v[132:135], v[136:139]
	v_mfma_i32_16x16x64_i8 v[120:123], v[92:95], v[128:131], v[120:123]
	v_mfma_i32_16x16x64_i8 v[120:123], v[100:103], v[132:135], v[120:123]
	v_mfma_i32_16x16x64_i8 v[116:119], v[92:95], v[140:143], v[116:119]
	v_mfma_i32_16x16x64_i8 v[116:119], v[100:103], v[188:191], v[116:119]
	v_mfma_i32_16x16x64_i8 v[124:127], v[84:87], v[140:143], v[124:127]
	v_mfma_i32_16x16x64_i8 v[132:135], v[88:91], v[188:191], v[124:127]
	v_mfma_i32_16x16x64_i8 v[112:115], v[84:87], v[192:195], v[112:115]
	v_mfma_i32_16x16x64_i8 v[112:115], v[88:91], v[196:199], v[112:115]
	v_mfma_i32_16x16x64_i8 v[108:111], v[92:95], v[192:195], v[108:111]
	v_mfma_i32_16x16x64_i8 v[108:111], v[100:103], v[196:199], v[108:111]
	v_mfma_i32_16x16x64_i8 v[96:99], v[92:95], v[216:219], v[96:99]
	v_mfma_i32_16x16x64_i8 v[96:99], v[100:103], v[220:223], v[96:99]
	v_mfma_i32_16x16x64_i8 v[104:107], v[84:87], v[216:219], v[104:107]
	v_mfma_i32_16x16x64_i8 v[104:107], v[88:91], v[220:223], v[104:107]
	s_barrier
	s_add_i32 s8, s10, s12
	s_add_u32 s98, s82, 0x80
	s_addc_u32 s99, s83, 0
	s_add_u32 s100, vcc_lo, 0x80
	s_addc_u32 s101, vcc_hi, 0
	s_mov_b32 m0, s8
	ds_read_b128 v[124:127], v215 offset:49152
	ds_read_b128 v[128:131], v215 offset:50176
	ds_read_b128 v[140:143], v215 offset:51200
	ds_read_b128 v[188:191], v215 offset:52224
	ds_read_b128 v[192:195], v215 offset:53248
	ds_read_b128 v[196:199], v215 offset:54272
	ds_read_b128 v[216:219], v215 offset:55296
	ds_read_b128 v[220:223], v215 offset:56320
	global_load_lds_dwordx4 v178, s[98:99]
	s_add_i32 m0, s8, 0x2000
	s_add_u32 s8, s82, 0x40080
	s_addc_u32 s9, s83, 0
	s_add_i32 s10, s11, s12
	global_load_lds_dwordx4 v182, s[98:99]
	s_mov_b32 m0, s10
	s_nop 0
	global_load_lds_dwordx4 v178, s[8:9]
	s_add_i32 m0, s10, 0x2000
	s_nop 0
	global_load_lds_dwordx4 v182, s[8:9]
	s_mov_b32 m0, s58
	s_nop 0
	global_load_lds_dwordx4 v176, s[100:101]
	s_mov_b32 m0, s4
	s_nop 0
	global_load_lds_dwordx4 v180, s[100:101]
	s_waitcnt vmcnt(8)
	s_waitcnt lgkmcnt(0)
	s_barrier
	s_waitcnt lgkmcnt(0)
	v_mfma_i32_16x16x64_i8 v[80:83], v[44:47], v[124:127], v[80:83]
	v_mfma_i32_16x16x64_i8 v[80:83], v[52:55], v[128:131], v[80:83]
	v_mfma_i32_16x16x64_i8 v[72:75], v[60:63], v[124:127], v[72:75]
	v_mfma_i32_16x16x64_i8 v[72:75], v[64:67], v[128:131], v[72:75]
	v_mfma_i32_16x16x64_i8 v[68:71], v[60:63], v[140:143], v[68:71]
	v_mfma_i32_16x16x64_i8 v[68:71], v[64:67], v[188:191], v[68:71]
	v_mfma_i32_16x16x64_i8 v[76:79], v[44:47], v[140:143], v[76:79]
	v_mfma_i32_16x16x64_i8 v[76:79], v[52:55], v[188:191], v[76:79]
	v_mfma_i32_16x16x64_i8 v[56:59], v[44:47], v[192:195], v[56:59]
	v_mfma_i32_16x16x64_i8 v[56:59], v[52:55], v[196:199], v[56:59]
	v_mfma_i32_16x16x64_i8 v[48:51], v[60:63], v[192:195], v[48:51]
	v_mfma_i32_16x16x64_i8 v[48:51], v[64:67], v[196:199], v[48:51]
	v_mfma_i32_16x16x64_i8 v[36:39], v[60:63], v[216:219], v[36:39]
	v_mfma_i32_16x16x64_i8 v[36:39], v[64:67], v[220:223], v[36:39]
	v_mfma_i32_16x16x64_i8 v[40:43], v[44:47], v[216:219], v[40:43]
	v_mfma_i32_16x16x64_i8 v[40:43], v[52:55], v[220:223], v[40:43]
	v_mfma_i32_16x16x64_i8 v[32:35], v[84:87], v[124:127], v[32:35]
	v_mfma_i32_16x16x64_i8 v[32:35], v[88:91], v[128:131], v[32:35]
	v_mfma_i32_16x16x64_i8 v[24:27], v[92:95], v[124:127], v[24:27]
	v_mfma_i32_16x16x64_i8 v[24:27], v[100:103], v[128:131], v[24:27]
	v_mfma_i32_16x16x64_i8 v[20:23], v[92:95], v[140:143], v[20:23]
	v_mfma_i32_16x16x64_i8 v[20:23], v[100:103], v[188:191], v[20:23]
	v_mfma_i32_16x16x64_i8 v[28:31], v[84:87], v[140:143], v[28:31]
	v_mfma_i32_16x16x64_i8 v[28:31], v[88:91], v[188:191], v[28:31]
	v_mfma_i32_16x16x64_i8 v[16:19], v[84:87], v[192:195], v[16:19]
	v_mfma_i32_16x16x64_i8 v[16:19], v[88:91], v[196:199], v[16:19]
	v_mfma_i32_16x16x64_i8 v[12:15], v[92:95], v[192:195], v[12:15]
	v_mfma_i32_16x16x64_i8 v[12:15], v[100:103], v[196:199], v[12:15]
	v_mfma_i32_16x16x64_i8 v[2:5], v[92:95], v[216:219], v[2:5]
	v_mfma_i32_16x16x64_i8 v[6:9], v[84:87], v[216:219], v[8:11]
	v_mfma_i32_16x16x64_i8 v[8:11], v[88:91], v[220:223], v[6:9]
	v_mfma_i32_16x16x64_i8 v[4:7], v[100:103], v[220:223], v[2:5]
	s_barrier
	s_add_i32 s5, s5, 2
	s_add_u32 s85, s85, 0x100
	s_addc_u32 s68, s68, 0
	s_cmp_gt_u32 s5, 13
	s_mov_b64 s[8:9], s[70:71]
	s_cbranch_scc0 .LBB0_385
